# code placement: every 8-byte instruction in the hand-written K-loops starts on an 8-byte boundary (s_nop 0 padding)
# speedup vs baseline: 1.0039x; 1.0039x over previous
.LBB0_127:
	s_add_i32 s42, s16, s46
	s_cmpk_gt_i32 s42, 0xb27
	s_mov_b64 s[40:41], -1
	s_cbranch_scc1 .LBB0_126
	s_mul_hi_i32 s40, s42, 0x30c30c31
	s_lshr_b32 s41, s40, 31
	s_ashr_i32 s40, s40, 7
	s_add_i32 s54, s40, s41
	s_mul_i32 s40, s54, 0xfffffd60
	s_lshl_b32 s43, s54, 3
	s_add_i32 s41, s40, s42
	s_sub_i32 s40, 34, s43
	s_cmpk_gt_i32 s42, 0xa7f
	s_cselect_b32 s42, s40, 8
	s_abs_i32 s40, s42
	v_cvt_f32_u32_e32 v0, s40
	s_sub_i32 s50, 0, s40
	s_abs_i32 s44, s41
	s_xor_b32 s45, s41, s42
	v_rcp_iflag_f32_e32 v0, v0
	s_ashr_i32 s45, s45, 31
	v_mov_b32_e32 v8, v204
	v_mul_f32_e32 v0, 0x4f7ffffe, v0
	v_cvt_u32_f32_e32 v0, v0
	v_bfe_u32 v2, v8, 2, 4
	v_ashrrev_i32_e32 v1, 6, v8
	v_lshlrev_b32_e32 v3, 16, v1
	v_readfirstlane_b32 s51, v0
	s_mul_i32 s50, s50, s51
	s_mul_hi_u32 s50, s51, s50
	s_add_i32 s51, s51, s50
	s_mul_hi_u32 s50, s44, s51
	s_mul_i32 s51, s50, s40
	s_sub_i32 s44, s44, s51
	s_add_i32 s52, s50, 1
	s_sub_i32 s51, s44, s40
	s_cmp_ge_u32 s44, s40
	s_cselect_b32 s50, s52, s50
	s_cselect_b32 s44, s51, s44
	s_add_i32 s51, s50, 1
	s_cmp_ge_u32 s44, s40
	s_cselect_b32 s40, s51, s50
	s_xor_b32 s40, s40, s45
	s_sub_i32 s40, s40, s45
	s_mul_i32 s55, s42, s40
	s_add_i32 s41, s41, s43
	s_sub_i32 s42, s41, s55
	s_ashr_i32 s43, s42, 31
	s_lshl_b64 s[44:45], s[42:43], 20
	s_add_u32 s50, s23, s44
	s_addc_u32 s51, s28, s45
	s_ashr_i32 s41, s40, 31
	v_bfe_u32 v0, v8, 4, 2
	s_lshl_b64 s[44:45], s[40:41], 19
	v_bitop3_b32 v0, v0, v8, 3 bitop3:0x78
	s_mov_b32 s41, 0x1fffc0
	v_lshlrev_b32_e32 v9, 3, v0
	v_and_or_b32 v0, v8, s41, v2
	v_lshl_or_b32 v0, v0, 11, v9
	v_lshl_add_u32 v165, v1, 12, 32
	v_lshlrev_b32_e32 v1, 11, v1
	v_sub_u32_e32 v166, v165, v1
	v_ashrrev_i32_e32 v1, 31, v0
	v_readfirstlane_b32 s41, v165
	v_add_u32_e32 v12, 0x400, v165
	v_lshlrev_b32_e32 v10, 11, v2
	v_lshl_add_u64 v[0:1], v[0:1], 1, s[50:51]
	s_mov_b32 m0, s41
	v_readfirstlane_b32 s41, v12
	v_add_u32_e32 v12, 0x800, v165
	v_or3_b32 v2, v10, v3, v9
	global_load_lds_dwordx4 v[0:1], off
	v_lshl_add_u64 v[6:7], v[0:1], 0, s[6:7]
	s_mov_b32 m0, s41
	s_mov_b64 s[50:51], 0x20000
	v_readfirstlane_b32 s41, v12
	v_add_u32_e32 v12, 0xc00, v165
	s_add_u32 s52, s29, s44
	v_add_u32_e32 v11, 0x4000, v166
	v_ashrrev_i32_e32 v3, 31, v2
	global_load_lds_dwordx4 v[6:7], off
	v_lshl_add_u64 v[6:7], v[0:1], 0, s[50:51]
	s_mov_b32 m0, s41
	s_mov_b64 s[50:51], 0x30000
	v_readfirstlane_b32 s41, v12
	s_addc_u32 s53, s30, s45
	v_lshlrev_b64 v[2:3], 1, v[2:3]
	v_lshrrev_b32_e32 v240, 4, v10
	v_add_u32_e32 v2, v2, v240
	global_load_lds_dwordx4 v[6:7], off
	v_lshl_add_u64 v[6:7], v[0:1], 0, s[50:51]
	s_mov_b32 m0, s41
	v_readfirstlane_b32 s41, v11
	v_add_u32_e32 v11, 0x4400, v166
	v_lshl_add_u64 v[4:5], s[52:53], 0, v[2:3]
	global_load_lds_dwordx4 v[6:7], off
	s_mov_b32 m0, s41
	v_readfirstlane_b32 s41, v11
	v_add_u32_e32 v11, 0x6000, v165
	global_load_lds_dwordx4 v[4:5], off
	s_mov_b64 s[50:51], 0x10800
	v_lshl_add_u64 v[6:7], v[4:5], 0, s[50:51]
	s_mov_b32 m0, s41
	v_readfirstlane_b32 s41, v11
	v_add_u32_e32 v11, 0x6400, v165
	global_load_lds_dwordx4 v[6:7], off
	v_lshl_add_u64 v[6:7], v[0:1], 0, 64
	s_mov_b32 m0, s41
	v_readfirstlane_b32 s41, v11
	v_add_u32_e32 v11, 0x6800, v165
	global_load_lds_dwordx4 v[6:7], off
	v_lshl_add_u64 v[6:7], v[0:1], 0, s[8:9]
	s_mov_b32 m0, s41
	s_mov_b64 s[50:51], 0x20040
	v_readfirstlane_b32 s41, v11
	global_load_lds_dwordx4 v[6:7], off
	v_lshl_add_u64 v[6:7], v[0:1], 0, s[50:51]
	s_mov_b32 m0, s41
	s_mov_b64 s[50:51], 0x30040
	global_load_lds_dwordx4 v[6:7], off
	v_add_u32_e32 v6, 0x6c00, v165
	v_lshl_add_u64 v[0:1], v[0:1], 0, s[50:51]
	v_readfirstlane_b32 s41, v6
	v_add_u32_e32 v6, 0xa000, v166
	s_mov_b32 m0, s41
	v_readfirstlane_b32 s41, v6
	global_load_lds_dwordx4 v[0:1], off
	v_lshl_add_u64 v[0:1], v[4:5], 0, 64
	s_mov_b32 m0, s41
	s_add_u32 s44, s94, s44
	global_load_lds_dwordx4 v[0:1], off
	s_mov_b64 s[50:51], 0x10840
	v_lshl_add_u64 v[0:1], v[4:5], 0, s[50:51]
	v_add_u32_e32 v4, 0xa400, v166
	s_addc_u32 s45, s95, s45
	v_readfirstlane_b32 s41, v4
	s_mov_b32 m0, s41
	v_bfe_u32 v4, v8, 2, 2
	global_load_lds_dwordx4 v[0:1], off
	v_bfe_u32 v0, v8, 5, 1
	v_lshrrev_b32_e32 v1, 2, v8
	s_sub_i32 s41, s47, s55
	s_mulk_i32 s54, 0x298
	v_bitop3_b32 v1, v0, v1, 3 bitop3:0x78
	v_bitop3_b32 v0, v0, v4, 2 bitop3:0x36
	v_lshl_add_u64 v[130:131], s[44:45], 0, v[2:3]
	s_sub_i32 s44, s41, s54
	v_lshlrev_b32_e32 v128, 4, v0
	s_ashr_i32 s45, s44, 31
	v_lshlrev_b32_e32 v0, 11, v8
	s_lshl_b64 s[44:45], s[44:45], 20
	v_and_b32_e32 v0, 0xfffe0000, v0
	v_or3_b32 v0, v0, v10, v9
	s_add_u32 s44, s94, s44
	v_lshlrev_b32_e32 v167, 4, v1
	v_ashrrev_i32_e32 v1, 31, v0
	s_addc_u32 s45, s95, s45
	v_lshlrev_b32_e32 v5, 6, v8
	v_lshl_add_u64 v[132:133], v[0:1], 1, s[44:45]
	v_mov_b32_e32 v0, 0
	s_mov_b32 s49, 0
	v_and_b32_e32 v168, 0xffffe7c0, v5
	v_and_b32_e32 v169, 0x17c0, v5
	s_mov_b64 s[44:45], 0
	v_mov_b32_e32 v1, v0
	v_mov_b32_e32 v2, v0
	v_mov_b32_e32 v3, v0
	v_mov_b32_e32 v4, v0
	v_mov_b32_e32 v5, v0
	v_mov_b32_e32 v6, v0
	v_mov_b32_e32 v7, v0
	v_mov_b32_e32 v8, v0
	v_mov_b32_e32 v9, v0
	v_mov_b32_e32 v10, v0
	v_mov_b32_e32 v11, v0
	v_mov_b32_e32 v12, v0
	v_mov_b32_e32 v13, v0
	v_mov_b32_e32 v14, v0
	v_mov_b32_e32 v15, v0
	v_mov_b32_e32 v16, v0
	v_mov_b32_e32 v17, v0
	v_mov_b32_e32 v18, v0
	v_mov_b32_e32 v19, v0
	v_mov_b32_e32 v20, v0
	v_mov_b32_e32 v21, v0
	v_mov_b32_e32 v22, v0
	v_mov_b32_e32 v23, v0
	v_mov_b32_e32 v24, v0
	v_mov_b32_e32 v25, v0
	v_mov_b32_e32 v26, v0
	v_mov_b32_e32 v27, v0
	v_mov_b32_e32 v28, v0
	v_mov_b32_e32 v29, v0
	v_mov_b32_e32 v30, v0
	v_mov_b32_e32 v31, v0
	v_mov_b32_e32 v32, v0
	v_mov_b32_e32 v33, v0
	v_mov_b32_e32 v34, v0
	v_mov_b32_e32 v35, v0
	v_mov_b32_e32 v36, v0
	v_mov_b32_e32 v37, v0
	v_mov_b32_e32 v38, v0
	v_mov_b32_e32 v39, v0
	v_mov_b32_e32 v40, v0
	v_mov_b32_e32 v41, v0
	v_mov_b32_e32 v42, v0
	v_mov_b32_e32 v43, v0
	v_mov_b32_e32 v44, v0
	v_mov_b32_e32 v45, v0
	v_mov_b32_e32 v46, v0
	v_mov_b32_e32 v47, v0
	v_mov_b32_e32 v48, v0
	v_mov_b32_e32 v49, v0
	v_mov_b32_e32 v50, v0
	v_mov_b32_e32 v51, v0
	v_mov_b32_e32 v52, v0
	v_mov_b32_e32 v53, v0
	v_mov_b32_e32 v54, v0
	v_mov_b32_e32 v55, v0
	v_mov_b32_e32 v56, v0
	v_mov_b32_e32 v57, v0
	v_mov_b32_e32 v58, v0
	v_mov_b32_e32 v59, v0
	v_mov_b32_e32 v60, v0
	v_mov_b32_e32 v61, v0
	v_mov_b32_e32 v62, v0
	v_mov_b32_e32 v63, v0
	v_mov_b32_e32 v64, v0
	v_mov_b32_e32 v65, v0
	v_mov_b32_e32 v66, v0
	v_mov_b32_e32 v67, v0
	v_mov_b32_e32 v68, v0
	v_mov_b32_e32 v69, v0
	v_mov_b32_e32 v70, v0
	v_mov_b32_e32 v71, v0
	v_mov_b32_e32 v72, v0
	v_mov_b32_e32 v73, v0
	v_mov_b32_e32 v74, v0
	v_mov_b32_e32 v75, v0
	v_mov_b32_e32 v76, v0
	v_mov_b32_e32 v77, v0
	v_mov_b32_e32 v78, v0
	v_mov_b32_e32 v79, v0
	v_mov_b32_e32 v80, v0
	v_mov_b32_e32 v81, v0
	v_mov_b32_e32 v82, v0
	v_mov_b32_e32 v83, v0
	v_mov_b32_e32 v84, v0
	v_mov_b32_e32 v85, v0
	v_mov_b32_e32 v86, v0
	v_mov_b32_e32 v87, v0
	v_mov_b32_e32 v88, v0
	v_mov_b32_e32 v89, v0
	v_mov_b32_e32 v90, v0
	v_mov_b32_e32 v91, v0
	v_mov_b32_e32 v92, v0
	v_mov_b32_e32 v93, v0
	v_mov_b32_e32 v94, v0
	v_mov_b32_e32 v95, v0
	v_mov_b32_e32 v96, v0
	v_mov_b32_e32 v97, v0
	v_mov_b32_e32 v98, v0
	v_mov_b32_e32 v99, v0
	v_mov_b32_e32 v100, v0
	v_mov_b32_e32 v101, v0
	v_mov_b32_e32 v102, v0
	v_mov_b32_e32 v103, v0
	v_mov_b32_e32 v104, v0
	v_mov_b32_e32 v105, v0
	v_mov_b32_e32 v106, v0
	v_mov_b32_e32 v107, v0
	v_mov_b32_e32 v108, v0
	v_mov_b32_e32 v109, v0
	v_mov_b32_e32 v110, v0
	v_mov_b32_e32 v111, v0
	v_mov_b32_e32 v112, v0
	v_mov_b32_e32 v113, v0
	v_mov_b32_e32 v114, v0
	v_mov_b32_e32 v115, v0
	v_mov_b32_e32 v116, v0
	v_mov_b32_e32 v117, v0
	v_mov_b32_e32 v118, v0
	v_mov_b32_e32 v119, v0
	v_mov_b32_e32 v120, v0
	v_mov_b32_e32 v121, v0
	v_mov_b32_e32 v122, v0
	v_mov_b32_e32 v123, v0
	v_mov_b32_e32 v124, v0
	v_mov_b32_e32 v125, v0
	v_mov_b32_e32 v126, v0
	v_mov_b32_e32 v127, v0
	s_nop 0
	v_add3_u32 v230, v168, v167, 32
	v_add3_u32 v231, v168, v128, 32
	v_add_u32_e32 v232, 0x4020, v169
	v_add_u32_e32 v233, v232, v128
	v_add_u32_e32 v232, v232, v167
	v_subrev_u32_e32 v234, s94, v132
	v_subrev_u32_e32 v238, s94, v130
	v_add_u32_e32 v234, 0x15c88080, v234
	v_sub_u32_e32 v238, v238, v240
	s_nop 0
	v_add_u32_e32 v238, 0x13288000, v238
	v_add_u32_e32 v235, 0x10000, v234
	v_add_u32_e32 v236, 0x20000, v234
	v_add_u32_e32 v237, 0x30000, v234
	v_add_u32_e32 v239, 0x10000, v238
	v_readfirstlane_b32 s101, v165
	v_readfirstlane_b32 s49, v166
	s_mov_b64 s[98:99], s[94:95]
	s_add_u32 s44, s94, 64
	s_addc_u32 s45, s95, 0
	s_nop 0
	s_add_u32 s49, s49, 0x4000
	s_movk_i32 s36, 0x80
	s_movk_i32 s37, 0x880
	s_waitcnt vmcnt(6)
	s_barrier
	ds_read_b128 v[170:173], v232 offset:0
	ds_read_b128 v[174:177], v232 offset:2048
	ds_read_b128 v[178:181], v230 offset:0
	ds_read_b128 v[182:185], v230 offset:2048
	ds_read_b128 v[186:189], v230 offset:4096
	ds_read_b128 v[190:193], v230 offset:6144
	s_waitcnt lgkmcnt(2)
	s_setprio 1
	v_mfma_f32_32x32x16_bf16 v[112:127], v[178:181], v[170:173], v[112:127]
	v_mfma_f32_32x32x16_bf16 v[96:111], v[178:181], v[174:177], v[96:111]
	v_mfma_f32_32x32x16_bf16 v[80:95], v[182:185], v[170:173], v[80:95]
	v_mfma_f32_32x32x16_bf16 v[64:79], v[182:185], v[174:177], v[64:79]
	s_setprio 0
	s_nop 0
	ds_read_b128 v[206:209], v233 offset:0
	ds_read_b128 v[210:213], v233 offset:2048
	ds_read_b128 v[214:217], v231 offset:0
	ds_read_b128 v[218:221], v231 offset:2048
	s_waitcnt lgkmcnt(4)
	s_setprio 1
	v_mfma_f32_32x32x16_bf16 v[48:63], v[186:189], v[170:173], v[48:63]
	v_mfma_f32_32x32x16_bf16 v[32:47], v[186:189], v[174:177], v[32:47]
	v_mfma_f32_32x32x16_bf16 v[16:31], v[190:193], v[170:173], v[16:31]
	v_mfma_f32_32x32x16_bf16 v[0:15], v[190:193], v[174:177], v[0:15]
	s_setprio 0
	s_nop 0
	ds_read_b128 v[222:225], v231 offset:4096
	ds_read_b128 v[226:229], v231 offset:6144
	s_waitcnt lgkmcnt(2)
	s_setprio 1
	v_mfma_f32_32x32x16_bf16 v[112:127], v[214:217], v[206:209], v[112:127]
	v_mfma_f32_32x32x16_bf16 v[96:111], v[214:217], v[210:213], v[96:111]
	v_mfma_f32_32x32x16_bf16 v[80:95], v[218:221], v[206:209], v[80:95]
	v_mfma_f32_32x32x16_bf16 v[64:79], v[218:221], v[210:213], v[64:79]
	s_setprio 0
	s_mov_b32 s100, 10
.Lp1m_kloop:
	s_waitcnt vmcnt(0) lgkmcnt(0)
	s_barrier
	ds_read_b128 v[170:173], v232 offset:24576
	ds_read_b128 v[174:177], v232 offset:26624
	ds_read_b128 v[178:181], v230 offset:24576
	ds_read_b128 v[182:185], v230 offset:26624
	ds_read_b128 v[186:189], v230 offset:28672
	ds_read_b128 v[190:193], v230 offset:30720
	s_setprio 1
	s_nop 0
	v_mfma_f32_32x32x16_bf16 v[48:63], v[222:225], v[206:209], v[48:63]
	v_mfma_f32_32x32x16_bf16 v[32:47], v[222:225], v[210:213], v[32:47]
	v_mfma_f32_32x32x16_bf16 v[16:31], v[226:229], v[206:209], v[16:31]
	v_mfma_f32_32x32x16_bf16 v[0:15], v[226:229], v[210:213], v[0:15]
	s_setprio 0
	s_nop 0
	s_add_u32 m0, s101, 0xc000
	s_nop 0
	s_nop 0
	global_load_lds_dwordx4 v234, s[98:99]
	s_add_u32 m0, s101, 0x0
	s_nop 0
	global_load_lds_dwordx4 v234, s[44:45]
	s_add_u32 m0, s101, 0xc400
	s_nop 0
	s_nop 0
	global_load_lds_dwordx4 v235, s[98:99]
	s_add_u32 m0, s101, 0x400
	s_nop 0
	s_nop 0
	global_load_lds_dwordx4 v235, s[44:45]
	s_waitcnt lgkmcnt(2)
	s_setprio 1
	v_mfma_f32_32x32x16_bf16 v[112:127], v[178:181], v[170:173], v[112:127]
	v_mfma_f32_32x32x16_bf16 v[96:111], v[178:181], v[174:177], v[96:111]
	v_mfma_f32_32x32x16_bf16 v[80:95], v[182:185], v[170:173], v[80:95]
	v_mfma_f32_32x32x16_bf16 v[64:79], v[182:185], v[174:177], v[64:79]
	s_setprio 0
	s_nop 0
	ds_read_b128 v[206:209], v233 offset:24576
	ds_read_b128 v[210:213], v233 offset:26624
	ds_read_b128 v[214:217], v231 offset:24576
	ds_read_b128 v[218:221], v231 offset:26624
	s_add_u32 m0, s101, 0xc800
	s_nop 0
	s_nop 0
	global_load_lds_dwordx4 v236, s[98:99]
	s_add_u32 m0, s101, 0x800
	s_nop 0
	s_nop 0
	global_load_lds_dwordx4 v236, s[44:45]
	s_add_u32 m0, s101, 0xcc00
	s_nop 0
	s_nop 0
	global_load_lds_dwordx4 v237, s[98:99]
	s_add_u32 m0, s101, 0xc00
	s_nop 0
	s_nop 0
	global_load_lds_dwordx4 v237, s[44:45]
	s_waitcnt lgkmcnt(4)
	s_setprio 1
	v_mfma_f32_32x32x16_bf16 v[48:63], v[186:189], v[170:173], v[48:63]
	v_mfma_f32_32x32x16_bf16 v[32:47], v[186:189], v[174:177], v[32:47]
	v_mfma_f32_32x32x16_bf16 v[16:31], v[190:193], v[170:173], v[16:31]
	v_mfma_f32_32x32x16_bf16 v[0:15], v[190:193], v[174:177], v[0:15]
	s_setprio 0
	s_nop 0
	ds_read_b128 v[222:225], v231 offset:28672
	ds_read_b128 v[226:229], v231 offset:30720
	v_xad_u32 v241, s36, v240, v238
	v_xad_u32 v242, s37, v240, v239
	s_add_u32 m0, s49, 0xc000
	s_nop 0
	s_nop 0
	global_load_lds_dwordx4 v241, s[94:95]
	s_add_u32 m0, s49, 0xffffffc0
	s_nop 0
	s_nop 0
	global_load_lds_dwordx4 v241, s[94:95] offset:64
	s_add_u32 m0, s49, 0xc400
	s_nop 0
	s_nop 0
	global_load_lds_dwordx4 v242, s[94:95]
	s_add_u32 m0, s49, 0x3c0
	s_nop 0
	s_nop 0
	global_load_lds_dwordx4 v242, s[94:95] offset:64
	s_add_u32 s36, s36, 0x80
	s_xor_b32 s37, s36, 0x800
	s_add_u32 s98, s98, 128
	s_addc_u32 s99, s99, 0
	s_nop 0
	s_add_u32 s44, s44, 128
	s_addc_u32 s45, s45, 0
	s_waitcnt lgkmcnt(2)
	s_setprio 1
	s_nop 0
	v_mfma_f32_32x32x16_bf16 v[112:127], v[214:217], v[206:209], v[112:127]
	v_mfma_f32_32x32x16_bf16 v[96:111], v[214:217], v[210:213], v[96:111]
	v_mfma_f32_32x32x16_bf16 v[80:95], v[218:221], v[206:209], v[80:95]
	v_mfma_f32_32x32x16_bf16 v[64:79], v[218:221], v[210:213], v[64:79]
	s_setprio 0
	s_waitcnt vmcnt(0) lgkmcnt(0)
	s_barrier
	s_nop 0
	ds_read_b128 v[170:173], v232 offset:49152
	ds_read_b128 v[174:177], v232 offset:51200
	ds_read_b128 v[178:181], v230 offset:49152
	ds_read_b128 v[182:185], v230 offset:51200
	ds_read_b128 v[186:189], v230 offset:53248
	ds_read_b128 v[190:193], v230 offset:55296
	s_setprio 1
	s_nop 0
	v_mfma_f32_32x32x16_bf16 v[48:63], v[222:225], v[206:209], v[48:63]
	v_mfma_f32_32x32x16_bf16 v[32:47], v[222:225], v[210:213], v[32:47]
	v_mfma_f32_32x32x16_bf16 v[16:31], v[226:229], v[206:209], v[16:31]
	v_mfma_f32_32x32x16_bf16 v[0:15], v[226:229], v[210:213], v[0:15]
	s_setprio 0
	s_waitcnt lgkmcnt(2)
	s_setprio 1
	s_nop 0
	v_mfma_f32_32x32x16_bf16 v[112:127], v[178:181], v[170:173], v[112:127]
	v_mfma_f32_32x32x16_bf16 v[96:111], v[178:181], v[174:177], v[96:111]
	v_mfma_f32_32x32x16_bf16 v[80:95], v[182:185], v[170:173], v[80:95]
	v_mfma_f32_32x32x16_bf16 v[64:79], v[182:185], v[174:177], v[64:79]
	s_setprio 0
	s_nop 0
	ds_read_b128 v[206:209], v233 offset:49152
	ds_read_b128 v[210:213], v233 offset:51200
	ds_read_b128 v[214:217], v231 offset:49152
	ds_read_b128 v[218:221], v231 offset:51200
	s_waitcnt lgkmcnt(4)
	s_setprio 1
	v_mfma_f32_32x32x16_bf16 v[48:63], v[186:189], v[170:173], v[48:63]
	v_mfma_f32_32x32x16_bf16 v[32:47], v[186:189], v[174:177], v[32:47]
	v_mfma_f32_32x32x16_bf16 v[16:31], v[190:193], v[170:173], v[16:31]
	v_mfma_f32_32x32x16_bf16 v[0:15], v[190:193], v[174:177], v[0:15]
	s_setprio 0
	s_nop 0
	ds_read_b128 v[222:225], v231 offset:53248
	ds_read_b128 v[226:229], v231 offset:55296
	s_waitcnt lgkmcnt(2)
	s_setprio 1
	v_mfma_f32_32x32x16_bf16 v[112:127], v[214:217], v[206:209], v[112:127]
	v_mfma_f32_32x32x16_bf16 v[96:111], v[214:217], v[210:213], v[96:111]
	v_mfma_f32_32x32x16_bf16 v[80:95], v[218:221], v[206:209], v[80:95]
	v_mfma_f32_32x32x16_bf16 v[64:79], v[218:221], v[210:213], v[64:79]
	s_setprio 0
	s_waitcnt vmcnt(0) lgkmcnt(0)
	s_barrier
	s_nop 0
	ds_read_b128 v[170:173], v232 offset:0
	ds_read_b128 v[174:177], v232 offset:2048
	ds_read_b128 v[178:181], v230 offset:0
	ds_read_b128 v[182:185], v230 offset:2048
	ds_read_b128 v[186:189], v230 offset:4096
	ds_read_b128 v[190:193], v230 offset:6144
	s_setprio 1
	s_nop 0
	v_mfma_f32_32x32x16_bf16 v[48:63], v[222:225], v[206:209], v[48:63]
	v_mfma_f32_32x32x16_bf16 v[32:47], v[222:225], v[210:213], v[32:47]
	v_mfma_f32_32x32x16_bf16 v[16:31], v[226:229], v[206:209], v[16:31]
	v_mfma_f32_32x32x16_bf16 v[0:15], v[226:229], v[210:213], v[0:15]
	s_setprio 0
	s_nop 0
	s_add_u32 m0, s101, 0x6000
	s_nop 0
	s_nop 0
	global_load_lds_dwordx4 v234, s[98:99]
	s_add_u32 m0, s101, 0xc000
	s_nop 0
	s_nop 0
	global_load_lds_dwordx4 v234, s[44:45]
	s_add_u32 m0, s101, 0x6400
	s_nop 0
	s_nop 0
	global_load_lds_dwordx4 v235, s[98:99]
	s_add_u32 m0, s101, 0xc400
	s_nop 0
	s_nop 0
	global_load_lds_dwordx4 v235, s[44:45]
	s_waitcnt lgkmcnt(2)
	s_setprio 1
	v_mfma_f32_32x32x16_bf16 v[112:127], v[178:181], v[170:173], v[112:127]
	v_mfma_f32_32x32x16_bf16 v[96:111], v[178:181], v[174:177], v[96:111]
	v_mfma_f32_32x32x16_bf16 v[80:95], v[182:185], v[170:173], v[80:95]
	v_mfma_f32_32x32x16_bf16 v[64:79], v[182:185], v[174:177], v[64:79]
	s_setprio 0
	s_nop 0
	ds_read_b128 v[206:209], v233 offset:0
	ds_read_b128 v[210:213], v233 offset:2048
	ds_read_b128 v[214:217], v231 offset:0
	ds_read_b128 v[218:221], v231 offset:2048
	s_add_u32 m0, s101, 0x6800
	s_nop 0
	s_nop 0
	global_load_lds_dwordx4 v236, s[98:99]
	s_add_u32 m0, s101, 0xc800
	s_nop 0
	s_nop 0
	global_load_lds_dwordx4 v236, s[44:45]
	s_add_u32 m0, s101, 0x6c00
	s_nop 0
	s_nop 0
	global_load_lds_dwordx4 v237, s[98:99]
	s_add_u32 m0, s101, 0xcc00
	s_nop 0
	s_nop 0
	global_load_lds_dwordx4 v237, s[44:45]
	s_waitcnt lgkmcnt(4)
	s_setprio 1
	v_mfma_f32_32x32x16_bf16 v[48:63], v[186:189], v[170:173], v[48:63]
	v_mfma_f32_32x32x16_bf16 v[32:47], v[186:189], v[174:177], v[32:47]
	v_mfma_f32_32x32x16_bf16 v[16:31], v[190:193], v[170:173], v[16:31]
	v_mfma_f32_32x32x16_bf16 v[0:15], v[190:193], v[174:177], v[0:15]
	s_setprio 0
	s_nop 0
	ds_read_b128 v[222:225], v231 offset:4096
	ds_read_b128 v[226:229], v231 offset:6144
	v_xad_u32 v241, s36, v240, v238
	v_xad_u32 v242, s37, v240, v239
	s_add_u32 m0, s49, 0x6000
	s_nop 0
	s_nop 0
	global_load_lds_dwordx4 v241, s[94:95]
	s_add_u32 m0, s49, 0xbfc0
	s_nop 0
	s_nop 0
	global_load_lds_dwordx4 v241, s[94:95] offset:64
	s_add_u32 m0, s49, 0x6400
	s_nop 0
	s_nop 0
	global_load_lds_dwordx4 v242, s[94:95]
	s_add_u32 m0, s49, 0xc3c0
	s_nop 0
	s_nop 0
	global_load_lds_dwordx4 v242, s[94:95] offset:64
	s_add_u32 s36, s36, 0x80
	s_xor_b32 s37, s36, 0x800
	s_add_u32 s98, s98, 128
	s_addc_u32 s99, s99, 0
	s_nop 0
	s_add_u32 s44, s44, 128
	s_addc_u32 s45, s45, 0
	s_waitcnt lgkmcnt(2)
	s_setprio 1
	s_nop 0
	v_mfma_f32_32x32x16_bf16 v[112:127], v[214:217], v[206:209], v[112:127]
	v_mfma_f32_32x32x16_bf16 v[96:111], v[214:217], v[210:213], v[96:111]
	v_mfma_f32_32x32x16_bf16 v[80:95], v[218:221], v[206:209], v[80:95]
	v_mfma_f32_32x32x16_bf16 v[64:79], v[218:221], v[210:213], v[64:79]
	s_setprio 0
	s_waitcnt vmcnt(0) lgkmcnt(0)
	s_barrier
	s_nop 0
	ds_read_b128 v[170:173], v232 offset:24576
	ds_read_b128 v[174:177], v232 offset:26624
	ds_read_b128 v[178:181], v230 offset:24576
	ds_read_b128 v[182:185], v230 offset:26624
	ds_read_b128 v[186:189], v230 offset:28672
	ds_read_b128 v[190:193], v230 offset:30720
	s_setprio 1
	s_nop 0
	v_mfma_f32_32x32x16_bf16 v[48:63], v[222:225], v[206:209], v[48:63]
	v_mfma_f32_32x32x16_bf16 v[32:47], v[222:225], v[210:213], v[32:47]
	v_mfma_f32_32x32x16_bf16 v[16:31], v[226:229], v[206:209], v[16:31]
	v_mfma_f32_32x32x16_bf16 v[0:15], v[226:229], v[210:213], v[0:15]
	s_setprio 0
	s_waitcnt lgkmcnt(2)
	s_setprio 1
	s_nop 0
	v_mfma_f32_32x32x16_bf16 v[112:127], v[178:181], v[170:173], v[112:127]
	v_mfma_f32_32x32x16_bf16 v[96:111], v[178:181], v[174:177], v[96:111]
	v_mfma_f32_32x32x16_bf16 v[80:95], v[182:185], v[170:173], v[80:95]
	v_mfma_f32_32x32x16_bf16 v[64:79], v[182:185], v[174:177], v[64:79]
	s_setprio 0
	s_nop 0
	ds_read_b128 v[206:209], v233 offset:24576
	ds_read_b128 v[210:213], v233 offset:26624
	ds_read_b128 v[214:217], v231 offset:24576
	ds_read_b128 v[218:221], v231 offset:26624
	s_waitcnt lgkmcnt(4)
	s_setprio 1
	v_mfma_f32_32x32x16_bf16 v[48:63], v[186:189], v[170:173], v[48:63]
	v_mfma_f32_32x32x16_bf16 v[32:47], v[186:189], v[174:177], v[32:47]
	v_mfma_f32_32x32x16_bf16 v[16:31], v[190:193], v[170:173], v[16:31]
	v_mfma_f32_32x32x16_bf16 v[0:15], v[190:193], v[174:177], v[0:15]
	s_setprio 0
	s_nop 0
	ds_read_b128 v[222:225], v231 offset:28672
	ds_read_b128 v[226:229], v231 offset:30720
	s_waitcnt lgkmcnt(2)
	s_setprio 1
	v_mfma_f32_32x32x16_bf16 v[112:127], v[214:217], v[206:209], v[112:127]
	v_mfma_f32_32x32x16_bf16 v[96:111], v[214:217], v[210:213], v[96:111]
	v_mfma_f32_32x32x16_bf16 v[80:95], v[218:221], v[206:209], v[80:95]
	v_mfma_f32_32x32x16_bf16 v[64:79], v[218:221], v[210:213], v[64:79]
	s_setprio 0
	s_waitcnt vmcnt(0) lgkmcnt(0)
	s_barrier
	s_nop 0
	ds_read_b128 v[170:173], v232 offset:49152
	ds_read_b128 v[174:177], v232 offset:51200
	ds_read_b128 v[178:181], v230 offset:49152
	ds_read_b128 v[182:185], v230 offset:51200
	ds_read_b128 v[186:189], v230 offset:53248
	ds_read_b128 v[190:193], v230 offset:55296
	s_setprio 1
	s_nop 0
	v_mfma_f32_32x32x16_bf16 v[48:63], v[222:225], v[206:209], v[48:63]
	v_mfma_f32_32x32x16_bf16 v[32:47], v[222:225], v[210:213], v[32:47]
	v_mfma_f32_32x32x16_bf16 v[16:31], v[226:229], v[206:209], v[16:31]
	v_mfma_f32_32x32x16_bf16 v[0:15], v[226:229], v[210:213], v[0:15]
	s_setprio 0
	s_add_u32 m0, s101, 0x0
	s_nop 0
	s_nop 0
	global_load_lds_dwordx4 v234, s[98:99]
	s_add_u32 m0, s101, 0x6000
	s_nop 0
	s_nop 0
	global_load_lds_dwordx4 v234, s[44:45]
	s_add_u32 m0, s101, 0x400
	s_nop 0
	s_nop 0
	global_load_lds_dwordx4 v235, s[98:99]
	s_add_u32 m0, s101, 0x6400
	s_nop 0
	s_nop 0
	global_load_lds_dwordx4 v235, s[44:45]
	s_waitcnt lgkmcnt(2)
	s_setprio 1
	v_mfma_f32_32x32x16_bf16 v[112:127], v[178:181], v[170:173], v[112:127]
	v_mfma_f32_32x32x16_bf16 v[96:111], v[178:181], v[174:177], v[96:111]
	v_mfma_f32_32x32x16_bf16 v[80:95], v[182:185], v[170:173], v[80:95]
	v_mfma_f32_32x32x16_bf16 v[64:79], v[182:185], v[174:177], v[64:79]
	s_setprio 0
	s_nop 0
	ds_read_b128 v[206:209], v233 offset:49152
	ds_read_b128 v[210:213], v233 offset:51200
	ds_read_b128 v[214:217], v231 offset:49152
	ds_read_b128 v[218:221], v231 offset:51200
	s_add_u32 m0, s101, 0x800
	s_nop 0
	s_nop 0
	global_load_lds_dwordx4 v236, s[98:99]
	s_add_u32 m0, s101, 0x6800
	s_nop 0
	s_nop 0
	global_load_lds_dwordx4 v236, s[44:45]
	s_add_u32 m0, s101, 0xc00
	s_nop 0
	s_nop 0
	global_load_lds_dwordx4 v237, s[98:99]
	s_add_u32 m0, s101, 0x6c00
	s_nop 0
	s_nop 0
	global_load_lds_dwordx4 v237, s[44:45]
	s_waitcnt lgkmcnt(4)
	s_setprio 1
	v_mfma_f32_32x32x16_bf16 v[48:63], v[186:189], v[170:173], v[48:63]
	v_mfma_f32_32x32x16_bf16 v[32:47], v[186:189], v[174:177], v[32:47]
	v_mfma_f32_32x32x16_bf16 v[16:31], v[190:193], v[170:173], v[16:31]
	v_mfma_f32_32x32x16_bf16 v[0:15], v[190:193], v[174:177], v[0:15]
	s_setprio 0
	s_nop 0
	ds_read_b128 v[222:225], v231 offset:53248
	ds_read_b128 v[226:229], v231 offset:55296
	v_xad_u32 v241, s36, v240, v238
	v_xad_u32 v242, s37, v240, v239
	s_add_u32 m0, s49, 0x0
	s_nop 0
	global_load_lds_dwordx4 v241, s[94:95]
	s_add_u32 m0, s49, 0x5fc0
	s_nop 0
	s_nop 0
	global_load_lds_dwordx4 v241, s[94:95] offset:64
	s_add_u32 m0, s49, 0x400
	s_nop 0
	s_nop 0
	global_load_lds_dwordx4 v242, s[94:95]
	s_add_u32 m0, s49, 0x63c0
	s_nop 0
	s_nop 0
	global_load_lds_dwordx4 v242, s[94:95] offset:64
	s_add_u32 s36, s36, 0x80
	s_xor_b32 s37, s36, 0x800
	s_add_u32 s98, s98, 128
	s_addc_u32 s99, s99, 0
	s_nop 0
	s_add_u32 s44, s44, 128
	s_addc_u32 s45, s45, 0
	s_waitcnt lgkmcnt(2)
	s_setprio 1
	s_nop 0
	v_mfma_f32_32x32x16_bf16 v[112:127], v[214:217], v[206:209], v[112:127]
	v_mfma_f32_32x32x16_bf16 v[96:111], v[214:217], v[210:213], v[96:111]
	v_mfma_f32_32x32x16_bf16 v[80:95], v[218:221], v[206:209], v[80:95]
	v_mfma_f32_32x32x16_bf16 v[64:79], v[218:221], v[210:213], v[64:79]
	s_setprio 0
	s_waitcnt vmcnt(0) lgkmcnt(0)
	s_barrier
	s_nop 0
	ds_read_b128 v[170:173], v232 offset:0
	ds_read_b128 v[174:177], v232 offset:2048
	ds_read_b128 v[178:181], v230 offset:0
	ds_read_b128 v[182:185], v230 offset:2048
	ds_read_b128 v[186:189], v230 offset:4096
	ds_read_b128 v[190:193], v230 offset:6144
	s_setprio 1
	s_nop 0
	v_mfma_f32_32x32x16_bf16 v[48:63], v[222:225], v[206:209], v[48:63]
	v_mfma_f32_32x32x16_bf16 v[32:47], v[222:225], v[210:213], v[32:47]
	v_mfma_f32_32x32x16_bf16 v[16:31], v[226:229], v[206:209], v[16:31]
	v_mfma_f32_32x32x16_bf16 v[0:15], v[226:229], v[210:213], v[0:15]
	s_setprio 0
	s_waitcnt lgkmcnt(2)
	s_setprio 1
	s_nop 0
	v_mfma_f32_32x32x16_bf16 v[112:127], v[178:181], v[170:173], v[112:127]
	v_mfma_f32_32x32x16_bf16 v[96:111], v[178:181], v[174:177], v[96:111]
	v_mfma_f32_32x32x16_bf16 v[80:95], v[182:185], v[170:173], v[80:95]
	v_mfma_f32_32x32x16_bf16 v[64:79], v[182:185], v[174:177], v[64:79]
	s_setprio 0
	s_nop 0
	ds_read_b128 v[206:209], v233 offset:0
	ds_read_b128 v[210:213], v233 offset:2048
	ds_read_b128 v[214:217], v231 offset:0
	ds_read_b128 v[218:221], v231 offset:2048
	s_waitcnt lgkmcnt(4)
	s_setprio 1
	v_mfma_f32_32x32x16_bf16 v[48:63], v[186:189], v[170:173], v[48:63]
	v_mfma_f32_32x32x16_bf16 v[32:47], v[186:189], v[174:177], v[32:47]
	v_mfma_f32_32x32x16_bf16 v[16:31], v[190:193], v[170:173], v[16:31]
	v_mfma_f32_32x32x16_bf16 v[0:15], v[190:193], v[174:177], v[0:15]
	s_setprio 0
	s_nop 0
	ds_read_b128 v[222:225], v231 offset:4096
	ds_read_b128 v[226:229], v231 offset:6144
	s_waitcnt lgkmcnt(2)
	s_setprio 1
	v_mfma_f32_32x32x16_bf16 v[112:127], v[214:217], v[206:209], v[112:127]
	v_mfma_f32_32x32x16_bf16 v[96:111], v[214:217], v[210:213], v[96:111]
	v_mfma_f32_32x32x16_bf16 v[80:95], v[218:221], v[206:209], v[80:95]
	v_mfma_f32_32x32x16_bf16 v[64:79], v[218:221], v[210:213], v[64:79]
	s_setprio 0
	s_sub_u32 s100, s100, 1
	s_cmp_lg_u32 s100, 0
	s_cbranch_scc1 .Lp1m_kloop
	s_waitcnt vmcnt(0) lgkmcnt(0)
	s_barrier
	ds_read_b128 v[170:173], v232 offset:24576
	ds_read_b128 v[174:177], v232 offset:26624
	ds_read_b128 v[178:181], v230 offset:24576
	ds_read_b128 v[182:185], v230 offset:26624
	ds_read_b128 v[186:189], v230 offset:28672
	ds_read_b128 v[190:193], v230 offset:30720
	s_setprio 1
	s_nop 0
	v_mfma_f32_32x32x16_bf16 v[48:63], v[222:225], v[206:209], v[48:63]
	v_mfma_f32_32x32x16_bf16 v[32:47], v[222:225], v[210:213], v[32:47]
	v_mfma_f32_32x32x16_bf16 v[16:31], v[226:229], v[206:209], v[16:31]
	v_mfma_f32_32x32x16_bf16 v[0:15], v[226:229], v[210:213], v[0:15]
	s_setprio 0
	s_nop 0
	s_add_u32 m0, s101, 0xc000
	s_nop 0
	s_nop 0
	global_load_lds_dwordx4 v234, s[98:99]
	s_add_u32 m0, s101, 0x0
	s_nop 0
	global_load_lds_dwordx4 v234, s[44:45]
	s_add_u32 m0, s101, 0xc400
	s_nop 0
	s_nop 0
	global_load_lds_dwordx4 v235, s[98:99]
	s_add_u32 m0, s101, 0x400
	s_nop 0
	s_nop 0
	global_load_lds_dwordx4 v235, s[44:45]
	s_waitcnt lgkmcnt(2)
	s_setprio 1
	v_mfma_f32_32x32x16_bf16 v[112:127], v[178:181], v[170:173], v[112:127]
	v_mfma_f32_32x32x16_bf16 v[96:111], v[178:181], v[174:177], v[96:111]
	v_mfma_f32_32x32x16_bf16 v[80:95], v[182:185], v[170:173], v[80:95]
	v_mfma_f32_32x32x16_bf16 v[64:79], v[182:185], v[174:177], v[64:79]
	s_setprio 0
	s_nop 0
	ds_read_b128 v[206:209], v233 offset:24576
	ds_read_b128 v[210:213], v233 offset:26624
	ds_read_b128 v[214:217], v231 offset:24576
	ds_read_b128 v[218:221], v231 offset:26624
	s_add_u32 m0, s101, 0xc800
	s_nop 0
	s_nop 0
	global_load_lds_dwordx4 v236, s[98:99]
	s_add_u32 m0, s101, 0x800
	s_nop 0
	s_nop 0
	global_load_lds_dwordx4 v236, s[44:45]
	s_add_u32 m0, s101, 0xcc00
	s_nop 0
	s_nop 0
	global_load_lds_dwordx4 v237, s[98:99]
	s_add_u32 m0, s101, 0xc00
	s_nop 0
	s_nop 0
	global_load_lds_dwordx4 v237, s[44:45]
	s_waitcnt lgkmcnt(4)
	s_setprio 1
	v_mfma_f32_32x32x16_bf16 v[48:63], v[186:189], v[170:173], v[48:63]
	v_mfma_f32_32x32x16_bf16 v[32:47], v[186:189], v[174:177], v[32:47]
	v_mfma_f32_32x32x16_bf16 v[16:31], v[190:193], v[170:173], v[16:31]
	v_mfma_f32_32x32x16_bf16 v[0:15], v[190:193], v[174:177], v[0:15]
	s_setprio 0
	s_nop 0
	ds_read_b128 v[222:225], v231 offset:28672
	ds_read_b128 v[226:229], v231 offset:30720
	v_xad_u32 v241, s36, v240, v238
	v_xad_u32 v242, s37, v240, v239
	s_add_u32 m0, s49, 0xc000
	s_nop 0
	s_nop 0
	global_load_lds_dwordx4 v241, s[94:95]
	s_add_u32 m0, s49, 0xffffffc0
	s_nop 0
	s_nop 0
	global_load_lds_dwordx4 v241, s[94:95] offset:64
	s_add_u32 m0, s49, 0xc400
	s_nop 0
	s_nop 0
	global_load_lds_dwordx4 v242, s[94:95]
	s_add_u32 m0, s49, 0x3c0
	s_nop 0
	s_nop 0
	global_load_lds_dwordx4 v242, s[94:95] offset:64
	s_add_u32 s36, s36, 0x80
	s_xor_b32 s37, s36, 0x800
	s_add_u32 s98, s98, 128
	s_addc_u32 s99, s99, 0
	s_nop 0
	s_add_u32 s44, s44, 128
	s_addc_u32 s45, s45, 0
	s_waitcnt lgkmcnt(2)
	s_setprio 1
	s_nop 0
	v_mfma_f32_32x32x16_bf16 v[112:127], v[214:217], v[206:209], v[112:127]
	v_mfma_f32_32x32x16_bf16 v[96:111], v[214:217], v[210:213], v[96:111]
	v_mfma_f32_32x32x16_bf16 v[80:95], v[218:221], v[206:209], v[80:95]
	v_mfma_f32_32x32x16_bf16 v[64:79], v[218:221], v[210:213], v[64:79]
	s_setprio 0
	s_waitcnt vmcnt(0) lgkmcnt(0)
	s_barrier
	s_nop 0
	ds_read_b128 v[170:173], v232 offset:49152
	ds_read_b128 v[174:177], v232 offset:51200
	ds_read_b128 v[178:181], v230 offset:49152
	ds_read_b128 v[182:185], v230 offset:51200
	ds_read_b128 v[186:189], v230 offset:53248
	ds_read_b128 v[190:193], v230 offset:55296
	s_setprio 1
	s_nop 0
	v_mfma_f32_32x32x16_bf16 v[48:63], v[222:225], v[206:209], v[48:63]
	v_mfma_f32_32x32x16_bf16 v[32:47], v[222:225], v[210:213], v[32:47]
	v_mfma_f32_32x32x16_bf16 v[16:31], v[226:229], v[206:209], v[16:31]
	v_mfma_f32_32x32x16_bf16 v[0:15], v[226:229], v[210:213], v[0:15]
	s_setprio 0
	s_waitcnt lgkmcnt(2)
	s_setprio 1
	s_nop 0
	v_mfma_f32_32x32x16_bf16 v[112:127], v[178:181], v[170:173], v[112:127]
	v_mfma_f32_32x32x16_bf16 v[96:111], v[178:181], v[174:177], v[96:111]
	v_mfma_f32_32x32x16_bf16 v[80:95], v[182:185], v[170:173], v[80:95]
	v_mfma_f32_32x32x16_bf16 v[64:79], v[182:185], v[174:177], v[64:79]
	s_setprio 0
	s_nop 0
	ds_read_b128 v[206:209], v233 offset:49152
	ds_read_b128 v[210:213], v233 offset:51200
	ds_read_b128 v[214:217], v231 offset:49152
	ds_read_b128 v[218:221], v231 offset:51200
	s_waitcnt lgkmcnt(4)
	s_setprio 1
	v_mfma_f32_32x32x16_bf16 v[48:63], v[186:189], v[170:173], v[48:63]
	v_mfma_f32_32x32x16_bf16 v[32:47], v[186:189], v[174:177], v[32:47]
	v_mfma_f32_32x32x16_bf16 v[16:31], v[190:193], v[170:173], v[16:31]
	v_mfma_f32_32x32x16_bf16 v[0:15], v[190:193], v[174:177], v[0:15]
	s_setprio 0
	s_nop 0
	ds_read_b128 v[222:225], v231 offset:53248
	ds_read_b128 v[226:229], v231 offset:55296
	s_waitcnt lgkmcnt(2)
	s_setprio 1
	v_mfma_f32_32x32x16_bf16 v[112:127], v[214:217], v[206:209], v[112:127]
	v_mfma_f32_32x32x16_bf16 v[96:111], v[214:217], v[210:213], v[96:111]
	v_mfma_f32_32x32x16_bf16 v[80:95], v[218:221], v[206:209], v[80:95]
	v_mfma_f32_32x32x16_bf16 v[64:79], v[218:221], v[210:213], v[64:79]
	s_setprio 0
	s_waitcnt vmcnt(0) lgkmcnt(0)
	s_barrier
	s_nop 0
	ds_read_b128 v[170:173], v232 offset:0
	ds_read_b128 v[174:177], v232 offset:2048
	ds_read_b128 v[178:181], v230 offset:0
	ds_read_b128 v[182:185], v230 offset:2048
	ds_read_b128 v[186:189], v230 offset:4096
	ds_read_b128 v[190:193], v230 offset:6144
	s_setprio 1
	s_nop 0
	v_mfma_f32_32x32x16_bf16 v[48:63], v[222:225], v[206:209], v[48:63]
	v_mfma_f32_32x32x16_bf16 v[32:47], v[222:225], v[210:213], v[32:47]
	v_mfma_f32_32x32x16_bf16 v[16:31], v[226:229], v[206:209], v[16:31]
	v_mfma_f32_32x32x16_bf16 v[0:15], v[226:229], v[210:213], v[0:15]
	s_setprio 0
	s_waitcnt lgkmcnt(2)
	s_setprio 1
	s_nop 0
	v_mfma_f32_32x32x16_bf16 v[112:127], v[178:181], v[170:173], v[112:127]
	v_mfma_f32_32x32x16_bf16 v[96:111], v[178:181], v[174:177], v[96:111]
	v_mfma_f32_32x32x16_bf16 v[80:95], v[182:185], v[170:173], v[80:95]
	v_mfma_f32_32x32x16_bf16 v[64:79], v[182:185], v[174:177], v[64:79]
	s_setprio 0
	s_nop 0
	ds_read_b128 v[206:209], v233 offset:0
	ds_read_b128 v[210:213], v233 offset:2048
	ds_read_b128 v[214:217], v231 offset:0
	ds_read_b128 v[218:221], v231 offset:2048
	s_waitcnt lgkmcnt(4)
	s_setprio 1
	v_mfma_f32_32x32x16_bf16 v[48:63], v[186:189], v[170:173], v[48:63]
	v_mfma_f32_32x32x16_bf16 v[32:47], v[186:189], v[174:177], v[32:47]
	v_mfma_f32_32x32x16_bf16 v[16:31], v[190:193], v[170:173], v[16:31]
	v_mfma_f32_32x32x16_bf16 v[0:15], v[190:193], v[174:177], v[0:15]
	s_setprio 0
	s_nop 0
	ds_read_b128 v[222:225], v231 offset:4096
	ds_read_b128 v[226:229], v231 offset:6144
	s_waitcnt lgkmcnt(2)
	s_setprio 1
	v_mfma_f32_32x32x16_bf16 v[112:127], v[214:217], v[206:209], v[112:127]
	v_mfma_f32_32x32x16_bf16 v[96:111], v[214:217], v[210:213], v[96:111]
	v_mfma_f32_32x32x16_bf16 v[80:95], v[218:221], v[206:209], v[80:95]
	v_mfma_f32_32x32x16_bf16 v[64:79], v[218:221], v[210:213], v[64:79]
	s_setprio 0
	s_waitcnt lgkmcnt(0)
	s_setprio 1
	s_nop 0
	v_mfma_f32_32x32x16_bf16 v[48:63], v[222:225], v[206:209], v[48:63]
	v_mfma_f32_32x32x16_bf16 v[32:47], v[222:225], v[210:213], v[32:47]
	v_mfma_f32_32x32x16_bf16 v[16:31], v[226:229], v[206:209], v[16:31]
	v_mfma_f32_32x32x16_bf16 v[0:15], v[226:229], v[210:213], v[0:15]
	s_setprio 0
	s_mul_hi_i32 s41, s42, 0x540000
	s_mul_i32 s42, s42, 0x540000
	s_add_u32 s42, s31, s42
	s_addc_u32 s43, s33, s41
	s_lshl_b32 s40, s40, 8
	s_add_u32 s42, s42, s40
	s_addc_u32 s43, s43, 0
	s_add_i32 s16, s16, s17
	s_add_i32 s47, s47, s17
	v_lshrrev_b32_e32 v170, 6, v204
	v_and_b32_e32 v171, 31, v204
	v_bfe_u32 v172, v204, 5, 1
	v_mul_u32_u24_e32 v173, 0x4400, v170
	v_mul_u32_u24_e32 v174, 544, v172
	v_lshl_add_u32 v174, v171, 2, v174
	v_add3_u32 v174, v174, v173, 32
	v_and_b32_e32 v175, 7, v204
	v_bfe_u32 v176, v204, 3, 3
	v_mul_u32_u24_e32 v177, 272, v176
	v_lshl_add_u32 v177, v175, 5, v177
	v_add3_u32 v177, v177, v173, 32
	v_lshrrev_b32_e32 v178, 1, v170
	v_and_b32_e32 v179, 1, v170
	v_lshlrev_b32_e32 v178, 7, v178
	v_lshl_add_u32 v178, v176, 1, v178
	v_mul_u32_u24_e32 v178, 0x5400, v178
	v_lshl_add_u32 v178, v179, 7, v178
	v_lshl_add_u32 v178, v175, 4, v178
	v_add_u32_e32 v179, 0x5400, v178
	v_mov_b32_e32 v180, 0x05040100
	v_mov_b32_e32 v181, 0x07060302
	s_waitcnt vmcnt(0)
	s_barrier
	v_cvt_pk_bf16_f32 v112, v112, v113
	ds_write_b32 v174, v112 offset:0
	v_cvt_pk_bf16_f32 v114, v114, v115
	ds_write_b32 v174, v114 offset:272
	v_cvt_pk_bf16_f32 v116, v116, v117
	ds_write_b32 v174, v116 offset:1088
	v_cvt_pk_bf16_f32 v118, v118, v119
	ds_write_b32 v174, v118 offset:1360
	v_cvt_pk_bf16_f32 v120, v120, v121
	ds_write_b32 v174, v120 offset:2176
	v_cvt_pk_bf16_f32 v122, v122, v123
	ds_write_b32 v174, v122 offset:2448
	v_cvt_pk_bf16_f32 v124, v124, v125
	ds_write_b32 v174, v124 offset:3264
	v_cvt_pk_bf16_f32 v126, v126, v127
	ds_write_b32 v174, v126 offset:3536
	v_cvt_pk_bf16_f32 v96, v96, v97
	ds_write_b32 v174, v96 offset:128
	v_cvt_pk_bf16_f32 v98, v98, v99
	ds_write_b32 v174, v98 offset:400
	v_cvt_pk_bf16_f32 v100, v100, v101
	ds_write_b32 v174, v100 offset:1216
	v_cvt_pk_bf16_f32 v102, v102, v103
	ds_write_b32 v174, v102 offset:1488
	v_cvt_pk_bf16_f32 v104, v104, v105
	ds_write_b32 v174, v104 offset:2304
	v_cvt_pk_bf16_f32 v106, v106, v107
	ds_write_b32 v174, v106 offset:2576
	v_cvt_pk_bf16_f32 v108, v108, v109
	ds_write_b32 v174, v108 offset:3392
	v_cvt_pk_bf16_f32 v110, v110, v111
	ds_write_b32 v174, v110 offset:3664
	v_cvt_pk_bf16_f32 v80, v80, v81
	ds_write_b32 v174, v80 offset:4352
	v_cvt_pk_bf16_f32 v82, v82, v83
	ds_write_b32 v174, v82 offset:4624
	v_cvt_pk_bf16_f32 v84, v84, v85
	ds_write_b32 v174, v84 offset:5440
	v_cvt_pk_bf16_f32 v86, v86, v87
	ds_write_b32 v174, v86 offset:5712
	v_cvt_pk_bf16_f32 v88, v88, v89
	ds_write_b32 v174, v88 offset:6528
	v_cvt_pk_bf16_f32 v90, v90, v91
	ds_write_b32 v174, v90 offset:6800
	v_cvt_pk_bf16_f32 v92, v92, v93
	ds_write_b32 v174, v92 offset:7616
	v_cvt_pk_bf16_f32 v94, v94, v95
	ds_write_b32 v174, v94 offset:7888
	v_cvt_pk_bf16_f32 v64, v64, v65
	ds_write_b32 v174, v64 offset:4480
	v_cvt_pk_bf16_f32 v66, v66, v67
	ds_write_b32 v174, v66 offset:4752
	v_cvt_pk_bf16_f32 v68, v68, v69
	ds_write_b32 v174, v68 offset:5568
	v_cvt_pk_bf16_f32 v70, v70, v71
	ds_write_b32 v174, v70 offset:5840
	v_cvt_pk_bf16_f32 v72, v72, v73
	ds_write_b32 v174, v72 offset:6656
	v_cvt_pk_bf16_f32 v74, v74, v75
	ds_write_b32 v174, v74 offset:6928
	v_cvt_pk_bf16_f32 v76, v76, v77
	ds_write_b32 v174, v76 offset:7744
	v_cvt_pk_bf16_f32 v78, v78, v79
	ds_write_b32 v174, v78 offset:8016
	v_cvt_pk_bf16_f32 v48, v48, v49
	ds_write_b32 v174, v48 offset:8704
	v_cvt_pk_bf16_f32 v50, v50, v51
	ds_write_b32 v174, v50 offset:8976
	v_cvt_pk_bf16_f32 v52, v52, v53
	ds_write_b32 v174, v52 offset:9792
	v_cvt_pk_bf16_f32 v54, v54, v55
	ds_write_b32 v174, v54 offset:10064
	v_cvt_pk_bf16_f32 v56, v56, v57
	ds_write_b32 v174, v56 offset:10880
	v_cvt_pk_bf16_f32 v58, v58, v59
	ds_write_b32 v174, v58 offset:11152
	v_cvt_pk_bf16_f32 v60, v60, v61
	ds_write_b32 v174, v60 offset:11968
	v_cvt_pk_bf16_f32 v62, v62, v63
	ds_write_b32 v174, v62 offset:12240
	v_cvt_pk_bf16_f32 v32, v32, v33
	ds_write_b32 v174, v32 offset:8832
	v_cvt_pk_bf16_f32 v34, v34, v35
	ds_write_b32 v174, v34 offset:9104
	v_cvt_pk_bf16_f32 v36, v36, v37
	ds_write_b32 v174, v36 offset:9920
	v_cvt_pk_bf16_f32 v38, v38, v39
	ds_write_b32 v174, v38 offset:10192
	v_cvt_pk_bf16_f32 v40, v40, v41
	ds_write_b32 v174, v40 offset:11008
	v_cvt_pk_bf16_f32 v42, v42, v43
	ds_write_b32 v174, v42 offset:11280
	v_cvt_pk_bf16_f32 v44, v44, v45
	ds_write_b32 v174, v44 offset:12096
	v_cvt_pk_bf16_f32 v46, v46, v47
	ds_write_b32 v174, v46 offset:12368
	v_cvt_pk_bf16_f32 v16, v16, v17
	ds_write_b32 v174, v16 offset:13056
	v_cvt_pk_bf16_f32 v18, v18, v19
	ds_write_b32 v174, v18 offset:13328
	v_cvt_pk_bf16_f32 v20, v20, v21
	ds_write_b32 v174, v20 offset:14144
	v_cvt_pk_bf16_f32 v22, v22, v23
	ds_write_b32 v174, v22 offset:14416
	v_cvt_pk_bf16_f32 v24, v24, v25
	ds_write_b32 v174, v24 offset:15232
	v_cvt_pk_bf16_f32 v26, v26, v27
	ds_write_b32 v174, v26 offset:15504
	v_cvt_pk_bf16_f32 v28, v28, v29
	ds_write_b32 v174, v28 offset:16320
	v_cvt_pk_bf16_f32 v30, v30, v31
	ds_write_b32 v174, v30 offset:16592
	v_cvt_pk_bf16_f32 v0, v0, v1
	ds_write_b32 v174, v0 offset:13184
	v_cvt_pk_bf16_f32 v2, v2, v3
	ds_write_b32 v174, v2 offset:13456
	v_cvt_pk_bf16_f32 v4, v4, v5
	ds_write_b32 v174, v4 offset:14272
	v_cvt_pk_bf16_f32 v6, v6, v7
	ds_write_b32 v174, v6 offset:14544
	v_cvt_pk_bf16_f32 v8, v8, v9
	ds_write_b32 v174, v8 offset:15360
	v_cvt_pk_bf16_f32 v10, v10, v11
	ds_write_b32 v174, v10 offset:15632
	v_cvt_pk_bf16_f32 v12, v12, v13
	ds_write_b32 v174, v12 offset:16448
	v_cvt_pk_bf16_f32 v14, v14, v15
	ds_write_b32 v174, v14 offset:16720
	s_cmp_ge_i32 s16, s22
	s_cselect_b64 s[40:41], -1, 0
	s_waitcnt lgkmcnt(0)
	ds_read_b128 v[182:185], v177 offset:0
	ds_read_b128 v[186:189], v177 offset:16
	ds_read_b128 v[190:193], v177 offset:2176
	ds_read_b128 v[194:197], v177 offset:2192
	s_waitcnt lgkmcnt(2)
	v_perm_b32 v198, v183, v182, v180
	v_perm_b32 v199, v185, v184, v180
	v_perm_b32 v200, v187, v186, v180
	v_perm_b32 v201, v189, v188, v180
	v_perm_b32 v206, v183, v182, v181
	v_perm_b32 v207, v185, v184, v181
	v_perm_b32 v208, v187, v186, v181
	v_perm_b32 v209, v189, v188, v181
	global_store_dwordx4 v178, v[198:201], s[42:43]
	global_store_dwordx4 v179, v[206:209], s[42:43]
	s_add_u32 s42, s42, 0x54000
	s_addc_u32 s43, s43, 0
	s_nop 1
	ds_read_b128 v[182:185], v177 offset:4352
	ds_read_b128 v[186:189], v177 offset:4368
	s_waitcnt lgkmcnt(2)
	v_perm_b32 v198, v191, v190, v180
	v_perm_b32 v199, v193, v192, v180
	v_perm_b32 v200, v195, v194, v180
	v_perm_b32 v201, v197, v196, v180
	v_perm_b32 v206, v191, v190, v181
	v_perm_b32 v207, v193, v192, v181
	v_perm_b32 v208, v195, v194, v181
	v_perm_b32 v209, v197, v196, v181
	global_store_dwordx4 v178, v[198:201], s[42:43]
	global_store_dwordx4 v179, v[206:209], s[42:43]
	s_add_u32 s42, s42, 0x54000
	s_addc_u32 s43, s43, 0
	s_nop 1
	ds_read_b128 v[190:193], v177 offset:6528
	ds_read_b128 v[194:197], v177 offset:6544
	s_waitcnt lgkmcnt(2)
	v_perm_b32 v198, v183, v182, v180
	v_perm_b32 v199, v185, v184, v180
	v_perm_b32 v200, v187, v186, v180
	v_perm_b32 v201, v189, v188, v180
	v_perm_b32 v206, v183, v182, v181
	v_perm_b32 v207, v185, v184, v181
	v_perm_b32 v208, v187, v186, v181
	v_perm_b32 v209, v189, v188, v181
	global_store_dwordx4 v178, v[198:201], s[42:43]
	global_store_dwordx4 v179, v[206:209], s[42:43]
	s_add_u32 s42, s42, 0x54000
	s_addc_u32 s43, s43, 0
	s_nop 1
	ds_read_b128 v[182:185], v177 offset:8704
	ds_read_b128 v[186:189], v177 offset:8720
	s_waitcnt lgkmcnt(2)
	v_perm_b32 v198, v191, v190, v180
	v_perm_b32 v199, v193, v192, v180
	v_perm_b32 v200, v195, v194, v180
	v_perm_b32 v201, v197, v196, v180
	v_perm_b32 v206, v191, v190, v181
	v_perm_b32 v207, v193, v192, v181
	v_perm_b32 v208, v195, v194, v181
	v_perm_b32 v209, v197, v196, v181
	global_store_dwordx4 v178, v[198:201], s[42:43]
	global_store_dwordx4 v179, v[206:209], s[42:43]
	s_add_u32 s42, s42, 0x54000
	s_addc_u32 s43, s43, 0
	s_nop 1
	ds_read_b128 v[190:193], v177 offset:10880
	ds_read_b128 v[194:197], v177 offset:10896
	s_waitcnt lgkmcnt(2)
	v_perm_b32 v198, v183, v182, v180
	v_perm_b32 v199, v185, v184, v180
	v_perm_b32 v200, v187, v186, v180
	v_perm_b32 v201, v189, v188, v180
	v_perm_b32 v206, v183, v182, v181
	v_perm_b32 v207, v185, v184, v181
	v_perm_b32 v208, v187, v186, v181
	v_perm_b32 v209, v189, v188, v181
	global_store_dwordx4 v178, v[198:201], s[42:43]
	global_store_dwordx4 v179, v[206:209], s[42:43]
	s_add_u32 s42, s42, 0x54000
	s_addc_u32 s43, s43, 0
	s_nop 1
	ds_read_b128 v[182:185], v177 offset:13056
	ds_read_b128 v[186:189], v177 offset:13072
	s_waitcnt lgkmcnt(2)
	v_perm_b32 v198, v191, v190, v180
	v_perm_b32 v199, v193, v192, v180
	v_perm_b32 v200, v195, v194, v180
	v_perm_b32 v201, v197, v196, v180
	v_perm_b32 v206, v191, v190, v181
	v_perm_b32 v207, v193, v192, v181
	v_perm_b32 v208, v195, v194, v181
	v_perm_b32 v209, v197, v196, v181
	global_store_dwordx4 v178, v[198:201], s[42:43]
	global_store_dwordx4 v179, v[206:209], s[42:43]
	s_add_u32 s42, s42, 0x54000
	s_addc_u32 s43, s43, 0
	s_nop 1
	ds_read_b128 v[190:193], v177 offset:15232
	ds_read_b128 v[194:197], v177 offset:15248
	s_waitcnt lgkmcnt(2)
	v_perm_b32 v198, v183, v182, v180
	v_perm_b32 v199, v185, v184, v180
	v_perm_b32 v200, v187, v186, v180
	v_perm_b32 v201, v189, v188, v180
	v_perm_b32 v206, v183, v182, v181
	v_perm_b32 v207, v185, v184, v181
	v_perm_b32 v208, v187, v186, v181
	v_perm_b32 v209, v189, v188, v181
	global_store_dwordx4 v178, v[198:201], s[42:43]
	global_store_dwordx4 v179, v[206:209], s[42:43]
	s_add_u32 s42, s42, 0x54000
	s_addc_u32 s43, s43, 0
	s_nop 1
	s_waitcnt lgkmcnt(0)
	s_barrier
	v_perm_b32 v198, v191, v190, v180
	v_perm_b32 v199, v193, v192, v180
	v_perm_b32 v200, v195, v194, v180
	v_perm_b32 v201, v197, v196, v180
	v_perm_b32 v206, v191, v190, v181
	v_perm_b32 v207, v193, v192, v181
	v_perm_b32 v208, v195, v194, v181
	v_perm_b32 v209, v197, v196, v181
	global_store_dwordx4 v178, v[198:201], s[42:43]
	global_store_dwordx4 v179, v[206:209], s[42:43]
	s_branch .LBB0_126

.LBB0_707:
	v_add_u32_e32 v0, v206, v207
	s_movk_i32 s22, 0x1ff
	v_cmp_lt_i32_e32 vcc, s22, v0
	s_cbranch_vccnz .LBB0_706
	v_readfirstlane_b32 s22, v0
	s_ashr_i32 s23, s22, 31
	s_lshr_b32 s23, s23, 25
	s_add_i32 s23, s22, s23
	s_ashr_i32 s33, s23, 7
	s_lshl_b32 s41, s33, 3
	s_and_b32 s23, s23, 0xffffff80
	s_sub_i32 s40, 32, s41
	s_cmpk_gt_i32 s22, 0x1ff
	s_cselect_b32 s42, s40, 8
	s_abs_i32 s40, s42
	v_cvt_f32_u32_e32 v1, s40
	v_subrev_u32_e32 v0, s23, v0
	s_sub_i32 s23, 0, s40
	v_sub_u32_e32 v2, 0, v0
	v_rcp_iflag_f32_e32 v1, v1
	v_max_i32_e32 v2, v0, v2
	v_xor_b32_e32 v3, s42, v0
	v_ashrrev_i32_e32 v3, 31, v3
	v_mul_f32_e32 v1, 0x4f7ffffe, v1
	v_cvt_u32_f32_e32 v1, v1
	v_mov_b32_e32 v8, v204
	s_mulk_i32 s33, 0x78
	v_mul_lo_u32 v4, s23, v1
	v_mul_hi_u32 v4, v1, v4
	v_add_u32_e32 v1, v1, v4
	v_mul_hi_u32 v1, v2, v1
	v_mul_lo_u32 v4, v1, s40
	v_sub_u32_e32 v2, v2, v4
	v_add_u32_e32 v5, 1, v1
	v_subrev_u32_e32 v4, s40, v2
	v_cmp_le_u32_e32 vcc, s40, v2
	s_mov_b32 s22, 0
	s_nop 0
	v_cndmask_b32_e32 v1, v1, v5, vcc
	v_cndmask_b32_e32 v2, v2, v4, vcc
	v_add_u32_e32 v4, 1, v1
	v_cmp_le_u32_e32 vcc, s40, v2
	v_bfe_u32 v2, v8, 4, 2
	v_bitop3_b32 v2, v2, v8, 3 bitop3:0x78
	v_cndmask_b32_e32 v1, v1, v4, vcc
	v_xor_b32_e32 v1, v1, v3
	v_sub_u32_e32 v1, v1, v3
	v_ashrrev_i32_e32 v3, 6, v8
	v_readfirstlane_b32 s40, v1
	s_mul_i32 s23, s42, s40
	v_subrev_u32_e32 v0, s23, v0
	s_waitcnt vmcnt(1)
	v_add_u32_e32 v138, s41, v0
	s_ashr_i32 s41, s40, 31
	v_lshlrev_b32_e32 v132, 8, v138
	s_lshl_b64 s[42:43], s[40:41], 19
	v_bfe_u32 v4, v8, 2, 4
	s_mov_b32 s41, 0x1fffc0
	v_ashrrev_i32_e32 v133, 31, v132
	v_lshlrev_b32_e32 v9, 3, v2
	v_and_or_b32 v2, v8, s41, v4
	v_lshlrev_b32_e32 v5, 16, v3
	v_lshlrev_b32_e32 v10, 11, v4
	v_lshlrev_b64 v[130:131], 11, v[132:133]
	v_lshlrev_b64 v[0:1], 12, v[132:133]
	v_lshl_or_b32 v2, v2, 11, v9
	v_or3_b32 v4, v10, v5, v9
	v_lshl_add_u32 v133, v3, 12, 32
	v_lshlrev_b32_e32 v3, 11, v3
	v_lshl_add_u64 v[0:1], s[6:7], 0, v[0:1]
	s_add_u32 s90, s52, s42
	v_sub_u32_e32 v139, v133, v3
	v_ashrrev_i32_e32 v3, 31, v2
	v_ashrrev_i32_e32 v5, 31, v4
	v_readfirstlane_b32 s41, v133
	v_add_u32_e32 v12, 0x400, v133
	s_addc_u32 s91, s53, s43
	v_lshl_add_u64 v[0:1], v[2:3], 1, v[0:1]
	v_lshlrev_b64 v[2:3], 1, v[4:5]
	v_lshrrev_b32_e32 v241, 4, v10
	v_add_u32_e32 v2, v2, v241
	s_mov_b32 m0, s41
	v_readfirstlane_b32 s41, v12
	v_add_u32_e32 v12, 0x800, v133
	v_lshl_add_u64 v[4:5], s[90:91], 0, v[2:3]
	global_load_lds_dwordx4 v[0:1], off
	v_lshl_add_u64 v[6:7], v[0:1], 0, s[10:11]
	s_mov_b32 m0, s41
	s_mov_b64 s[90:91], 0x20000
	v_readfirstlane_b32 s41, v12
	v_add_u32_e32 v12, 0xc00, v133
	v_add_u32_e32 v11, 0x4000, v139
	global_load_lds_dwordx4 v[6:7], off
	v_lshl_add_u64 v[6:7], v[0:1], 0, s[90:91]
	s_mov_b32 m0, s41
	s_mov_b64 s[90:91], 0x30000
	v_readfirstlane_b32 s41, v12
	global_load_lds_dwordx4 v[6:7], off
	v_lshl_add_u64 v[6:7], v[0:1], 0, s[90:91]
	s_mov_b32 m0, s41
	v_readfirstlane_b32 s41, v11
	v_add_u32_e32 v11, 0x4400, v139
	global_load_lds_dwordx4 v[6:7], off
	s_mov_b32 m0, s41
	v_readfirstlane_b32 s41, v11
	v_add_u32_e32 v11, 0x6000, v133
	global_load_lds_dwordx4 v[4:5], off
	s_mov_b64 s[90:91], 0x10800
	v_lshl_add_u64 v[6:7], v[4:5], 0, s[90:91]
	s_mov_b32 m0, s41
	v_readfirstlane_b32 s41, v11
	v_add_u32_e32 v11, 0x6400, v133
	global_load_lds_dwordx4 v[6:7], off
	v_lshl_add_u64 v[6:7], v[0:1], 0, 64
	s_mov_b32 m0, s41
	v_readfirstlane_b32 s41, v11
	v_add_u32_e32 v11, 0x6800, v133
	global_load_lds_dwordx4 v[6:7], off
	v_lshl_add_u64 v[6:7], v[0:1], 0, s[12:13]
	s_mov_b32 m0, s41
	s_mov_b64 s[90:91], 0x20040
	v_readfirstlane_b32 s41, v11
	global_load_lds_dwordx4 v[6:7], off
	v_lshl_add_u64 v[6:7], v[0:1], 0, s[90:91]
	s_mov_b32 m0, s41
	s_mov_b64 s[90:91], 0x30040
	global_load_lds_dwordx4 v[6:7], off
	v_add_u32_e32 v6, 0x6c00, v133
	v_lshl_add_u64 v[0:1], v[0:1], 0, s[90:91]
	v_readfirstlane_b32 s41, v6
	v_add_u32_e32 v6, 0xa000, v139
	s_mov_b32 m0, s41
	v_readfirstlane_b32 s41, v6
	global_load_lds_dwordx4 v[0:1], off
	v_lshl_add_u64 v[0:1], v[4:5], 0, 64
	s_mov_b32 m0, s41
	s_add_u32 s42, s94, s42
	global_load_lds_dwordx4 v[0:1], off
	s_mov_b64 s[90:91], 0x10840
	v_lshl_add_u64 v[0:1], v[4:5], 0, s[90:91]
	v_add_u32_e32 v4, 0xa400, v139
	s_addc_u32 s43, s95, s43
	v_readfirstlane_b32 s41, v4
	s_mov_b32 m0, s41
	v_bfe_u32 v4, v8, 2, 2
	global_load_lds_dwordx4 v[0:1], off
	v_bfe_u32 v0, v8, 5, 1
	v_lshrrev_b32_e32 v1, 2, v8
	v_bitop3_b32 v1, v0, v1, 3 bitop3:0x78
	v_bitop3_b32 v0, v0, v4, 2 bitop3:0x36
	v_lshlrev_b32_e32 v128, 4, v0
	v_subrev_u32_e32 v0, s23, v208
	v_subrev_u32_e32 v0, s33, v0
	v_lshl_add_u64 v[134:135], s[42:43], 0, v[2:3]
	v_lshlrev_b32_e32 v0, 8, v0
	v_lshlrev_b32_e32 v2, 11, v8
	v_lshlrev_b32_e32 v140, 4, v1
	v_ashrrev_i32_e32 v1, 31, v0
	v_and_b32_e32 v2, 0xfffe0000, v2
	v_lshlrev_b64 v[0:1], 12, v[0:1]
	v_or3_b32 v2, v2, v10, v9
	v_ashrrev_i32_e32 v3, 31, v2
	v_lshl_add_u64 v[0:1], s[94:95], 0, v[0:1]
	v_lshlrev_b32_e32 v5, 6, v8
	v_lshl_add_u64 v[136:137], v[2:3], 1, v[0:1]
	v_mov_b32_e32 v0, 0
	v_and_b32_e32 v141, 0xffffe7c0, v5
	s_waitcnt vmcnt(0)
	v_and_b32_e32 v142, 0x17c0, v5
	s_mov_b64 s[42:43], 0
	v_mov_b32_e32 v1, v0
	v_mov_b32_e32 v2, v0
	v_mov_b32_e32 v3, v0
	v_mov_b32_e32 v4, v0
	v_mov_b32_e32 v5, v0
	v_mov_b32_e32 v6, v0
	v_mov_b32_e32 v7, v0
	v_mov_b32_e32 v8, v0
	v_mov_b32_e32 v9, v0
	v_mov_b32_e32 v10, v0
	v_mov_b32_e32 v11, v0
	v_mov_b32_e32 v12, v0
	v_mov_b32_e32 v13, v0
	v_mov_b32_e32 v14, v0
	v_mov_b32_e32 v15, v0
	v_mov_b32_e32 v16, v0
	v_mov_b32_e32 v17, v0
	v_mov_b32_e32 v18, v0
	v_mov_b32_e32 v19, v0
	v_mov_b32_e32 v20, v0
	v_mov_b32_e32 v21, v0
	v_mov_b32_e32 v22, v0
	v_mov_b32_e32 v23, v0
	v_mov_b32_e32 v24, v0
	v_mov_b32_e32 v25, v0
	v_mov_b32_e32 v26, v0
	v_mov_b32_e32 v27, v0
	v_mov_b32_e32 v28, v0
	v_mov_b32_e32 v29, v0
	v_mov_b32_e32 v30, v0
	v_mov_b32_e32 v31, v0
	v_mov_b32_e32 v32, v0
	v_mov_b32_e32 v33, v0
	v_mov_b32_e32 v34, v0
	v_mov_b32_e32 v35, v0
	v_mov_b32_e32 v36, v0
	v_mov_b32_e32 v37, v0
	v_mov_b32_e32 v38, v0
	v_mov_b32_e32 v39, v0
	v_mov_b32_e32 v40, v0
	v_mov_b32_e32 v41, v0
	v_mov_b32_e32 v42, v0
	v_mov_b32_e32 v43, v0
	v_mov_b32_e32 v44, v0
	v_mov_b32_e32 v45, v0
	v_mov_b32_e32 v46, v0
	v_mov_b32_e32 v47, v0
	v_mov_b32_e32 v48, v0
	v_mov_b32_e32 v49, v0
	v_mov_b32_e32 v50, v0
	v_mov_b32_e32 v51, v0
	v_mov_b32_e32 v52, v0
	v_mov_b32_e32 v53, v0
	v_mov_b32_e32 v54, v0
	v_mov_b32_e32 v55, v0
	v_mov_b32_e32 v56, v0
	v_mov_b32_e32 v57, v0
	v_mov_b32_e32 v58, v0
	v_mov_b32_e32 v59, v0
	v_mov_b32_e32 v60, v0
	v_mov_b32_e32 v61, v0
	v_mov_b32_e32 v62, v0
	v_mov_b32_e32 v63, v0
	v_mov_b32_e32 v64, v0
	v_mov_b32_e32 v65, v0
	v_mov_b32_e32 v66, v0
	v_mov_b32_e32 v67, v0
	v_mov_b32_e32 v68, v0
	v_mov_b32_e32 v69, v0
	v_mov_b32_e32 v70, v0
	v_mov_b32_e32 v71, v0
	v_mov_b32_e32 v72, v0
	v_mov_b32_e32 v73, v0
	v_mov_b32_e32 v74, v0
	v_mov_b32_e32 v75, v0
	v_mov_b32_e32 v76, v0
	v_mov_b32_e32 v77, v0
	v_mov_b32_e32 v78, v0
	v_mov_b32_e32 v79, v0
	v_mov_b32_e32 v80, v0
	v_mov_b32_e32 v81, v0
	v_mov_b32_e32 v82, v0
	v_mov_b32_e32 v83, v0
	v_mov_b32_e32 v84, v0
	v_mov_b32_e32 v85, v0
	v_mov_b32_e32 v86, v0
	v_mov_b32_e32 v87, v0
	v_mov_b32_e32 v88, v0
	v_mov_b32_e32 v89, v0
	v_mov_b32_e32 v90, v0
	v_mov_b32_e32 v91, v0
	v_mov_b32_e32 v92, v0
	v_mov_b32_e32 v93, v0
	v_mov_b32_e32 v94, v0
	v_mov_b32_e32 v95, v0
	v_mov_b32_e32 v96, v0
	v_mov_b32_e32 v97, v0
	v_mov_b32_e32 v98, v0
	v_mov_b32_e32 v99, v0
	v_mov_b32_e32 v100, v0
	v_mov_b32_e32 v101, v0
	v_mov_b32_e32 v102, v0
	v_mov_b32_e32 v103, v0
	v_mov_b32_e32 v104, v0
	v_mov_b32_e32 v105, v0
	v_mov_b32_e32 v106, v0
	v_mov_b32_e32 v107, v0
	v_mov_b32_e32 v108, v0
	v_mov_b32_e32 v109, v0
	v_mov_b32_e32 v110, v0
	v_mov_b32_e32 v111, v0
	v_mov_b32_e32 v112, v0
	v_mov_b32_e32 v113, v0
	v_mov_b32_e32 v114, v0
	v_mov_b32_e32 v115, v0
	v_mov_b32_e32 v116, v0
	v_mov_b32_e32 v117, v0
	v_mov_b32_e32 v118, v0
	v_mov_b32_e32 v119, v0
	v_mov_b32_e32 v120, v0
	v_mov_b32_e32 v121, v0
	v_mov_b32_e32 v122, v0
	v_mov_b32_e32 v123, v0
	v_mov_b32_e32 v124, v0
	v_mov_b32_e32 v125, v0
	v_mov_b32_e32 v126, v0
	v_mov_b32_e32 v127, v0
	v_add3_u32 v192, v141, v140, 32
	v_add3_u32 v193, v141, v128, 32
	v_add_u32_e32 v194, 0x4020, v142
	v_add_u32_e32 v195, v194, v128
	v_add_u32_e32 v194, v194, v140
	v_subrev_u32_e32 v196, s94, v136
	v_subrev_u32_e32 v200, s94, v134
	v_add_u32_e32 v196, 0x15c88080, v196
	v_sub_u32_e32 v200, v200, v241
	s_nop 0
	v_add_u32_e32 v200, 0x18a88000, v200
	v_add_u32_e32 v197, 0x10000, v196
	v_add_u32_e32 v198, 0x20000, v196
	v_add_u32_e32 v199, 0x30000, v196
	v_add_u32_e32 v201, 0x10000, v200
	v_readfirstlane_b32 s22, v133
	v_readfirstlane_b32 s23, v139
	s_mov_b64 s[98:99], s[94:95]
	s_add_u32 s100, s94, 64
	s_addc_u32 s101, s95, 0
	s_nop 0
	s_add_u32 s23, s23, 0x4000
	v_or_b32_e32 v245, 0x800, v241
	s_movk_i32 s32, 0x80
	s_waitcnt vmcnt(6)
	s_barrier
	s_nop 0
	ds_read_b128 v[144:147], v194 offset:0
	ds_read_b128 v[148:151], v194 offset:2048
	ds_read_b128 v[152:155], v192 offset:0
	ds_read_b128 v[156:159], v192 offset:2048
	ds_read_b128 v[160:163], v192 offset:4096
	ds_read_b128 v[164:167], v192 offset:6144
	s_waitcnt lgkmcnt(2)
	s_setprio 1
	v_mfma_f32_32x32x16_bf16 v[112:127], v[152:155], v[144:147], v[112:127]
	v_mfma_f32_32x32x16_bf16 v[96:111], v[152:155], v[148:151], v[96:111]
	v_mfma_f32_32x32x16_bf16 v[80:95], v[156:159], v[144:147], v[80:95]
	v_mfma_f32_32x32x16_bf16 v[64:79], v[156:159], v[148:151], v[64:79]
	s_setprio 0
	s_nop 0
	ds_read_b128 v[168:171], v195 offset:0
	ds_read_b128 v[172:175], v195 offset:2048
	ds_read_b128 v[176:179], v193 offset:0
	ds_read_b128 v[180:183], v193 offset:2048
	s_waitcnt lgkmcnt(4)
	s_setprio 1
	v_mfma_f32_32x32x16_bf16 v[48:63], v[160:163], v[144:147], v[48:63]
	v_mfma_f32_32x32x16_bf16 v[32:47], v[160:163], v[148:151], v[32:47]
	v_mfma_f32_32x32x16_bf16 v[16:31], v[164:167], v[144:147], v[16:31]
	v_mfma_f32_32x32x16_bf16 v[0:15], v[164:167], v[148:151], v[0:15]
	s_setprio 0
	s_nop 0
	ds_read_b128 v[184:187], v193 offset:4096
	ds_read_b128 v[188:191], v193 offset:6144
	s_waitcnt lgkmcnt(2)
	s_setprio 1
	v_mfma_f32_32x32x16_bf16 v[112:127], v[176:179], v[168:171], v[112:127]
	v_mfma_f32_32x32x16_bf16 v[96:111], v[176:179], v[172:175], v[96:111]
	v_mfma_f32_32x32x16_bf16 v[80:95], v[180:183], v[168:171], v[80:95]
	v_mfma_f32_32x32x16_bf16 v[64:79], v[180:183], v[172:175], v[64:79]
	s_setprio 0
	s_mov_b32 s33, 10
.Lp5m_kloop:
	s_waitcnt vmcnt(0) lgkmcnt(0)
	s_barrier
	ds_read_b128 v[144:147], v194 offset:24576
	ds_read_b128 v[148:151], v194 offset:26624
	ds_read_b128 v[152:155], v192 offset:24576
	ds_read_b128 v[156:159], v192 offset:26624
	ds_read_b128 v[160:163], v192 offset:28672
	ds_read_b128 v[164:167], v192 offset:30720
	s_setprio 1
	s_nop 0
	v_mfma_f32_32x32x16_bf16 v[48:63], v[184:187], v[168:171], v[48:63]
	v_mfma_f32_32x32x16_bf16 v[32:47], v[184:187], v[172:175], v[32:47]
	v_mfma_f32_32x32x16_bf16 v[16:31], v[188:191], v[168:171], v[16:31]
	v_mfma_f32_32x32x16_bf16 v[0:15], v[188:191], v[172:175], v[0:15]
	s_setprio 0
	s_nop 0
	s_add_u32 m0, s22, 0xc000
	s_nop 0
	s_nop 0
	global_load_lds_dwordx4 v196, s[98:99]
	s_add_u32 m0, s22, 0x0
	s_nop 0
	global_load_lds_dwordx4 v196, s[100:101]
	s_add_u32 m0, s22, 0xc400
	s_nop 0
	s_nop 0
	global_load_lds_dwordx4 v197, s[98:99]
	s_add_u32 m0, s22, 0x400
	s_nop 0
	s_nop 0
	global_load_lds_dwordx4 v197, s[100:101]
	s_waitcnt lgkmcnt(2)
	s_setprio 1
	v_mfma_f32_32x32x16_bf16 v[112:127], v[152:155], v[144:147], v[112:127]
	v_mfma_f32_32x32x16_bf16 v[96:111], v[152:155], v[148:151], v[96:111]
	v_mfma_f32_32x32x16_bf16 v[80:95], v[156:159], v[144:147], v[80:95]
	v_mfma_f32_32x32x16_bf16 v[64:79], v[156:159], v[148:151], v[64:79]
	s_setprio 0
	s_nop 0
	ds_read_b128 v[168:171], v195 offset:24576
	ds_read_b128 v[172:175], v195 offset:26624
	ds_read_b128 v[176:179], v193 offset:24576
	ds_read_b128 v[180:183], v193 offset:26624
	s_add_u32 m0, s22, 0xc800
	s_nop 0
	s_nop 0
	global_load_lds_dwordx4 v198, s[98:99]
	s_add_u32 m0, s22, 0x800
	s_nop 0
	s_nop 0
	global_load_lds_dwordx4 v198, s[100:101]
	s_add_u32 m0, s22, 0xcc00
	s_nop 0
	s_nop 0
	global_load_lds_dwordx4 v199, s[98:99]
	s_add_u32 m0, s22, 0xc00
	s_nop 0
	s_nop 0
	global_load_lds_dwordx4 v199, s[100:101]
	s_waitcnt lgkmcnt(4)
	s_setprio 1
	v_mfma_f32_32x32x16_bf16 v[48:63], v[160:163], v[144:147], v[48:63]
	v_mfma_f32_32x32x16_bf16 v[32:47], v[160:163], v[148:151], v[32:47]
	v_mfma_f32_32x32x16_bf16 v[16:31], v[164:167], v[144:147], v[16:31]
	v_mfma_f32_32x32x16_bf16 v[0:15], v[164:167], v[148:151], v[0:15]
	s_setprio 0
	s_nop 0
	ds_read_b128 v[184:187], v193 offset:28672
	ds_read_b128 v[188:191], v193 offset:30720
	v_xad_u32 v246, s32, v241, v200
	v_xad_u32 v247, s32, v245, v201
	s_add_u32 m0, s23, 0xc000
	s_nop 0
	s_nop 0
	global_load_lds_dwordx4 v246, s[94:95]
	s_add_u32 m0, s23, 0xffffffc0
	s_nop 0
	s_nop 0
	global_load_lds_dwordx4 v246, s[94:95] offset:64
	s_add_u32 m0, s23, 0xc400
	s_nop 0
	s_nop 0
	global_load_lds_dwordx4 v247, s[94:95]
	s_add_u32 m0, s23, 0x3c0
	s_nop 0
	s_nop 0
	global_load_lds_dwordx4 v247, s[94:95] offset:64
	s_add_u32 s32, s32, 0x80
	s_add_u32 s98, s98, 128
	s_addc_u32 s99, s99, 0
	s_nop 0
	s_add_u32 s100, s100, 128
	s_addc_u32 s101, s101, 0
	s_waitcnt lgkmcnt(2)
	s_setprio 1
	s_nop 0
	v_mfma_f32_32x32x16_bf16 v[112:127], v[176:179], v[168:171], v[112:127]
	v_mfma_f32_32x32x16_bf16 v[96:111], v[176:179], v[172:175], v[96:111]
	v_mfma_f32_32x32x16_bf16 v[80:95], v[180:183], v[168:171], v[80:95]
	v_mfma_f32_32x32x16_bf16 v[64:79], v[180:183], v[172:175], v[64:79]
	s_setprio 0
	s_waitcnt vmcnt(0) lgkmcnt(0)
	s_barrier
	s_nop 0
	ds_read_b128 v[144:147], v194 offset:49152
	ds_read_b128 v[148:151], v194 offset:51200
	ds_read_b128 v[152:155], v192 offset:49152
	ds_read_b128 v[156:159], v192 offset:51200
	ds_read_b128 v[160:163], v192 offset:53248
	ds_read_b128 v[164:167], v192 offset:55296
	s_setprio 1
	s_nop 0
	v_mfma_f32_32x32x16_bf16 v[48:63], v[184:187], v[168:171], v[48:63]
	v_mfma_f32_32x32x16_bf16 v[32:47], v[184:187], v[172:175], v[32:47]
	v_mfma_f32_32x32x16_bf16 v[16:31], v[188:191], v[168:171], v[16:31]
	v_mfma_f32_32x32x16_bf16 v[0:15], v[188:191], v[172:175], v[0:15]
	s_setprio 0
	s_waitcnt lgkmcnt(2)
	s_setprio 1
	s_nop 0
	v_mfma_f32_32x32x16_bf16 v[112:127], v[152:155], v[144:147], v[112:127]
	v_mfma_f32_32x32x16_bf16 v[96:111], v[152:155], v[148:151], v[96:111]
	v_mfma_f32_32x32x16_bf16 v[80:95], v[156:159], v[144:147], v[80:95]
	v_mfma_f32_32x32x16_bf16 v[64:79], v[156:159], v[148:151], v[64:79]
	s_setprio 0
	s_nop 0
	ds_read_b128 v[168:171], v195 offset:49152
	ds_read_b128 v[172:175], v195 offset:51200
	ds_read_b128 v[176:179], v193 offset:49152
	ds_read_b128 v[180:183], v193 offset:51200
	s_waitcnt lgkmcnt(4)
	s_setprio 1
	v_mfma_f32_32x32x16_bf16 v[48:63], v[160:163], v[144:147], v[48:63]
	v_mfma_f32_32x32x16_bf16 v[32:47], v[160:163], v[148:151], v[32:47]
	v_mfma_f32_32x32x16_bf16 v[16:31], v[164:167], v[144:147], v[16:31]
	v_mfma_f32_32x32x16_bf16 v[0:15], v[164:167], v[148:151], v[0:15]
	s_setprio 0
	s_nop 0
	ds_read_b128 v[184:187], v193 offset:53248
	ds_read_b128 v[188:191], v193 offset:55296
	s_waitcnt lgkmcnt(2)
	s_setprio 1
	v_mfma_f32_32x32x16_bf16 v[112:127], v[176:179], v[168:171], v[112:127]
	v_mfma_f32_32x32x16_bf16 v[96:111], v[176:179], v[172:175], v[96:111]
	v_mfma_f32_32x32x16_bf16 v[80:95], v[180:183], v[168:171], v[80:95]
	v_mfma_f32_32x32x16_bf16 v[64:79], v[180:183], v[172:175], v[64:79]
	s_setprio 0
	s_waitcnt vmcnt(0) lgkmcnt(0)
	s_barrier
	s_nop 0
	ds_read_b128 v[144:147], v194 offset:0
	ds_read_b128 v[148:151], v194 offset:2048
	ds_read_b128 v[152:155], v192 offset:0
	ds_read_b128 v[156:159], v192 offset:2048
	ds_read_b128 v[160:163], v192 offset:4096
	ds_read_b128 v[164:167], v192 offset:6144
	s_setprio 1
	s_nop 0
	v_mfma_f32_32x32x16_bf16 v[48:63], v[184:187], v[168:171], v[48:63]
	v_mfma_f32_32x32x16_bf16 v[32:47], v[184:187], v[172:175], v[32:47]
	v_mfma_f32_32x32x16_bf16 v[16:31], v[188:191], v[168:171], v[16:31]
	v_mfma_f32_32x32x16_bf16 v[0:15], v[188:191], v[172:175], v[0:15]
	s_setprio 0
	s_nop 0
	s_add_u32 m0, s22, 0x6000
	s_nop 0
	s_nop 0
	global_load_lds_dwordx4 v196, s[98:99]
	s_add_u32 m0, s22, 0xc000
	s_nop 0
	s_nop 0
	global_load_lds_dwordx4 v196, s[100:101]
	s_add_u32 m0, s22, 0x6400
	s_nop 0
	s_nop 0
	global_load_lds_dwordx4 v197, s[98:99]
	s_add_u32 m0, s22, 0xc400
	s_nop 0
	s_nop 0
	global_load_lds_dwordx4 v197, s[100:101]
	s_waitcnt lgkmcnt(2)
	s_setprio 1
	v_mfma_f32_32x32x16_bf16 v[112:127], v[152:155], v[144:147], v[112:127]
	v_mfma_f32_32x32x16_bf16 v[96:111], v[152:155], v[148:151], v[96:111]
	v_mfma_f32_32x32x16_bf16 v[80:95], v[156:159], v[144:147], v[80:95]
	v_mfma_f32_32x32x16_bf16 v[64:79], v[156:159], v[148:151], v[64:79]
	s_setprio 0
	s_nop 0
	ds_read_b128 v[168:171], v195 offset:0
	ds_read_b128 v[172:175], v195 offset:2048
	ds_read_b128 v[176:179], v193 offset:0
	ds_read_b128 v[180:183], v193 offset:2048
	s_add_u32 m0, s22, 0x6800
	s_nop 0
	s_nop 0
	global_load_lds_dwordx4 v198, s[98:99]
	s_add_u32 m0, s22, 0xc800
	s_nop 0
	s_nop 0
	global_load_lds_dwordx4 v198, s[100:101]
	s_add_u32 m0, s22, 0x6c00
	s_nop 0
	s_nop 0
	global_load_lds_dwordx4 v199, s[98:99]
	s_add_u32 m0, s22, 0xcc00
	s_nop 0
	s_nop 0
	global_load_lds_dwordx4 v199, s[100:101]
	s_waitcnt lgkmcnt(4)
	s_setprio 1
	v_mfma_f32_32x32x16_bf16 v[48:63], v[160:163], v[144:147], v[48:63]
	v_mfma_f32_32x32x16_bf16 v[32:47], v[160:163], v[148:151], v[32:47]
	v_mfma_f32_32x32x16_bf16 v[16:31], v[164:167], v[144:147], v[16:31]
	v_mfma_f32_32x32x16_bf16 v[0:15], v[164:167], v[148:151], v[0:15]
	s_setprio 0
	s_nop 0
	ds_read_b128 v[184:187], v193 offset:4096
	ds_read_b128 v[188:191], v193 offset:6144
	v_xad_u32 v246, s32, v241, v200
	v_xad_u32 v247, s32, v245, v201
	s_add_u32 m0, s23, 0x6000
	s_nop 0
	s_nop 0
	global_load_lds_dwordx4 v246, s[94:95]
	s_add_u32 m0, s23, 0xbfc0
	s_nop 0
	s_nop 0
	global_load_lds_dwordx4 v246, s[94:95] offset:64
	s_add_u32 m0, s23, 0x6400
	s_nop 0
	s_nop 0
	global_load_lds_dwordx4 v247, s[94:95]
	s_add_u32 m0, s23, 0xc3c0
	s_nop 0
	s_nop 0
	global_load_lds_dwordx4 v247, s[94:95] offset:64
	s_add_u32 s32, s32, 0x80
	s_add_u32 s98, s98, 128
	s_addc_u32 s99, s99, 0
	s_nop 0
	s_add_u32 s100, s100, 128
	s_addc_u32 s101, s101, 0
	s_waitcnt lgkmcnt(2)
	s_setprio 1
	s_nop 0
	v_mfma_f32_32x32x16_bf16 v[112:127], v[176:179], v[168:171], v[112:127]
	v_mfma_f32_32x32x16_bf16 v[96:111], v[176:179], v[172:175], v[96:111]
	v_mfma_f32_32x32x16_bf16 v[80:95], v[180:183], v[168:171], v[80:95]
	v_mfma_f32_32x32x16_bf16 v[64:79], v[180:183], v[172:175], v[64:79]
	s_setprio 0
	s_waitcnt vmcnt(0) lgkmcnt(0)
	s_barrier
	s_nop 0
	ds_read_b128 v[144:147], v194 offset:24576
	ds_read_b128 v[148:151], v194 offset:26624
	ds_read_b128 v[152:155], v192 offset:24576
	ds_read_b128 v[156:159], v192 offset:26624
	ds_read_b128 v[160:163], v192 offset:28672
	ds_read_b128 v[164:167], v192 offset:30720
	s_setprio 1
	s_nop 0
	v_mfma_f32_32x32x16_bf16 v[48:63], v[184:187], v[168:171], v[48:63]
	v_mfma_f32_32x32x16_bf16 v[32:47], v[184:187], v[172:175], v[32:47]
	v_mfma_f32_32x32x16_bf16 v[16:31], v[188:191], v[168:171], v[16:31]
	v_mfma_f32_32x32x16_bf16 v[0:15], v[188:191], v[172:175], v[0:15]
	s_setprio 0
	s_waitcnt lgkmcnt(2)
	s_setprio 1
	s_nop 0
	v_mfma_f32_32x32x16_bf16 v[112:127], v[152:155], v[144:147], v[112:127]
	v_mfma_f32_32x32x16_bf16 v[96:111], v[152:155], v[148:151], v[96:111]
	v_mfma_f32_32x32x16_bf16 v[80:95], v[156:159], v[144:147], v[80:95]
	v_mfma_f32_32x32x16_bf16 v[64:79], v[156:159], v[148:151], v[64:79]
	s_setprio 0
	s_nop 0
	ds_read_b128 v[168:171], v195 offset:24576
	ds_read_b128 v[172:175], v195 offset:26624
	ds_read_b128 v[176:179], v193 offset:24576
	ds_read_b128 v[180:183], v193 offset:26624
	s_waitcnt lgkmcnt(4)
	s_setprio 1
	v_mfma_f32_32x32x16_bf16 v[48:63], v[160:163], v[144:147], v[48:63]
	v_mfma_f32_32x32x16_bf16 v[32:47], v[160:163], v[148:151], v[32:47]
	v_mfma_f32_32x32x16_bf16 v[16:31], v[164:167], v[144:147], v[16:31]
	v_mfma_f32_32x32x16_bf16 v[0:15], v[164:167], v[148:151], v[0:15]
	s_setprio 0
	s_nop 0
	ds_read_b128 v[184:187], v193 offset:28672
	ds_read_b128 v[188:191], v193 offset:30720
	s_waitcnt lgkmcnt(2)
	s_setprio 1
	v_mfma_f32_32x32x16_bf16 v[112:127], v[176:179], v[168:171], v[112:127]
	v_mfma_f32_32x32x16_bf16 v[96:111], v[176:179], v[172:175], v[96:111]
	v_mfma_f32_32x32x16_bf16 v[80:95], v[180:183], v[168:171], v[80:95]
	v_mfma_f32_32x32x16_bf16 v[64:79], v[180:183], v[172:175], v[64:79]
	s_setprio 0
	s_waitcnt vmcnt(0) lgkmcnt(0)
	s_barrier
	s_nop 0
	ds_read_b128 v[144:147], v194 offset:49152
	ds_read_b128 v[148:151], v194 offset:51200
	ds_read_b128 v[152:155], v192 offset:49152
	ds_read_b128 v[156:159], v192 offset:51200
	ds_read_b128 v[160:163], v192 offset:53248
	ds_read_b128 v[164:167], v192 offset:55296
	s_setprio 1
	s_nop 0
	v_mfma_f32_32x32x16_bf16 v[48:63], v[184:187], v[168:171], v[48:63]
	v_mfma_f32_32x32x16_bf16 v[32:47], v[184:187], v[172:175], v[32:47]
	v_mfma_f32_32x32x16_bf16 v[16:31], v[188:191], v[168:171], v[16:31]
	v_mfma_f32_32x32x16_bf16 v[0:15], v[188:191], v[172:175], v[0:15]
	s_setprio 0
	s_add_u32 m0, s22, 0x0
	s_nop 0
	s_nop 0
	global_load_lds_dwordx4 v196, s[98:99]
	s_add_u32 m0, s22, 0x6000
	s_nop 0
	s_nop 0
	global_load_lds_dwordx4 v196, s[100:101]
	s_add_u32 m0, s22, 0x400
	s_nop 0
	s_nop 0
	global_load_lds_dwordx4 v197, s[98:99]
	s_add_u32 m0, s22, 0x6400
	s_nop 0
	s_nop 0
	global_load_lds_dwordx4 v197, s[100:101]
	s_waitcnt lgkmcnt(2)
	s_setprio 1
	v_mfma_f32_32x32x16_bf16 v[112:127], v[152:155], v[144:147], v[112:127]
	v_mfma_f32_32x32x16_bf16 v[96:111], v[152:155], v[148:151], v[96:111]
	v_mfma_f32_32x32x16_bf16 v[80:95], v[156:159], v[144:147], v[80:95]
	v_mfma_f32_32x32x16_bf16 v[64:79], v[156:159], v[148:151], v[64:79]
	s_setprio 0
	s_nop 0
	ds_read_b128 v[168:171], v195 offset:49152
	ds_read_b128 v[172:175], v195 offset:51200
	ds_read_b128 v[176:179], v193 offset:49152
	ds_read_b128 v[180:183], v193 offset:51200
	s_add_u32 m0, s22, 0x800
	s_nop 0
	s_nop 0
	global_load_lds_dwordx4 v198, s[98:99]
	s_add_u32 m0, s22, 0x6800
	s_nop 0
	s_nop 0
	global_load_lds_dwordx4 v198, s[100:101]
	s_add_u32 m0, s22, 0xc00
	s_nop 0
	s_nop 0
	global_load_lds_dwordx4 v199, s[98:99]
	s_add_u32 m0, s22, 0x6c00
	s_nop 0
	s_nop 0
	global_load_lds_dwordx4 v199, s[100:101]
	s_waitcnt lgkmcnt(4)
	s_setprio 1
	v_mfma_f32_32x32x16_bf16 v[48:63], v[160:163], v[144:147], v[48:63]
	v_mfma_f32_32x32x16_bf16 v[32:47], v[160:163], v[148:151], v[32:47]
	v_mfma_f32_32x32x16_bf16 v[16:31], v[164:167], v[144:147], v[16:31]
	v_mfma_f32_32x32x16_bf16 v[0:15], v[164:167], v[148:151], v[0:15]
	s_setprio 0
	s_nop 0
	ds_read_b128 v[184:187], v193 offset:53248
	ds_read_b128 v[188:191], v193 offset:55296
	v_xad_u32 v246, s32, v241, v200
	v_xad_u32 v247, s32, v245, v201
	s_add_u32 m0, s23, 0x0
	s_nop 0
	global_load_lds_dwordx4 v246, s[94:95]
	s_add_u32 m0, s23, 0x5fc0
	s_nop 0
	s_nop 0
	global_load_lds_dwordx4 v246, s[94:95] offset:64
	s_add_u32 m0, s23, 0x400
	s_nop 0
	s_nop 0
	global_load_lds_dwordx4 v247, s[94:95]
	s_add_u32 m0, s23, 0x63c0
	s_nop 0
	s_nop 0
	global_load_lds_dwordx4 v247, s[94:95] offset:64
	s_add_u32 s32, s32, 0x80
	s_add_u32 s98, s98, 128
	s_addc_u32 s99, s99, 0
	s_nop 0
	s_add_u32 s100, s100, 128
	s_addc_u32 s101, s101, 0
	s_waitcnt lgkmcnt(2)
	s_setprio 1
	s_nop 0
	v_mfma_f32_32x32x16_bf16 v[112:127], v[176:179], v[168:171], v[112:127]
	v_mfma_f32_32x32x16_bf16 v[96:111], v[176:179], v[172:175], v[96:111]
	v_mfma_f32_32x32x16_bf16 v[80:95], v[180:183], v[168:171], v[80:95]
	v_mfma_f32_32x32x16_bf16 v[64:79], v[180:183], v[172:175], v[64:79]
	s_setprio 0
	s_waitcnt vmcnt(0) lgkmcnt(0)
	s_barrier
	s_nop 0
	ds_read_b128 v[144:147], v194 offset:0
	ds_read_b128 v[148:151], v194 offset:2048
	ds_read_b128 v[152:155], v192 offset:0
	ds_read_b128 v[156:159], v192 offset:2048
	ds_read_b128 v[160:163], v192 offset:4096
	ds_read_b128 v[164:167], v192 offset:6144
	s_setprio 1
	s_nop 0
	v_mfma_f32_32x32x16_bf16 v[48:63], v[184:187], v[168:171], v[48:63]
	v_mfma_f32_32x32x16_bf16 v[32:47], v[184:187], v[172:175], v[32:47]
	v_mfma_f32_32x32x16_bf16 v[16:31], v[188:191], v[168:171], v[16:31]
	v_mfma_f32_32x32x16_bf16 v[0:15], v[188:191], v[172:175], v[0:15]
	s_setprio 0
	s_waitcnt lgkmcnt(2)
	s_setprio 1
	s_nop 0
	v_mfma_f32_32x32x16_bf16 v[112:127], v[152:155], v[144:147], v[112:127]
	v_mfma_f32_32x32x16_bf16 v[96:111], v[152:155], v[148:151], v[96:111]
	v_mfma_f32_32x32x16_bf16 v[80:95], v[156:159], v[144:147], v[80:95]
	v_mfma_f32_32x32x16_bf16 v[64:79], v[156:159], v[148:151], v[64:79]
	s_setprio 0
	s_nop 0
	ds_read_b128 v[168:171], v195 offset:0
	ds_read_b128 v[172:175], v195 offset:2048
	ds_read_b128 v[176:179], v193 offset:0
	ds_read_b128 v[180:183], v193 offset:2048
	s_waitcnt lgkmcnt(4)
	s_setprio 1
	v_mfma_f32_32x32x16_bf16 v[48:63], v[160:163], v[144:147], v[48:63]
	v_mfma_f32_32x32x16_bf16 v[32:47], v[160:163], v[148:151], v[32:47]
	v_mfma_f32_32x32x16_bf16 v[16:31], v[164:167], v[144:147], v[16:31]
	v_mfma_f32_32x32x16_bf16 v[0:15], v[164:167], v[148:151], v[0:15]
	s_setprio 0
	s_nop 0
	ds_read_b128 v[184:187], v193 offset:4096
	ds_read_b128 v[188:191], v193 offset:6144
	s_waitcnt lgkmcnt(2)
	s_setprio 1
	v_mfma_f32_32x32x16_bf16 v[112:127], v[176:179], v[168:171], v[112:127]
	v_mfma_f32_32x32x16_bf16 v[96:111], v[176:179], v[172:175], v[96:111]
	v_mfma_f32_32x32x16_bf16 v[80:95], v[180:183], v[168:171], v[80:95]
	v_mfma_f32_32x32x16_bf16 v[64:79], v[180:183], v[172:175], v[64:79]
	s_setprio 0
	s_sub_u32 s33, s33, 1
	s_cmp_lg_u32 s33, 0
	s_cbranch_scc1 .Lp5m_kloop
	s_waitcnt vmcnt(0) lgkmcnt(0)
	s_barrier
	ds_read_b128 v[144:147], v194 offset:24576
	ds_read_b128 v[148:151], v194 offset:26624
	ds_read_b128 v[152:155], v192 offset:24576
	ds_read_b128 v[156:159], v192 offset:26624
	ds_read_b128 v[160:163], v192 offset:28672
	ds_read_b128 v[164:167], v192 offset:30720
	s_setprio 1
	s_nop 0
	v_mfma_f32_32x32x16_bf16 v[48:63], v[184:187], v[168:171], v[48:63]
	v_mfma_f32_32x32x16_bf16 v[32:47], v[184:187], v[172:175], v[32:47]
	v_mfma_f32_32x32x16_bf16 v[16:31], v[188:191], v[168:171], v[16:31]
	v_mfma_f32_32x32x16_bf16 v[0:15], v[188:191], v[172:175], v[0:15]
	s_setprio 0
	s_nop 0
	s_add_u32 m0, s22, 0xc000
	s_nop 0
	s_nop 0
	global_load_lds_dwordx4 v196, s[98:99]
	s_add_u32 m0, s22, 0x0
	s_nop 0
	global_load_lds_dwordx4 v196, s[100:101]
	s_add_u32 m0, s22, 0xc400
	s_nop 0
	s_nop 0
	global_load_lds_dwordx4 v197, s[98:99]
	s_add_u32 m0, s22, 0x400
	s_nop 0
	s_nop 0
	global_load_lds_dwordx4 v197, s[100:101]
	s_waitcnt lgkmcnt(2)
	s_setprio 1
	v_mfma_f32_32x32x16_bf16 v[112:127], v[152:155], v[144:147], v[112:127]
	v_mfma_f32_32x32x16_bf16 v[96:111], v[152:155], v[148:151], v[96:111]
	v_mfma_f32_32x32x16_bf16 v[80:95], v[156:159], v[144:147], v[80:95]
	v_mfma_f32_32x32x16_bf16 v[64:79], v[156:159], v[148:151], v[64:79]
	s_setprio 0
	s_nop 0
	ds_read_b128 v[168:171], v195 offset:24576
	ds_read_b128 v[172:175], v195 offset:26624
	ds_read_b128 v[176:179], v193 offset:24576
	ds_read_b128 v[180:183], v193 offset:26624
	s_add_u32 m0, s22, 0xc800
	s_nop 0
	s_nop 0
	global_load_lds_dwordx4 v198, s[98:99]
	s_add_u32 m0, s22, 0x800
	s_nop 0
	s_nop 0
	global_load_lds_dwordx4 v198, s[100:101]
	s_add_u32 m0, s22, 0xcc00
	s_nop 0
	s_nop 0
	global_load_lds_dwordx4 v199, s[98:99]
	s_add_u32 m0, s22, 0xc00
	s_nop 0
	s_nop 0
	global_load_lds_dwordx4 v199, s[100:101]
	s_waitcnt lgkmcnt(4)
	s_setprio 1
	v_mfma_f32_32x32x16_bf16 v[48:63], v[160:163], v[144:147], v[48:63]
	v_mfma_f32_32x32x16_bf16 v[32:47], v[160:163], v[148:151], v[32:47]
	v_mfma_f32_32x32x16_bf16 v[16:31], v[164:167], v[144:147], v[16:31]
	v_mfma_f32_32x32x16_bf16 v[0:15], v[164:167], v[148:151], v[0:15]
	s_setprio 0
	s_nop 0
	ds_read_b128 v[184:187], v193 offset:28672
	ds_read_b128 v[188:191], v193 offset:30720
	v_xad_u32 v246, s32, v241, v200
	v_xad_u32 v247, s32, v245, v201
	s_add_u32 m0, s23, 0xc000
	s_nop 0
	s_nop 0
	global_load_lds_dwordx4 v246, s[94:95]
	s_add_u32 m0, s23, 0xffffffc0
	s_nop 0
	s_nop 0
	global_load_lds_dwordx4 v246, s[94:95] offset:64
	s_add_u32 m0, s23, 0xc400
	s_nop 0
	s_nop 0
	global_load_lds_dwordx4 v247, s[94:95]
	s_add_u32 m0, s23, 0x3c0
	s_nop 0
	s_nop 0
	global_load_lds_dwordx4 v247, s[94:95] offset:64
	s_add_u32 s32, s32, 0x80
	s_add_u32 s98, s98, 128
	s_addc_u32 s99, s99, 0
	s_nop 0
	s_add_u32 s100, s100, 128
	s_addc_u32 s101, s101, 0
	s_waitcnt lgkmcnt(2)
	s_setprio 1
	s_nop 0
	v_mfma_f32_32x32x16_bf16 v[112:127], v[176:179], v[168:171], v[112:127]
	v_mfma_f32_32x32x16_bf16 v[96:111], v[176:179], v[172:175], v[96:111]
	v_mfma_f32_32x32x16_bf16 v[80:95], v[180:183], v[168:171], v[80:95]
	v_mfma_f32_32x32x16_bf16 v[64:79], v[180:183], v[172:175], v[64:79]
	s_setprio 0
	s_waitcnt vmcnt(0) lgkmcnt(0)
	s_barrier
	s_nop 0
	ds_read_b128 v[144:147], v194 offset:49152
	ds_read_b128 v[148:151], v194 offset:51200
	ds_read_b128 v[152:155], v192 offset:49152
	ds_read_b128 v[156:159], v192 offset:51200
	ds_read_b128 v[160:163], v192 offset:53248
	ds_read_b128 v[164:167], v192 offset:55296
	s_setprio 1
	s_nop 0
	v_mfma_f32_32x32x16_bf16 v[48:63], v[184:187], v[168:171], v[48:63]
	v_mfma_f32_32x32x16_bf16 v[32:47], v[184:187], v[172:175], v[32:47]
	v_mfma_f32_32x32x16_bf16 v[16:31], v[188:191], v[168:171], v[16:31]
	v_mfma_f32_32x32x16_bf16 v[0:15], v[188:191], v[172:175], v[0:15]
	s_setprio 0
	s_waitcnt lgkmcnt(2)
	s_setprio 1
	s_nop 0
	v_mfma_f32_32x32x16_bf16 v[112:127], v[152:155], v[144:147], v[112:127]
	v_mfma_f32_32x32x16_bf16 v[96:111], v[152:155], v[148:151], v[96:111]
	v_mfma_f32_32x32x16_bf16 v[80:95], v[156:159], v[144:147], v[80:95]
	v_mfma_f32_32x32x16_bf16 v[64:79], v[156:159], v[148:151], v[64:79]
	s_setprio 0
	s_nop 0
	ds_read_b128 v[168:171], v195 offset:49152
	ds_read_b128 v[172:175], v195 offset:51200
	ds_read_b128 v[176:179], v193 offset:49152
	ds_read_b128 v[180:183], v193 offset:51200
	s_waitcnt lgkmcnt(4)
	s_setprio 1
	v_mfma_f32_32x32x16_bf16 v[48:63], v[160:163], v[144:147], v[48:63]
	v_mfma_f32_32x32x16_bf16 v[32:47], v[160:163], v[148:151], v[32:47]
	v_mfma_f32_32x32x16_bf16 v[16:31], v[164:167], v[144:147], v[16:31]
	v_mfma_f32_32x32x16_bf16 v[0:15], v[164:167], v[148:151], v[0:15]
	s_setprio 0
	s_nop 0
	ds_read_b128 v[184:187], v193 offset:53248
	ds_read_b128 v[188:191], v193 offset:55296
	s_waitcnt lgkmcnt(2)
	s_setprio 1
	v_mfma_f32_32x32x16_bf16 v[112:127], v[176:179], v[168:171], v[112:127]
	v_mfma_f32_32x32x16_bf16 v[96:111], v[176:179], v[172:175], v[96:111]
	v_mfma_f32_32x32x16_bf16 v[80:95], v[180:183], v[168:171], v[80:95]
	v_mfma_f32_32x32x16_bf16 v[64:79], v[180:183], v[172:175], v[64:79]
	s_setprio 0
	s_waitcnt vmcnt(0) lgkmcnt(0)
	s_barrier
	s_nop 0
	ds_read_b128 v[144:147], v194 offset:0
	ds_read_b128 v[148:151], v194 offset:2048
	ds_read_b128 v[152:155], v192 offset:0
	ds_read_b128 v[156:159], v192 offset:2048
	ds_read_b128 v[160:163], v192 offset:4096
	ds_read_b128 v[164:167], v192 offset:6144
	s_setprio 1
	s_nop 0
	v_mfma_f32_32x32x16_bf16 v[48:63], v[184:187], v[168:171], v[48:63]
	v_mfma_f32_32x32x16_bf16 v[32:47], v[184:187], v[172:175], v[32:47]
	v_mfma_f32_32x32x16_bf16 v[16:31], v[188:191], v[168:171], v[16:31]
	v_mfma_f32_32x32x16_bf16 v[0:15], v[188:191], v[172:175], v[0:15]
	s_setprio 0
	s_waitcnt lgkmcnt(2)
	s_setprio 1
	s_nop 0
	v_mfma_f32_32x32x16_bf16 v[112:127], v[152:155], v[144:147], v[112:127]
	v_mfma_f32_32x32x16_bf16 v[96:111], v[152:155], v[148:151], v[96:111]
	v_mfma_f32_32x32x16_bf16 v[80:95], v[156:159], v[144:147], v[80:95]
	v_mfma_f32_32x32x16_bf16 v[64:79], v[156:159], v[148:151], v[64:79]
	s_setprio 0
	s_nop 0
	ds_read_b128 v[168:171], v195 offset:0
	ds_read_b128 v[172:175], v195 offset:2048
	ds_read_b128 v[176:179], v193 offset:0
	ds_read_b128 v[180:183], v193 offset:2048
	s_waitcnt lgkmcnt(4)
	s_setprio 1
	v_mfma_f32_32x32x16_bf16 v[48:63], v[160:163], v[144:147], v[48:63]
	v_mfma_f32_32x32x16_bf16 v[32:47], v[160:163], v[148:151], v[32:47]
	v_mfma_f32_32x32x16_bf16 v[16:31], v[164:167], v[144:147], v[16:31]
	v_mfma_f32_32x32x16_bf16 v[0:15], v[164:167], v[148:151], v[0:15]
	s_setprio 0
	s_nop 0
	ds_read_b128 v[184:187], v193 offset:4096
	ds_read_b128 v[188:191], v193 offset:6144
	s_waitcnt lgkmcnt(2)
	s_setprio 1
	v_mfma_f32_32x32x16_bf16 v[112:127], v[176:179], v[168:171], v[112:127]
	v_mfma_f32_32x32x16_bf16 v[96:111], v[176:179], v[172:175], v[96:111]
	v_mfma_f32_32x32x16_bf16 v[80:95], v[180:183], v[168:171], v[80:95]
	v_mfma_f32_32x32x16_bf16 v[64:79], v[180:183], v[172:175], v[64:79]
	s_setprio 0
	s_waitcnt lgkmcnt(0)
	s_setprio 1
	s_nop 0
	v_mfma_f32_32x32x16_bf16 v[48:63], v[184:187], v[168:171], v[48:63]
	v_mfma_f32_32x32x16_bf16 v[32:47], v[184:187], v[172:175], v[32:47]
	v_mfma_f32_32x32x16_bf16 v[16:31], v[188:191], v[168:171], v[16:31]
	v_mfma_f32_32x32x16_bf16 v[0:15], v[188:191], v[172:175], v[0:15]
	s_setprio 0
	s_load_dwordx16 s[60:75], s[0:1], 0x0
	v_add_u32_e32 v128, 0xffffe000, v132
	v_lshlrev_b64 v[134:135], 2, v[130:131]
	v_lshlrev_b64 v[132:133], 13, v[128:129]
	v_cmp_gt_i32_e32 vcc, 32, v138
	s_waitcnt lgkmcnt(0)
	v_lshl_add_u64 v[136:137], s[60:61], 0, v[134:135]
	v_lshl_add_u64 v[132:133], s[62:63], 0, v[132:133]
	v_lshlrev_b64 v[130:131], 1, v[130:131]
	v_cndmask_b32_e32 v133, v133, v137, vcc
	v_cndmask_b32_e32 v132, v132, v136, vcc
	v_lshl_add_u64 v[136:137], s[8:9], 0, v[130:131]
	v_mov_b32_e32 v130, v204
	s_waitcnt vmcnt(0)
	s_barrier
	s_load_dwordx16 s[60:75], s[0:1], 0xc0
	s_lshl_b32 s40, s40, 7
	v_and_b32_e32 v131, 0x1fff80, v130
	v_and_b32_e32 v138, 0x5f, v130
	v_lshrrev_b32_e32 v130, 3, v130
	v_and_or_b32 v130, v130, 4, v131
	s_ashr_i32 s41, s40, 31
	v_lshl_or_b32 v130, v130, 11, v138
	s_lshl_b64 s[42:43], s[40:41], 2
	v_ashrrev_i32_e32 v131, 31, v130
	v_lshl_add_u64 v[132:133], v[132:133], 0, s[42:43]
	s_waitcnt lgkmcnt(0)
	s_add_u32 s22, s66, s42
	v_lshlrev_b64 v[140:141], 2, v[130:131]
	s_addc_u32 s23, s67, s43
	v_lshlrev_b32_e32 v128, 2, v138
	v_lshl_add_u64 v[138:139], v[132:133], 0, v[140:141]
	v_or_b32_e32 v188, 0x800, v130
	global_load_dword v209, v128, s[22:23]
	s_nop 0
	global_load_dword v128, v128, s[22:23] offset:128
	v_ashrrev_i32_e32 v189, 31, v188
	global_load_dword v142, v[138:139], off
	v_lshlrev_b64 v[202:203], 2, v[188:189]
	v_lshl_add_u64 v[144:145], v[132:133], 0, v[202:203]
	v_or_b32_e32 v184, 0x1000, v130
	global_load_dword v240, v[144:145], off
	v_ashrrev_i32_e32 v185, 31, v184
	v_lshlrev_b64 v[200:201], 2, v[184:185]
	v_lshl_add_u64 v[144:145], v[132:133], 0, v[200:201]
	v_or_b32_e32 v178, 0x1800, v130
	global_load_dword v239, v[144:145], off
	v_ashrrev_i32_e32 v179, 31, v178
	v_lshlrev_b64 v[198:199], 2, v[178:179]
	v_lshl_add_u64 v[144:145], v[132:133], 0, v[198:199]
	v_or_b32_e32 v174, 0x4000, v130
	global_load_dword v238, v[144:145], off
	v_ashrrev_i32_e32 v175, 31, v174
	v_lshlrev_b64 v[196:197], 2, v[174:175]
	v_lshl_add_u64 v[144:145], v[132:133], 0, v[196:197]
	v_or_b32_e32 v170, 0x4800, v130
	global_load_dword v237, v[144:145], off
	v_ashrrev_i32_e32 v171, 31, v170
	v_lshlrev_b64 v[194:195], 2, v[170:171]
	v_lshl_add_u64 v[144:145], v[132:133], 0, v[194:195]
	v_or_b32_e32 v166, 0x5000, v130
	global_load_dword v236, v[144:145], off
	v_ashrrev_i32_e32 v167, 31, v166
	v_lshlrev_b64 v[192:193], 2, v[166:167]
	v_lshl_add_u64 v[144:145], v[132:133], 0, v[192:193]
	v_or_b32_e32 v162, 0x5800, v130
	global_load_dword v235, v[144:145], off
	v_ashrrev_i32_e32 v163, 31, v162
	v_lshlrev_b64 v[190:191], 2, v[162:163]
	v_lshl_add_u64 v[144:145], v[132:133], 0, v[190:191]
	v_or_b32_e32 v158, 0x8000, v130
	global_load_dword v233, v[144:145], off
	v_ashrrev_i32_e32 v159, 31, v158
	v_lshlrev_b64 v[186:187], 2, v[158:159]
	v_lshl_add_u64 v[144:145], v[132:133], 0, v[186:187]
	v_or_b32_e32 v154, 0x8800, v130
	global_load_dword v232, v[144:145], off
	v_ashrrev_i32_e32 v155, 31, v154
	v_lshlrev_b64 v[180:181], 2, v[154:155]
	v_lshl_add_u64 v[144:145], v[132:133], 0, v[180:181]
	v_or_b32_e32 v152, 0x9000, v130
	global_load_dword v230, v[144:145], off
	v_ashrrev_i32_e32 v153, 31, v152
	v_lshlrev_b64 v[176:177], 2, v[152:153]
	v_lshl_add_u64 v[144:145], v[132:133], 0, v[176:177]
	v_or_b32_e32 v150, 0x9800, v130
	global_load_dword v229, v[144:145], off
	v_ashrrev_i32_e32 v151, 31, v150
	v_lshlrev_b64 v[172:173], 2, v[150:151]
	v_lshl_add_u64 v[144:145], v[132:133], 0, v[172:173]
	v_or_b32_e32 v148, 0xc000, v130
	global_load_dword v228, v[144:145], off
	v_ashrrev_i32_e32 v149, 31, v148
	v_or_b32_e32 v146, 0xc800, v130
	v_lshlrev_b64 v[168:169], 2, v[148:149]
	v_ashrrev_i32_e32 v147, 31, v146
	v_lshl_add_u64 v[144:145], v[132:133], 0, v[168:169]
	v_lshlrev_b64 v[164:165], 2, v[146:147]
	global_load_dword v227, v[144:145], off
	v_lshl_add_u64 v[144:145], v[132:133], 0, v[164:165]
	global_load_dword v226, v[144:145], off
	v_or_b32_e32 v144, 0xd000, v130
	v_ashrrev_i32_e32 v145, 31, v144
	v_lshlrev_b64 v[160:161], 2, v[144:145]
	v_lshl_add_u64 v[156:157], v[132:133], 0, v[160:161]
	global_load_dword v234, v[156:157], off
	v_or_b32_e32 v156, 0xd800, v130
	v_ashrrev_i32_e32 v157, 31, v156
	v_lshlrev_b64 v[182:183], 2, v[156:157]
	v_lshl_add_u64 v[210:211], v[132:133], 0, v[182:183]
	global_load_dword v231, v[210:211], off
	s_lshl_b64 s[22:23], s[40:41], 1
	v_lshl_add_u64 v[136:137], v[136:137], 0, s[22:23]
	s_movk_i32 s22, 0x2000
	v_add_co_u32_e32 v212, vcc, s22, v138
	s_movk_i32 s22, 0x4000
	s_nop 0
	v_addc_co_u32_e32 v213, vcc, 0, v139, vcc
	global_load_dword v210, v[138:139], off offset:128
	global_load_dword v211, v[212:213], off offset:128
	v_add_co_u32_e32 v212, vcc, s22, v138
	s_movk_i32 s22, 0x6000
	s_nop 0
	v_addc_co_u32_e32 v213, vcc, 0, v139, vcc
	v_add_co_u32_e32 v214, vcc, s22, v138
	s_mov_b32 s22, 0x10000
	s_nop 0
	v_addc_co_u32_e32 v215, vcc, 0, v139, vcc
	global_load_dword v212, v[212:213], off offset:128
	v_lshl_add_u64 v[134:135], s[92:93], 0, v[134:135]
	global_load_dword v213, v[214:215], off offset:128
	v_add_co_u32_e32 v214, vcc, s22, v138
	s_mov_b32 s22, 0x12000
	s_nop 0
	v_addc_co_u32_e32 v215, vcc, 0, v139, vcc
	v_add_co_u32_e32 v216, vcc, s22, v138
	s_mov_b32 s22, 0x14000
	s_nop 0
	v_addc_co_u32_e32 v217, vcc, 0, v139, vcc
	global_load_dword v214, v[214:215], off offset:128
	v_lshl_add_u64 v[134:135], v[134:135], 0, s[42:43]
	global_load_dword v215, v[216:217], off offset:128
	v_add_co_u32_e32 v216, vcc, s22, v138
	s_mov_b32 s22, 0x16000
	s_nop 0
	v_addc_co_u32_e32 v217, vcc, 0, v139, vcc
	v_add_co_u32_e32 v218, vcc, s22, v138
	s_mov_b32 s22, 0x20000
	s_nop 0
	v_addc_co_u32_e32 v219, vcc, 0, v139, vcc
	global_load_dword v216, v[216:217], off offset:128
	s_waitcnt vmcnt(22)
	v_add_f32_e32 v112, v112, v142
	global_load_dword v220, v[218:219], off offset:128
	v_add_co_u32_e32 v218, vcc, s22, v138
	s_mov_b32 s22, 0x22000
	s_nop 0
	v_addc_co_u32_e32 v219, vcc, 0, v139, vcc
	global_load_dword v221, v[218:219], off offset:128
	v_add_co_u32_e32 v218, vcc, s22, v138
	s_mov_b32 s22, 0x24000
	s_nop 0
	v_addc_co_u32_e32 v219, vcc, 0, v139, vcc
	global_load_dword v223, v[218:219], off offset:128
	v_add_co_u32_e32 v218, vcc, s22, v138
	s_mov_b32 s22, 0x26000
	s_nop 0
	v_addc_co_u32_e32 v219, vcc, 0, v139, vcc
	global_load_dword v224, v[218:219], off offset:128
	v_add_co_u32_e32 v218, vcc, s22, v138
	s_mov_b32 s22, 0x30000
	s_nop 0
	v_addc_co_u32_e32 v219, vcc, 0, v139, vcc
	global_load_dword v225, v[218:219], off offset:128
	v_add_co_u32_e32 v218, vcc, s22, v138
	s_mov_b32 s22, 0x32000
	s_nop 0
	v_addc_co_u32_e32 v219, vcc, 0, v139, vcc
	global_load_dword v222, v[218:219], off offset:128
	v_add_co_u32_e32 v218, vcc, s22, v138
	s_mov_b32 s22, 0x34000
	s_nop 0
	v_addc_co_u32_e32 v219, vcc, 0, v139, vcc
	v_add_co_u32_e32 v242, vcc, s22, v138
	s_mov_b32 s22, 0x36000
	s_nop 0
	v_addc_co_u32_e32 v243, vcc, 0, v139, vcc
	global_load_dword v218, v[218:219], off offset:128
	v_lshl_add_u64 v[140:141], v[134:135], 0, v[140:141]
	global_load_dword v217, v[242:243], off offset:128
	v_add_co_u32_e32 v242, vcc, s22, v138
	v_lshl_add_u64 v[142:143], v[130:131], 1, v[136:137]
	s_nop 0
	v_addc_co_u32_e32 v243, vcc, 0, v139, vcc
	global_load_dword v219, v[242:243], off offset:128
	s_waitcnt vmcnt(30)
	v_add_f32_e32 v131, v113, v240
	global_store_dword v[140:141], v112, off
	v_mul_f32_e32 v112, v209, v112
	v_cvt_pk_bf16_f32 v112, v112, s0
	global_store_short v[142:143], v112, off
	v_lshl_add_u64 v[112:113], v[134:135], 0, v[202:203]
	global_store_dword v[112:113], v131, off
	v_mul_f32_e32 v112, v209, v131
	v_cvt_pk_bf16_f32 v131, v112, s0
	v_lshl_add_u64 v[112:113], v[188:189], 1, v[136:137]
	global_store_short v[112:113], v131, off
	s_waitcnt vmcnt(33)
	v_add_f32_e32 v114, v114, v239
	v_lshl_add_u64 v[112:113], v[134:135], 0, v[200:201]
	global_store_dword v[112:113], v114, off
	v_mul_f32_e32 v112, v209, v114
	v_cvt_pk_bf16_f32 v114, v112, s0
	v_lshl_add_u64 v[112:113], v[184:185], 1, v[136:137]
	global_store_short v[112:113], v114, off
	s_waitcnt vmcnt(34)
	v_add_f32_e32 v114, v115, v238
	v_lshl_add_u64 v[112:113], v[134:135], 0, v[198:199]
	global_store_dword v[112:113], v114, off
	v_mul_f32_e32 v112, v209, v114
	v_cvt_pk_bf16_f32 v114, v112, s0
	v_lshl_add_u64 v[112:113], v[178:179], 1, v[136:137]
	global_store_short v[112:113], v114, off
	s_waitcnt vmcnt(35)
	v_add_f32_e32 v114, v116, v237
	v_lshl_add_u64 v[112:113], v[134:135], 0, v[196:197]
	global_store_dword v[112:113], v114, off
	v_mul_f32_e32 v112, v209, v114
	v_cvt_pk_bf16_f32 v114, v112, s0
	v_lshl_add_u64 v[112:113], v[174:175], 1, v[136:137]
	global_store_short v[112:113], v114, off
	s_waitcnt vmcnt(36)
	v_add_f32_e32 v114, v117, v236
	v_lshl_add_u64 v[112:113], v[134:135], 0, v[194:195]
	global_store_dword v[112:113], v114, off
	v_mul_f32_e32 v112, v209, v114
	v_cvt_pk_bf16_f32 v114, v112, s0
	v_lshl_add_u64 v[112:113], v[170:171], 1, v[136:137]
	global_store_short v[112:113], v114, off
	s_waitcnt vmcnt(37)
	v_add_f32_e32 v114, v118, v235
	v_lshl_add_u64 v[112:113], v[134:135], 0, v[192:193]
	global_store_dword v[112:113], v114, off
	v_mul_f32_e32 v112, v209, v114
	v_cvt_pk_bf16_f32 v114, v112, s0
	v_lshl_add_u64 v[112:113], v[166:167], 1, v[136:137]
	global_store_short v[112:113], v114, off
	s_waitcnt vmcnt(38)
	v_add_f32_e32 v114, v119, v233
	v_lshl_add_u64 v[112:113], v[134:135], 0, v[190:191]
	global_store_dword v[112:113], v114, off
	v_mul_f32_e32 v112, v209, v114
	v_cvt_pk_bf16_f32 v114, v112, s0
	v_lshl_add_u64 v[112:113], v[162:163], 1, v[136:137]
	global_store_short v[112:113], v114, off
	s_waitcnt vmcnt(39)
	v_add_f32_e32 v114, v120, v232
	v_lshl_add_u64 v[112:113], v[134:135], 0, v[186:187]
	global_store_dword v[112:113], v114, off
	v_mul_f32_e32 v112, v209, v114
	v_cvt_pk_bf16_f32 v114, v112, s0
	v_lshl_add_u64 v[112:113], v[158:159], 1, v[136:137]
	global_store_short v[112:113], v114, off
	s_waitcnt vmcnt(40)
	v_add_f32_e32 v114, v121, v230
	v_lshl_add_u64 v[112:113], v[134:135], 0, v[180:181]
	global_store_dword v[112:113], v114, off
	v_mul_f32_e32 v112, v209, v114
	v_cvt_pk_bf16_f32 v114, v112, s0
	v_lshl_add_u64 v[112:113], v[154:155], 1, v[136:137]
	global_store_short v[112:113], v114, off
	s_waitcnt vmcnt(41)
	v_add_f32_e32 v114, v122, v229
	v_lshl_add_u64 v[112:113], v[134:135], 0, v[176:177]
	global_store_dword v[112:113], v114, off
	v_mul_f32_e32 v112, v209, v114
	v_cvt_pk_bf16_f32 v114, v112, s0
	v_lshl_add_u64 v[112:113], v[152:153], 1, v[136:137]
	global_store_short v[112:113], v114, off
	s_waitcnt vmcnt(42)
	v_add_f32_e32 v114, v123, v228
	v_lshl_add_u64 v[112:113], v[134:135], 0, v[172:173]
	global_store_dword v[112:113], v114, off
	v_mul_f32_e32 v112, v209, v114
	v_cvt_pk_bf16_f32 v114, v112, s0
	v_lshl_add_u64 v[112:113], v[150:151], 1, v[136:137]
	global_store_short v[112:113], v114, off
	s_waitcnt vmcnt(43)
	v_add_f32_e32 v114, v124, v227
	v_lshl_add_u64 v[112:113], v[134:135], 0, v[168:169]
	global_store_dword v[112:113], v114, off
	v_mul_f32_e32 v112, v209, v114
	v_cvt_pk_bf16_f32 v114, v112, s0
	v_lshl_add_u64 v[112:113], v[148:149], 1, v[136:137]
	global_store_short v[112:113], v114, off
	s_waitcnt vmcnt(44)
	v_add_f32_e32 v114, v125, v226
	v_lshl_add_u64 v[112:113], v[134:135], 0, v[164:165]
	global_store_dword v[112:113], v114, off
	v_mul_f32_e32 v112, v209, v114
	v_cvt_pk_bf16_f32 v114, v112, s0
	v_lshl_add_u64 v[112:113], v[146:147], 1, v[136:137]
	global_store_short v[112:113], v114, off
	s_waitcnt vmcnt(45)
	v_add_f32_e32 v114, v126, v234
	v_lshl_add_u64 v[112:113], v[134:135], 0, v[160:161]
	global_store_dword v[112:113], v114, off
	v_mul_f32_e32 v112, v209, v114
	v_cvt_pk_bf16_f32 v114, v112, s0
	v_lshl_add_u64 v[112:113], v[144:145], 1, v[136:137]
	global_store_short v[112:113], v114, off
	s_waitcnt vmcnt(46)
	v_add_f32_e32 v114, v127, v231
	v_lshl_add_u64 v[112:113], v[134:135], 0, v[182:183]
	global_store_dword v[112:113], v114, off
	v_mul_f32_e32 v112, v209, v114
	v_cvt_pk_bf16_f32 v114, v112, s0
	v_lshl_add_u64 v[112:113], v[156:157], 1, v[136:137]
	s_mov_b32 s22, 0x40000
	global_store_short v[112:113], v114, off
	v_add_co_u32_e32 v112, vcc, s22, v138
	s_mov_b32 s22, 0x42000
	s_nop 0
	v_addc_co_u32_e32 v113, vcc, 0, v139, vcc
	global_load_dword v148, v[112:113], off
	v_add_co_u32_e32 v112, vcc, s22, v138
	s_mov_b32 s22, 0x44000
	s_nop 0
	v_addc_co_u32_e32 v113, vcc, 0, v139, vcc
	v_add_co_u32_e32 v114, vcc, s22, v138
	s_mov_b32 s22, 0x46000
	s_nop 0
	v_addc_co_u32_e32 v115, vcc, 0, v139, vcc
	v_add_co_u32_e32 v116, vcc, s22, v138
	s_mov_b32 s22, 0x50000
	s_nop 0
	v_addc_co_u32_e32 v117, vcc, 0, v139, vcc
	v_add_co_u32_e32 v118, vcc, s22, v138
	s_mov_b32 s22, 0x52000
	s_nop 0
	v_addc_co_u32_e32 v119, vcc, 0, v139, vcc
	v_add_co_u32_e32 v120, vcc, s22, v138
	s_mov_b32 s22, 0x54000
	s_nop 0
	v_addc_co_u32_e32 v121, vcc, 0, v139, vcc
	v_add_co_u32_e32 v122, vcc, s22, v138
	s_mov_b32 s22, 0x56000
	s_nop 0
	v_addc_co_u32_e32 v123, vcc, 0, v139, vcc
	v_add_co_u32_e32 v124, vcc, s22, v138
	s_mov_b32 s22, 0x60000
	s_nop 0
	v_addc_co_u32_e32 v125, vcc, 0, v139, vcc
	v_add_co_u32_e32 v126, vcc, s22, v138
	s_mov_b32 s22, 0x62000
	s_nop 0
	v_addc_co_u32_e32 v127, vcc, 0, v139, vcc
	v_add_co_u32_e32 v144, vcc, s22, v138
	s_mov_b32 s22, 0x64000
	s_nop 0
	v_addc_co_u32_e32 v145, vcc, 0, v139, vcc
	v_add_co_u32_e32 v146, vcc, s22, v138
	s_mov_b32 s22, 0x66000
	s_nop 0
	v_addc_co_u32_e32 v147, vcc, 0, v139, vcc
	v_add_co_u32_e32 v150, vcc, s22, v138
	s_mov_b32 s22, 0x70000
	s_nop 0
	v_addc_co_u32_e32 v151, vcc, 0, v139, vcc
	v_add_co_u32_e32 v152, vcc, s22, v138
	s_mov_b32 s22, 0x72000
	s_nop 0
	v_addc_co_u32_e32 v153, vcc, 0, v139, vcc
	v_add_co_u32_e32 v154, vcc, s22, v138
	s_mov_b32 s22, 0x74000
	s_nop 0
	v_addc_co_u32_e32 v155, vcc, 0, v139, vcc
	v_add_co_u32_e32 v156, vcc, s22, v138
	s_mov_b32 s22, 0x76000
	s_nop 0
	v_addc_co_u32_e32 v157, vcc, 0, v139, vcc
	v_add_co_u32_e32 v158, vcc, s22, v138
	s_waitcnt vmcnt(48)
	v_add_f32_e32 v96, v96, v210
	v_addc_co_u32_e32 v159, vcc, 0, v139, vcc
	global_load_dword v149, v[112:113], off
	global_load_dword v160, v[114:115], off
	global_load_dword v161, v[116:117], off
	global_load_dword v162, v[118:119], off
	global_load_dword v163, v[120:121], off
	global_load_dword v164, v[122:123], off
	global_load_dword v165, v[124:125], off
	global_load_dword v166, v[126:127], off
	global_load_dword v167, v[144:145], off
	global_load_dword v168, v[146:147], off
	global_load_dword v169, v[150:151], off
	global_load_dword v170, v[152:153], off
	global_load_dword v171, v[154:155], off
	global_load_dword v172, v[156:157], off
	global_load_dword v173, v[158:159], off
	s_waitcnt vmcnt(62)
	v_add_f32_e32 v131, v97, v211
	global_store_dword v[140:141], v96, off offset:128
	v_mul_f32_e32 v96, v128, v96
	v_cvt_pk_bf16_f32 v96, v96, s0
	global_store_short v[142:143], v96, off offset:64
	v_or_b32_e32 v96, 0x820, v130
	v_ashrrev_i32_e32 v97, 31, v96
	v_lshl_add_u64 v[140:141], v[96:97], 2, v[134:135]
	global_store_dword v[140:141], v131, off
	v_mul_f32_e32 v131, v128, v131
	v_cvt_pk_bf16_f32 v131, v131, s0
	v_lshl_add_u64 v[96:97], v[96:97], 1, v[136:137]
	global_store_short v[96:97], v131, off
	v_or_b32_e32 v96, 0x1020, v130
	v_ashrrev_i32_e32 v97, 31, v96
	s_waitcnt vmcnt(62)
	v_add_f32_e32 v98, v98, v212
	v_lshl_add_u64 v[140:141], v[96:97], 2, v[134:135]
	global_store_dword v[140:141], v98, off
	v_mul_f32_e32 v98, v128, v98
	v_cvt_pk_bf16_f32 v98, v98, s0
	v_lshl_add_u64 v[96:97], v[96:97], 1, v[136:137]
	global_store_short v[96:97], v98, off
	v_or_b32_e32 v96, 0x1820, v130
	v_ashrrev_i32_e32 v97, 31, v96
	v_add_f32_e32 v131, v99, v213
	v_lshl_add_u64 v[98:99], v[96:97], 2, v[134:135]
	global_store_dword v[98:99], v131, off
	v_mul_f32_e32 v98, v128, v131
	v_cvt_pk_bf16_f32 v98, v98, s0
	v_lshl_add_u64 v[96:97], v[96:97], 1, v[136:137]
	global_store_short v[96:97], v98, off
	v_or_b32_e32 v96, 0x4020, v130
	v_ashrrev_i32_e32 v97, 31, v96
	v_add_f32_e32 v100, v100, v214
	v_lshl_add_u64 v[98:99], v[96:97], 2, v[134:135]
	global_store_dword v[98:99], v100, off
	v_mul_f32_e32 v98, v128, v100
	v_cvt_pk_bf16_f32 v98, v98, s0
	v_lshl_add_u64 v[96:97], v[96:97], 1, v[136:137]
	global_store_short v[96:97], v98, off
	v_or_b32_e32 v96, 0x4820, v130
	v_ashrrev_i32_e32 v97, 31, v96
	v_add_f32_e32 v100, v101, v215
	v_lshl_add_u64 v[98:99], v[96:97], 2, v[134:135]
	global_store_dword v[98:99], v100, off
	v_mul_f32_e32 v98, v128, v100
	v_cvt_pk_bf16_f32 v98, v98, s0
	v_lshl_add_u64 v[96:97], v[96:97], 1, v[136:137]
	global_store_short v[96:97], v98, off
	v_or_b32_e32 v96, 0x5020, v130
	v_ashrrev_i32_e32 v97, 31, v96
	s_waitcnt vmcnt(62)
	v_add_f32_e32 v100, v102, v216
	v_lshl_add_u64 v[98:99], v[96:97], 2, v[134:135]
	global_store_dword v[98:99], v100, off
	v_mul_f32_e32 v98, v128, v100
	v_cvt_pk_bf16_f32 v98, v98, s0
	v_lshl_add_u64 v[96:97], v[96:97], 1, v[136:137]
	global_store_short v[96:97], v98, off
	v_or_b32_e32 v96, 0x5820, v130
	v_ashrrev_i32_e32 v97, 31, v96
	v_add_f32_e32 v100, v103, v220
	v_lshl_add_u64 v[98:99], v[96:97], 2, v[134:135]
	global_store_dword v[98:99], v100, off
	v_mul_f32_e32 v98, v128, v100
	v_cvt_pk_bf16_f32 v98, v98, s0
	v_lshl_add_u64 v[96:97], v[96:97], 1, v[136:137]
	global_store_short v[96:97], v98, off
	v_or_b32_e32 v96, 0x8020, v130
	v_ashrrev_i32_e32 v97, 31, v96
	v_add_f32_e32 v100, v104, v221
	v_lshl_add_u64 v[98:99], v[96:97], 2, v[134:135]
	global_store_dword v[98:99], v100, off
	v_mul_f32_e32 v98, v128, v100
	v_cvt_pk_bf16_f32 v98, v98, s0
	v_lshl_add_u64 v[96:97], v[96:97], 1, v[136:137]
	global_store_short v[96:97], v98, off
	v_or_b32_e32 v96, 0x8820, v130
	v_ashrrev_i32_e32 v97, 31, v96
	v_add_f32_e32 v100, v105, v223
	v_lshl_add_u64 v[98:99], v[96:97], 2, v[134:135]
	global_store_dword v[98:99], v100, off
	v_mul_f32_e32 v98, v128, v100
	v_cvt_pk_bf16_f32 v98, v98, s0
	v_lshl_add_u64 v[96:97], v[96:97], 1, v[136:137]
	global_store_short v[96:97], v98, off
	v_or_b32_e32 v96, 0x9020, v130
	v_ashrrev_i32_e32 v97, 31, v96
	v_add_f32_e32 v100, v106, v224
	v_lshl_add_u64 v[98:99], v[96:97], 2, v[134:135]
	global_store_dword v[98:99], v100, off
	v_mul_f32_e32 v98, v128, v100
	v_cvt_pk_bf16_f32 v98, v98, s0
	v_lshl_add_u64 v[96:97], v[96:97], 1, v[136:137]
	global_store_short v[96:97], v98, off
	v_or_b32_e32 v96, 0x9820, v130
	v_ashrrev_i32_e32 v97, 31, v96
	v_add_f32_e32 v100, v107, v225
	v_lshl_add_u64 v[98:99], v[96:97], 2, v[134:135]
	global_store_dword v[98:99], v100, off
	v_mul_f32_e32 v98, v128, v100
	v_cvt_pk_bf16_f32 v98, v98, s0
	v_lshl_add_u64 v[96:97], v[96:97], 1, v[136:137]
	global_store_short v[96:97], v98, off
	v_or_b32_e32 v96, 0xc020, v130
	v_ashrrev_i32_e32 v97, 31, v96
	v_add_f32_e32 v100, v108, v222
	v_lshl_add_u64 v[98:99], v[96:97], 2, v[134:135]
	global_store_dword v[98:99], v100, off
	v_mul_f32_e32 v98, v128, v100
	v_cvt_pk_bf16_f32 v98, v98, s0
	v_lshl_add_u64 v[96:97], v[96:97], 1, v[136:137]
	global_store_short v[96:97], v98, off
	v_or_b32_e32 v96, 0xc820, v130
	v_ashrrev_i32_e32 v97, 31, v96
	v_add_f32_e32 v100, v109, v218
	v_lshl_add_u64 v[98:99], v[96:97], 2, v[134:135]
	global_store_dword v[98:99], v100, off
	v_mul_f32_e32 v98, v128, v100
	v_cvt_pk_bf16_f32 v98, v98, s0
	v_lshl_add_u64 v[96:97], v[96:97], 1, v[136:137]
	global_store_short v[96:97], v98, off
	v_or_b32_e32 v96, 0xd020, v130
	v_ashrrev_i32_e32 v97, 31, v96
	s_waitcnt vmcnt(62)
	v_add_f32_e32 v100, v110, v217
	v_lshl_add_u64 v[98:99], v[96:97], 2, v[134:135]
	global_store_dword v[98:99], v100, off
	v_mul_f32_e32 v98, v128, v100
	v_cvt_pk_bf16_f32 v98, v98, s0
	v_lshl_add_u64 v[96:97], v[96:97], 1, v[136:137]
	global_store_short v[96:97], v98, off
	v_or_b32_e32 v96, 0xd820, v130
	v_ashrrev_i32_e32 v97, 31, v96
	v_add_f32_e32 v100, v111, v219
	v_lshl_add_u64 v[98:99], v[96:97], 2, v[134:135]
	global_store_dword v[98:99], v100, off
	v_mul_f32_e32 v98, v128, v100
	v_cvt_pk_bf16_f32 v98, v98, s0
	v_lshl_add_u64 v[96:97], v[96:97], 1, v[136:137]
	global_store_short v[96:97], v98, off
	v_or_b32_e32 v96, 0x10000, v130
	v_ashrrev_i32_e32 v97, 31, v96
	v_lshlrev_b64 v[140:141], 2, v[96:97]
	v_lshl_add_u64 v[98:99], v[132:133], 0, v[140:141]
	global_load_dword v131, v[98:99], off offset:128
	s_nop 0
	global_load_dword v112, v[112:113], off offset:128
	s_nop 0
	global_load_dword v111, v[114:115], off offset:128
	global_load_dword v110, v[116:117], off offset:128
	global_load_dword v109, v[118:119], off offset:128
	global_load_dword v108, v[120:121], off offset:128
	global_load_dword v107, v[122:123], off offset:128
	global_load_dword v106, v[124:125], off offset:128
	global_load_dword v105, v[126:127], off offset:128
	global_load_dword v104, v[144:145], off offset:128
	global_load_dword v103, v[146:147], off offset:128
	global_load_dword v102, v[150:151], off offset:128
	global_load_dword v101, v[152:153], off offset:128
	global_load_dword v100, v[154:155], off offset:128
	global_load_dword v99, v[156:157], off offset:128
	global_load_dword v98, v[158:159], off offset:128
	s_waitcnt vmcnt(62)
	v_add_f32_e32 v80, v80, v148
	v_lshl_add_u64 v[114:115], v[134:135], 0, v[140:141]
	global_store_dword v[114:115], v80, off
	v_mul_f32_e32 v80, v209, v80
	v_cvt_pk_bf16_f32 v80, v80, s0
	v_lshl_add_u64 v[96:97], v[96:97], 1, v[136:137]
	global_store_short v[96:97], v80, off
	v_or_b32_e32 v80, 0x10800, v130
	v_add_f32_e32 v113, v81, v149
	v_ashrrev_i32_e32 v81, 31, v80
	v_lshl_add_u64 v[96:97], v[80:81], 2, v[134:135]
	global_store_dword v[96:97], v113, off
	v_mul_f32_e32 v96, v209, v113
	v_cvt_pk_bf16_f32 v96, v96, s0
	v_lshl_add_u64 v[80:81], v[80:81], 1, v[136:137]
	global_store_short v[80:81], v96, off
	v_or_b32_e32 v80, 0x11000, v130
	v_ashrrev_i32_e32 v81, 31, v80
	s_waitcnt vmcnt(62)
	v_add_f32_e32 v82, v82, v160
	v_lshl_add_u64 v[96:97], v[80:81], 2, v[134:135]
	global_store_dword v[96:97], v82, off
	v_mul_f32_e32 v82, v209, v82
	v_cvt_pk_bf16_f32 v82, v82, s0
	v_lshl_add_u64 v[80:81], v[80:81], 1, v[136:137]
	global_store_short v[80:81], v82, off
	v_or_b32_e32 v80, 0x11800, v130
	v_ashrrev_i32_e32 v81, 31, v80
	v_add_f32_e32 v96, v83, v161
	v_lshl_add_u64 v[82:83], v[80:81], 2, v[134:135]
	global_store_dword v[82:83], v96, off
	v_mul_f32_e32 v82, v209, v96
	v_cvt_pk_bf16_f32 v82, v82, s0
	v_lshl_add_u64 v[80:81], v[80:81], 1, v[136:137]
	global_store_short v[80:81], v82, off
	v_or_b32_e32 v80, 0x14000, v130
	v_ashrrev_i32_e32 v81, 31, v80
	v_add_f32_e32 v84, v84, v162
	v_lshl_add_u64 v[82:83], v[80:81], 2, v[134:135]
	global_store_dword v[82:83], v84, off
	v_mul_f32_e32 v82, v209, v84
	v_cvt_pk_bf16_f32 v82, v82, s0
	v_lshl_add_u64 v[80:81], v[80:81], 1, v[136:137]
	global_store_short v[80:81], v82, off
	v_or_b32_e32 v80, 0x14800, v130
	v_ashrrev_i32_e32 v81, 31, v80
	v_add_f32_e32 v84, v85, v163
	v_lshl_add_u64 v[82:83], v[80:81], 2, v[134:135]
	global_store_dword v[82:83], v84, off
	v_mul_f32_e32 v82, v209, v84
	v_cvt_pk_bf16_f32 v82, v82, s0
	v_lshl_add_u64 v[80:81], v[80:81], 1, v[136:137]
	global_store_short v[80:81], v82, off
	v_or_b32_e32 v80, 0x15000, v130
	v_ashrrev_i32_e32 v81, 31, v80
	s_waitcnt vmcnt(62)
	v_add_f32_e32 v84, v86, v164
	v_lshl_add_u64 v[82:83], v[80:81], 2, v[134:135]
	global_store_dword v[82:83], v84, off
	v_mul_f32_e32 v82, v209, v84
	v_cvt_pk_bf16_f32 v82, v82, s0
	v_lshl_add_u64 v[80:81], v[80:81], 1, v[136:137]
	global_store_short v[80:81], v82, off
	v_or_b32_e32 v80, 0x15800, v130
	v_ashrrev_i32_e32 v81, 31, v80
	v_add_f32_e32 v84, v87, v165
	v_lshl_add_u64 v[82:83], v[80:81], 2, v[134:135]
	global_store_dword v[82:83], v84, off
	v_mul_f32_e32 v82, v209, v84
	v_cvt_pk_bf16_f32 v82, v82, s0
	v_lshl_add_u64 v[80:81], v[80:81], 1, v[136:137]
	global_store_short v[80:81], v82, off
	v_or_b32_e32 v80, 0x18000, v130
	v_ashrrev_i32_e32 v81, 31, v80
	v_add_f32_e32 v84, v88, v166
	v_lshl_add_u64 v[82:83], v[80:81], 2, v[134:135]
	global_store_dword v[82:83], v84, off
	v_mul_f32_e32 v82, v209, v84
	v_cvt_pk_bf16_f32 v82, v82, s0
	v_lshl_add_u64 v[80:81], v[80:81], 1, v[136:137]
	global_store_short v[80:81], v82, off
	v_or_b32_e32 v80, 0x18800, v130
	v_ashrrev_i32_e32 v81, 31, v80
	v_add_f32_e32 v84, v89, v167
	v_lshl_add_u64 v[82:83], v[80:81], 2, v[134:135]
	global_store_dword v[82:83], v84, off
	v_mul_f32_e32 v82, v209, v84
	v_cvt_pk_bf16_f32 v82, v82, s0
	v_lshl_add_u64 v[80:81], v[80:81], 1, v[136:137]
	global_store_short v[80:81], v82, off
	v_or_b32_e32 v80, 0x19000, v130
	v_ashrrev_i32_e32 v81, 31, v80
	v_add_f32_e32 v84, v90, v168
	v_lshl_add_u64 v[82:83], v[80:81], 2, v[134:135]
	global_store_dword v[82:83], v84, off
	v_mul_f32_e32 v82, v209, v84
	v_cvt_pk_bf16_f32 v82, v82, s0
	v_lshl_add_u64 v[80:81], v[80:81], 1, v[136:137]
	global_store_short v[80:81], v82, off
	v_or_b32_e32 v80, 0x19800, v130
	v_ashrrev_i32_e32 v81, 31, v80
	v_add_f32_e32 v84, v91, v169
	v_lshl_add_u64 v[82:83], v[80:81], 2, v[134:135]
	global_store_dword v[82:83], v84, off
	v_mul_f32_e32 v82, v209, v84
	v_cvt_pk_bf16_f32 v82, v82, s0
	v_lshl_add_u64 v[80:81], v[80:81], 1, v[136:137]
	global_store_short v[80:81], v82, off
	v_or_b32_e32 v80, 0x1c000, v130
	v_ashrrev_i32_e32 v81, 31, v80
	v_add_f32_e32 v84, v92, v170
	v_lshl_add_u64 v[82:83], v[80:81], 2, v[134:135]
	global_store_dword v[82:83], v84, off
	v_mul_f32_e32 v82, v209, v84
	v_cvt_pk_bf16_f32 v82, v82, s0
	v_lshl_add_u64 v[80:81], v[80:81], 1, v[136:137]
	global_store_short v[80:81], v82, off
	v_or_b32_e32 v80, 0x1c800, v130
	v_ashrrev_i32_e32 v81, 31, v80
	v_add_f32_e32 v84, v93, v171
	v_lshl_add_u64 v[82:83], v[80:81], 2, v[134:135]
	global_store_dword v[82:83], v84, off
	v_mul_f32_e32 v82, v209, v84
	v_cvt_pk_bf16_f32 v82, v82, s0
	v_lshl_add_u64 v[80:81], v[80:81], 1, v[136:137]
	global_store_short v[80:81], v82, off
	v_or_b32_e32 v80, 0x1d000, v130
	v_ashrrev_i32_e32 v81, 31, v80
	s_waitcnt vmcnt(62)
	v_add_f32_e32 v84, v94, v172
	v_lshl_add_u64 v[82:83], v[80:81], 2, v[134:135]
	global_store_dword v[82:83], v84, off
	v_mul_f32_e32 v82, v209, v84
	v_cvt_pk_bf16_f32 v82, v82, s0
	v_lshl_add_u64 v[80:81], v[80:81], 1, v[136:137]
	global_store_short v[80:81], v82, off
	v_or_b32_e32 v80, 0x1d800, v130
	v_ashrrev_i32_e32 v81, 31, v80
	v_add_f32_e32 v84, v95, v173
	v_lshl_add_u64 v[82:83], v[80:81], 2, v[134:135]
	global_store_dword v[82:83], v84, off
	v_mul_f32_e32 v82, v209, v84
	v_cvt_pk_bf16_f32 v82, v82, s0
	v_lshl_add_u64 v[80:81], v[80:81], 1, v[136:137]
	global_store_short v[80:81], v82, off
	v_add_co_u32_e32 v80, vcc, s50, v138
	s_mov_b32 s22, 0xb4000
	s_nop 0
	v_addc_co_u32_e32 v81, vcc, 0, v139, vcc
	global_load_dword v142, v[80:81], off
	v_add_co_u32_e32 v80, vcc, s2, v138
	v_or_b32_e32 v126, 0x10020, v130
	s_nop 0
	v_addc_co_u32_e32 v81, vcc, 0, v139, vcc
	v_add_co_u32_e32 v82, vcc, s36, v138
	v_ashrrev_i32_e32 v127, 31, v126
	s_nop 0
	v_addc_co_u32_e32 v83, vcc, 0, v139, vcc
	v_add_co_u32_e32 v84, vcc, s37, v138
	s_waitcnt vmcnt(48)
	v_add_f32_e32 v64, v64, v131
	v_addc_co_u32_e32 v85, vcc, 0, v139, vcc
	v_add_co_u32_e32 v86, vcc, s38, v138
	v_lshl_add_u64 v[140:141], v[126:127], 2, v[134:135]
	s_nop 0
	v_addc_co_u32_e32 v87, vcc, 0, v139, vcc
	v_add_co_u32_e32 v88, vcc, s39, v138
	global_load_dword v143, v[80:81], off
	global_load_dword v144, v[82:83], off
	global_load_dword v145, v[84:85], off
	global_load_dword v146, v[86:87], off
	v_addc_co_u32_e32 v89, vcc, 0, v139, vcc
	v_add_co_u32_e32 v90, vcc, s96, v138
	global_load_dword v147, v[88:89], off
	s_nop 0
	v_addc_co_u32_e32 v91, vcc, 0, v139, vcc
	v_add_co_u32_e32 v92, vcc, s97, v138
	global_load_dword v148, v[90:91], off
	s_nop 0
	v_addc_co_u32_e32 v93, vcc, 0, v139, vcc
	v_add_co_u32_e32 v94, vcc, s3, v138
	global_load_dword v149, v[92:93], off
	s_nop 0
	v_addc_co_u32_e32 v95, vcc, 0, v139, vcc
	v_add_co_u32_e32 v96, vcc, s4, v138
	global_load_dword v150, v[94:95], off
	s_nop 0
	v_addc_co_u32_e32 v97, vcc, 0, v139, vcc
	v_add_co_u32_e32 v114, vcc, s5, v138
	global_load_dword v151, v[96:97], off
	s_nop 0
	v_addc_co_u32_e32 v115, vcc, 0, v139, vcc
	v_add_co_u32_e32 v116, vcc, s45, v138
	global_load_dword v152, v[114:115], off
	s_nop 0
	v_addc_co_u32_e32 v117, vcc, 0, v139, vcc
	v_add_co_u32_e32 v118, vcc, s54, v138
	global_load_dword v153, v[116:117], off
	s_nop 0
	v_addc_co_u32_e32 v119, vcc, 0, v139, vcc
	v_add_co_u32_e32 v120, vcc, s55, v138
	global_load_dword v154, v[118:119], off
	s_nop 0
	v_addc_co_u32_e32 v121, vcc, 0, v139, vcc
	v_add_co_u32_e32 v122, vcc, s22, v138
	s_mov_b32 s22, 0xb6000
	s_nop 0
	v_addc_co_u32_e32 v123, vcc, 0, v139, vcc
	v_add_co_u32_e32 v124, vcc, s22, v138
	global_load_dword v155, v[120:121], off
	global_load_dword v156, v[122:123], off
	v_addc_co_u32_e32 v125, vcc, 0, v139, vcc
	global_load_dword v157, v[124:125], off
	v_lshl_add_u64 v[126:127], v[126:127], 1, v[136:137]
	global_store_dword v[140:141], v64, off
	v_mul_f32_e32 v64, v128, v64
	v_cvt_pk_bf16_f32 v64, v64, s0
	global_store_short v[126:127], v64, off
	v_or_b32_e32 v64, 0x10820, v130
	s_waitcnt vmcnt(62)
	v_add_f32_e32 v126, v65, v112
	v_ashrrev_i32_e32 v65, 31, v64
	v_lshl_add_u64 v[112:113], v[64:65], 2, v[134:135]
	global_store_dword v[112:113], v126, off
	v_mul_f32_e32 v112, v128, v126
	v_cvt_pk_bf16_f32 v112, v112, s0
	v_lshl_add_u64 v[64:65], v[64:65], 1, v[136:137]
	global_store_short v[64:65], v112, off
	v_or_b32_e32 v64, 0x11020, v130
	v_ashrrev_i32_e32 v65, 31, v64
	v_add_f32_e32 v66, v66, v111
	v_lshl_add_u64 v[112:113], v[64:65], 2, v[134:135]
	global_store_dword v[112:113], v66, off
	v_mul_f32_e32 v66, v128, v66
	v_cvt_pk_bf16_f32 v66, v66, s0
	v_lshl_add_u64 v[64:65], v[64:65], 1, v[136:137]
	global_store_short v[64:65], v66, off
	v_or_b32_e32 v64, 0x11820, v130
	v_ashrrev_i32_e32 v65, 31, v64
	v_add_f32_e32 v110, v67, v110
	v_lshl_add_u64 v[66:67], v[64:65], 2, v[134:135]
	global_store_dword v[66:67], v110, off
	v_mul_f32_e32 v66, v128, v110
	v_cvt_pk_bf16_f32 v66, v66, s0
	v_lshl_add_u64 v[64:65], v[64:65], 1, v[136:137]
	global_store_short v[64:65], v66, off
	v_or_b32_e32 v64, 0x14020, v130
	v_ashrrev_i32_e32 v65, 31, v64
	s_waitcnt vmcnt(62)
	v_add_f32_e32 v68, v68, v109
	v_lshl_add_u64 v[66:67], v[64:65], 2, v[134:135]
	global_store_dword v[66:67], v68, off
	v_mul_f32_e32 v66, v128, v68
	v_cvt_pk_bf16_f32 v66, v66, s0
	v_lshl_add_u64 v[64:65], v[64:65], 1, v[136:137]
	global_store_short v[64:65], v66, off
	v_or_b32_e32 v64, 0x14820, v130
	v_ashrrev_i32_e32 v65, 31, v64
	v_add_f32_e32 v68, v69, v108
	v_lshl_add_u64 v[66:67], v[64:65], 2, v[134:135]
	global_store_dword v[66:67], v68, off
	v_mul_f32_e32 v66, v128, v68
	v_cvt_pk_bf16_f32 v66, v66, s0
	v_lshl_add_u64 v[64:65], v[64:65], 1, v[136:137]
	global_store_short v[64:65], v66, off
	v_or_b32_e32 v64, 0x15020, v130
	v_ashrrev_i32_e32 v65, 31, v64
	v_add_f32_e32 v68, v70, v107
	v_lshl_add_u64 v[66:67], v[64:65], 2, v[134:135]
	global_store_dword v[66:67], v68, off
	v_mul_f32_e32 v66, v128, v68
	v_cvt_pk_bf16_f32 v66, v66, s0
	v_lshl_add_u64 v[64:65], v[64:65], 1, v[136:137]
	global_store_short v[64:65], v66, off
	v_or_b32_e32 v64, 0x15820, v130
	v_ashrrev_i32_e32 v65, 31, v64
	v_add_f32_e32 v68, v71, v106
	v_lshl_add_u64 v[66:67], v[64:65], 2, v[134:135]
	global_store_dword v[66:67], v68, off
	v_mul_f32_e32 v66, v128, v68
	v_cvt_pk_bf16_f32 v66, v66, s0
	v_lshl_add_u64 v[64:65], v[64:65], 1, v[136:137]
	global_store_short v[64:65], v66, off
	v_or_b32_e32 v64, 0x18020, v130
	v_ashrrev_i32_e32 v65, 31, v64
	v_add_f32_e32 v68, v72, v105
	v_lshl_add_u64 v[66:67], v[64:65], 2, v[134:135]
	global_store_dword v[66:67], v68, off
	v_mul_f32_e32 v66, v128, v68
	v_cvt_pk_bf16_f32 v66, v66, s0
	v_lshl_add_u64 v[64:65], v[64:65], 1, v[136:137]
	global_store_short v[64:65], v66, off
	v_or_b32_e32 v64, 0x18820, v130
	v_ashrrev_i32_e32 v65, 31, v64
	v_add_f32_e32 v68, v73, v104
	v_lshl_add_u64 v[66:67], v[64:65], 2, v[134:135]
	global_store_dword v[66:67], v68, off
	v_mul_f32_e32 v66, v128, v68
	v_cvt_pk_bf16_f32 v66, v66, s0
	v_lshl_add_u64 v[64:65], v[64:65], 1, v[136:137]
	global_store_short v[64:65], v66, off
	v_or_b32_e32 v64, 0x19020, v130
	v_ashrrev_i32_e32 v65, 31, v64
	s_waitcnt vmcnt(62)
	v_add_f32_e32 v68, v74, v103
	v_lshl_add_u64 v[66:67], v[64:65], 2, v[134:135]
	global_store_dword v[66:67], v68, off
	v_mul_f32_e32 v66, v128, v68
	v_cvt_pk_bf16_f32 v66, v66, s0
	v_lshl_add_u64 v[64:65], v[64:65], 1, v[136:137]
	global_store_short v[64:65], v66, off
	v_or_b32_e32 v64, 0x19820, v130
	v_ashrrev_i32_e32 v65, 31, v64
	v_add_f32_e32 v68, v75, v102
	v_lshl_add_u64 v[66:67], v[64:65], 2, v[134:135]
	global_store_dword v[66:67], v68, off
	v_mul_f32_e32 v66, v128, v68
	v_cvt_pk_bf16_f32 v66, v66, s0
	v_lshl_add_u64 v[64:65], v[64:65], 1, v[136:137]
	global_store_short v[64:65], v66, off
	v_or_b32_e32 v64, 0x1c020, v130
	v_ashrrev_i32_e32 v65, 31, v64
	v_add_f32_e32 v68, v76, v101
	v_lshl_add_u64 v[66:67], v[64:65], 2, v[134:135]
	global_store_dword v[66:67], v68, off
	v_mul_f32_e32 v66, v128, v68
	v_cvt_pk_bf16_f32 v66, v66, s0
	v_lshl_add_u64 v[64:65], v[64:65], 1, v[136:137]
	global_store_short v[64:65], v66, off
	v_or_b32_e32 v64, 0x1c820, v130
	v_ashrrev_i32_e32 v65, 31, v64
	v_add_f32_e32 v68, v77, v100
	v_lshl_add_u64 v[66:67], v[64:65], 2, v[134:135]
	global_store_dword v[66:67], v68, off
	v_mul_f32_e32 v66, v128, v68
	v_cvt_pk_bf16_f32 v66, v66, s0
	v_lshl_add_u64 v[64:65], v[64:65], 1, v[136:137]
	global_store_short v[64:65], v66, off
	v_or_b32_e32 v64, 0x1d020, v130
	v_ashrrev_i32_e32 v65, 31, v64
	v_add_f32_e32 v68, v78, v99
	v_lshl_add_u64 v[66:67], v[64:65], 2, v[134:135]
	global_store_dword v[66:67], v68, off
	v_mul_f32_e32 v66, v128, v68
	v_cvt_pk_bf16_f32 v66, v66, s0
	v_lshl_add_u64 v[64:65], v[64:65], 1, v[136:137]
	global_store_short v[64:65], v66, off
	v_or_b32_e32 v64, 0x1d820, v130
	v_ashrrev_i32_e32 v65, 31, v64
	v_add_f32_e32 v68, v79, v98
	v_lshl_add_u64 v[66:67], v[64:65], 2, v[134:135]
	global_store_dword v[66:67], v68, off
	v_mul_f32_e32 v66, v128, v68
	v_cvt_pk_bf16_f32 v66, v66, s0
	v_lshl_add_u64 v[64:65], v[64:65], 1, v[136:137]
	global_store_short v[64:65], v66, off
	v_or_b32_e32 v64, 0x20000, v130
	v_ashrrev_i32_e32 v65, 31, v64
	v_lshlrev_b64 v[66:67], 2, v[64:65]
	v_lshl_add_u64 v[68:69], v[132:133], 0, v[66:67]
	s_waitcnt vmcnt(47)
	v_add_f32_e32 v48, v48, v142
	v_lshl_add_u64 v[66:67], v[134:135], 0, v[66:67]
	global_load_dword v102, v[68:69], off offset:128
	global_load_dword v101, v[80:81], off offset:128
	global_load_dword v100, v[82:83], off offset:128
	global_load_dword v99, v[84:85], off offset:128
	global_load_dword v98, v[86:87], off offset:128
	s_nop 0
	global_load_dword v88, v[88:89], off offset:128
	s_nop 0
	global_load_dword v87, v[90:91], off offset:128
	global_load_dword v86, v[92:93], off offset:128
	global_load_dword v85, v[94:95], off offset:128
	global_load_dword v84, v[96:97], off offset:128
	global_load_dword v83, v[114:115], off offset:128
	global_load_dword v82, v[116:117], off offset:128
	global_load_dword v81, v[118:119], off offset:128
	global_load_dword v80, v[120:121], off offset:128
	global_load_dword v79, v[122:123], off offset:128
	global_load_dword v78, v[124:125], off offset:128
	v_lshl_add_u64 v[64:65], v[64:65], 1, v[136:137]
	global_store_dword v[66:67], v48, off
	v_mul_f32_e32 v48, v209, v48
	v_cvt_pk_bf16_f32 v48, v48, s0
	global_store_short v[64:65], v48, off
	v_or_b32_e32 v48, 0x20800, v130
	s_waitcnt vmcnt(62)
	v_add_f32_e32 v66, v49, v143
	v_ashrrev_i32_e32 v49, 31, v48
	v_lshl_add_u64 v[64:65], v[48:49], 2, v[134:135]
	global_store_dword v[64:65], v66, off
	v_mul_f32_e32 v64, v209, v66
	v_cvt_pk_bf16_f32 v64, v64, s0
	v_lshl_add_u64 v[48:49], v[48:49], 1, v[136:137]
	global_store_short v[48:49], v64, off
	v_or_b32_e32 v48, 0x21000, v130
	v_ashrrev_i32_e32 v49, 31, v48
	v_add_f32_e32 v50, v50, v144
	v_lshl_add_u64 v[64:65], v[48:49], 2, v[134:135]
	global_store_dword v[64:65], v50, off
	v_mul_f32_e32 v50, v209, v50
	v_cvt_pk_bf16_f32 v50, v50, s0
	v_lshl_add_u64 v[48:49], v[48:49], 1, v[136:137]
	global_store_short v[48:49], v50, off
	v_or_b32_e32 v48, 0x21800, v130
	v_ashrrev_i32_e32 v49, 31, v48
	v_add_f32_e32 v64, v51, v145
	v_lshl_add_u64 v[50:51], v[48:49], 2, v[134:135]
	global_store_dword v[50:51], v64, off
	v_mul_f32_e32 v50, v209, v64
	v_cvt_pk_bf16_f32 v50, v50, s0
	v_lshl_add_u64 v[48:49], v[48:49], 1, v[136:137]
	global_store_short v[48:49], v50, off
	v_or_b32_e32 v48, 0x24000, v130
	v_ashrrev_i32_e32 v49, 31, v48
	s_waitcnt vmcnt(62)
	v_add_f32_e32 v52, v52, v146
	v_lshl_add_u64 v[50:51], v[48:49], 2, v[134:135]
	global_store_dword v[50:51], v52, off
	v_mul_f32_e32 v50, v209, v52
	v_cvt_pk_bf16_f32 v50, v50, s0
	v_lshl_add_u64 v[48:49], v[48:49], 1, v[136:137]
	global_store_short v[48:49], v50, off
	v_or_b32_e32 v48, 0x24800, v130
	v_ashrrev_i32_e32 v49, 31, v48
	v_add_f32_e32 v52, v53, v147
	v_lshl_add_u64 v[50:51], v[48:49], 2, v[134:135]
	global_store_dword v[50:51], v52, off
	v_mul_f32_e32 v50, v209, v52
	v_cvt_pk_bf16_f32 v50, v50, s0
	v_lshl_add_u64 v[48:49], v[48:49], 1, v[136:137]
	global_store_short v[48:49], v50, off
	v_or_b32_e32 v48, 0x25000, v130
	v_ashrrev_i32_e32 v49, 31, v48
	v_add_f32_e32 v52, v54, v148
	v_lshl_add_u64 v[50:51], v[48:49], 2, v[134:135]
	global_store_dword v[50:51], v52, off
	v_mul_f32_e32 v50, v209, v52
	v_cvt_pk_bf16_f32 v50, v50, s0
	v_lshl_add_u64 v[48:49], v[48:49], 1, v[136:137]
	global_store_short v[48:49], v50, off
	v_or_b32_e32 v48, 0x25800, v130
	v_ashrrev_i32_e32 v49, 31, v48
	v_add_f32_e32 v52, v55, v149
	v_lshl_add_u64 v[50:51], v[48:49], 2, v[134:135]
	global_store_dword v[50:51], v52, off
	v_mul_f32_e32 v50, v209, v52
	v_cvt_pk_bf16_f32 v50, v50, s0
	v_lshl_add_u64 v[48:49], v[48:49], 1, v[136:137]
	global_store_short v[48:49], v50, off
	v_or_b32_e32 v48, 0x28000, v130
	v_ashrrev_i32_e32 v49, 31, v48
	v_add_f32_e32 v52, v56, v150
	v_lshl_add_u64 v[50:51], v[48:49], 2, v[134:135]
	global_store_dword v[50:51], v52, off
	v_mul_f32_e32 v50, v209, v52
	v_cvt_pk_bf16_f32 v50, v50, s0
	v_lshl_add_u64 v[48:49], v[48:49], 1, v[136:137]
	global_store_short v[48:49], v50, off
	v_or_b32_e32 v48, 0x28800, v130
	v_ashrrev_i32_e32 v49, 31, v48
	v_add_f32_e32 v52, v57, v151
	v_lshl_add_u64 v[50:51], v[48:49], 2, v[134:135]
	global_store_dword v[50:51], v52, off
	v_mul_f32_e32 v50, v209, v52
	v_cvt_pk_bf16_f32 v50, v50, s0
	v_lshl_add_u64 v[48:49], v[48:49], 1, v[136:137]
	global_store_short v[48:49], v50, off
	v_or_b32_e32 v48, 0x29000, v130
	v_ashrrev_i32_e32 v49, 31, v48
	s_waitcnt vmcnt(62)
	v_add_f32_e32 v52, v58, v152
	v_lshl_add_u64 v[50:51], v[48:49], 2, v[134:135]
	global_store_dword v[50:51], v52, off
	v_mul_f32_e32 v50, v209, v52
	v_cvt_pk_bf16_f32 v50, v50, s0
	v_lshl_add_u64 v[48:49], v[48:49], 1, v[136:137]
	global_store_short v[48:49], v50, off
	v_or_b32_e32 v48, 0x29800, v130
	v_ashrrev_i32_e32 v49, 31, v48
	v_add_f32_e32 v52, v59, v153
	v_lshl_add_u64 v[50:51], v[48:49], 2, v[134:135]
	global_store_dword v[50:51], v52, off
	v_mul_f32_e32 v50, v209, v52
	v_cvt_pk_bf16_f32 v50, v50, s0
	v_lshl_add_u64 v[48:49], v[48:49], 1, v[136:137]
	global_store_short v[48:49], v50, off
	v_or_b32_e32 v48, 0x2c000, v130
	v_ashrrev_i32_e32 v49, 31, v48
	v_add_f32_e32 v52, v60, v154
	v_lshl_add_u64 v[50:51], v[48:49], 2, v[134:135]
	global_store_dword v[50:51], v52, off
	v_mul_f32_e32 v50, v209, v52
	v_cvt_pk_bf16_f32 v50, v50, s0
	v_lshl_add_u64 v[48:49], v[48:49], 1, v[136:137]
	global_store_short v[48:49], v50, off
	v_or_b32_e32 v48, 0x2c800, v130
	v_ashrrev_i32_e32 v49, 31, v48
	v_add_f32_e32 v52, v61, v155
	v_lshl_add_u64 v[50:51], v[48:49], 2, v[134:135]
	global_store_dword v[50:51], v52, off
	v_mul_f32_e32 v50, v209, v52
	v_cvt_pk_bf16_f32 v50, v50, s0
	v_lshl_add_u64 v[48:49], v[48:49], 1, v[136:137]
	global_store_short v[48:49], v50, off
	v_or_b32_e32 v48, 0x2d000, v130
	v_ashrrev_i32_e32 v49, 31, v48
	v_add_f32_e32 v52, v62, v156
	v_lshl_add_u64 v[50:51], v[48:49], 2, v[134:135]
	global_store_dword v[50:51], v52, off
	v_mul_f32_e32 v50, v209, v52
	v_cvt_pk_bf16_f32 v50, v50, s0
	v_lshl_add_u64 v[48:49], v[48:49], 1, v[136:137]
	global_store_short v[48:49], v50, off
	v_or_b32_e32 v48, 0x2d800, v130
	v_ashrrev_i32_e32 v49, 31, v48
	v_add_f32_e32 v52, v63, v157
	v_lshl_add_u64 v[50:51], v[48:49], 2, v[134:135]
	global_store_dword v[50:51], v52, off
	v_mul_f32_e32 v50, v209, v52
	v_cvt_pk_bf16_f32 v50, v50, s0
	v_lshl_add_u64 v[48:49], v[48:49], 1, v[136:137]
	s_mov_b32 s22, 0xc0000
	global_store_short v[48:49], v50, off
	v_add_co_u32_e32 v48, vcc, s22, v138
	s_mov_b32 s22, 0xc2000
	s_nop 0
	v_addc_co_u32_e32 v49, vcc, 0, v139, vcc
	global_load_dword v89, v[48:49], off
	v_add_co_u32_e32 v48, vcc, s22, v138
	v_or_b32_e32 v110, 0x20020, v130
	s_nop 0
	v_addc_co_u32_e32 v49, vcc, 0, v139, vcc
	v_add_co_u32_e32 v50, vcc, s76, v138
	v_ashrrev_i32_e32 v111, 31, v110
	s_nop 0
	v_addc_co_u32_e32 v51, vcc, 0, v139, vcc
	v_add_co_u32_e32 v52, vcc, s77, v138
	s_waitcnt vmcnt(48)
	v_add_f32_e32 v32, v32, v102
	v_addc_co_u32_e32 v53, vcc, 0, v139, vcc
	v_add_co_u32_e32 v54, vcc, s78, v138
	v_lshl_add_u64 v[112:113], v[110:111], 2, v[134:135]
	s_nop 0
	v_addc_co_u32_e32 v55, vcc, 0, v139, vcc
	v_add_co_u32_e32 v56, vcc, s79, v138
	global_load_dword v90, v[48:49], off
	global_load_dword v91, v[50:51], off
	global_load_dword v92, v[52:53], off
	global_load_dword v93, v[54:55], off
	v_addc_co_u32_e32 v57, vcc, 0, v139, vcc
	v_add_co_u32_e32 v58, vcc, s80, v138
	global_load_dword v94, v[56:57], off
	s_nop 0
	v_addc_co_u32_e32 v59, vcc, 0, v139, vcc
	v_add_co_u32_e32 v60, vcc, s81, v138
	global_load_dword v95, v[58:59], off
	s_nop 0
	v_addc_co_u32_e32 v61, vcc, 0, v139, vcc
	v_add_co_u32_e32 v62, vcc, s82, v138
	global_load_dword v96, v[60:61], off
	s_nop 0
	v_addc_co_u32_e32 v63, vcc, 0, v139, vcc
	v_add_co_u32_e32 v64, vcc, s83, v138
	global_load_dword v97, v[62:63], off
	s_nop 0
	v_addc_co_u32_e32 v65, vcc, 0, v139, vcc
	v_add_co_u32_e32 v66, vcc, s84, v138
	global_load_dword v103, v[64:65], off
	s_nop 0
	v_addc_co_u32_e32 v67, vcc, 0, v139, vcc
	v_add_co_u32_e32 v68, vcc, s85, v138
	global_load_dword v104, v[66:67], off
	s_nop 0
	v_addc_co_u32_e32 v69, vcc, 0, v139, vcc
	v_add_co_u32_e32 v70, vcc, s86, v138
	global_load_dword v105, v[68:69], off
	s_nop 0
	v_addc_co_u32_e32 v71, vcc, 0, v139, vcc
	v_add_co_u32_e32 v72, vcc, s87, v138
	global_load_dword v106, v[70:71], off
	s_nop 0
	v_addc_co_u32_e32 v73, vcc, 0, v139, vcc
	v_add_co_u32_e32 v74, vcc, s88, v138
	global_load_dword v107, v[72:73], off
	s_nop 0
	v_addc_co_u32_e32 v75, vcc, 0, v139, vcc
	v_add_co_u32_e32 v76, vcc, s89, v138
	global_load_dword v108, v[74:75], off
	s_nop 0
	v_addc_co_u32_e32 v77, vcc, 0, v139, vcc
	global_load_dword v109, v[76:77], off
	v_lshl_add_u64 v[110:111], v[110:111], 1, v[136:137]
	global_store_dword v[112:113], v32, off
	v_mul_f32_e32 v32, v128, v32
	v_cvt_pk_bf16_f32 v32, v32, s0
	global_store_short v[110:111], v32, off
	v_or_b32_e32 v32, 0x20820, v130
	s_waitcnt vmcnt(62)
	v_add_f32_e32 v101, v33, v101
	v_ashrrev_i32_e32 v33, 31, v32
	v_lshl_add_u64 v[110:111], v[32:33], 2, v[134:135]
	global_store_dword v[110:111], v101, off
	v_mul_f32_e32 v101, v128, v101
	v_cvt_pk_bf16_f32 v101, v101, s0
	v_lshl_add_u64 v[32:33], v[32:33], 1, v[136:137]
	global_store_short v[32:33], v101, off
	v_or_b32_e32 v32, 0x21020, v130
	v_ashrrev_i32_e32 v33, 31, v32
	v_add_f32_e32 v34, v34, v100
	v_lshl_add_u64 v[100:101], v[32:33], 2, v[134:135]
	global_store_dword v[100:101], v34, off
	v_mul_f32_e32 v34, v128, v34
	v_cvt_pk_bf16_f32 v34, v34, s0
	v_lshl_add_u64 v[32:33], v[32:33], 1, v[136:137]
	global_store_short v[32:33], v34, off
	v_or_b32_e32 v32, 0x21820, v130
	v_ashrrev_i32_e32 v33, 31, v32
	v_add_f32_e32 v99, v35, v99
	v_lshl_add_u64 v[34:35], v[32:33], 2, v[134:135]
	global_store_dword v[34:35], v99, off
	v_mul_f32_e32 v34, v128, v99
	v_cvt_pk_bf16_f32 v34, v34, s0
	v_lshl_add_u64 v[32:33], v[32:33], 1, v[136:137]
	global_store_short v[32:33], v34, off
	v_or_b32_e32 v32, 0x24020, v130
	v_ashrrev_i32_e32 v33, 31, v32
	s_waitcnt vmcnt(62)
	v_add_f32_e32 v36, v36, v98
	v_lshl_add_u64 v[34:35], v[32:33], 2, v[134:135]
	global_store_dword v[34:35], v36, off
	v_mul_f32_e32 v34, v128, v36
	v_cvt_pk_bf16_f32 v34, v34, s0
	v_lshl_add_u64 v[32:33], v[32:33], 1, v[136:137]
	global_store_short v[32:33], v34, off
	v_or_b32_e32 v32, 0x24820, v130
	v_ashrrev_i32_e32 v33, 31, v32
	v_add_f32_e32 v36, v37, v88
	v_lshl_add_u64 v[34:35], v[32:33], 2, v[134:135]
	global_store_dword v[34:35], v36, off
	v_mul_f32_e32 v34, v128, v36
	v_cvt_pk_bf16_f32 v34, v34, s0
	v_lshl_add_u64 v[32:33], v[32:33], 1, v[136:137]
	global_store_short v[32:33], v34, off
	v_or_b32_e32 v32, 0x25020, v130
	v_ashrrev_i32_e32 v33, 31, v32
	v_add_f32_e32 v36, v38, v87
	v_lshl_add_u64 v[34:35], v[32:33], 2, v[134:135]
	global_store_dword v[34:35], v36, off
	v_mul_f32_e32 v34, v128, v36
	v_cvt_pk_bf16_f32 v34, v34, s0
	v_lshl_add_u64 v[32:33], v[32:33], 1, v[136:137]
	global_store_short v[32:33], v34, off
	v_or_b32_e32 v32, 0x25820, v130
	v_ashrrev_i32_e32 v33, 31, v32
	v_add_f32_e32 v36, v39, v86
	v_lshl_add_u64 v[34:35], v[32:33], 2, v[134:135]
	global_store_dword v[34:35], v36, off
	v_mul_f32_e32 v34, v128, v36
	v_cvt_pk_bf16_f32 v34, v34, s0
	v_lshl_add_u64 v[32:33], v[32:33], 1, v[136:137]
	global_store_short v[32:33], v34, off
	v_or_b32_e32 v32, 0x28020, v130
	v_ashrrev_i32_e32 v33, 31, v32
	v_add_f32_e32 v36, v40, v85
	v_lshl_add_u64 v[34:35], v[32:33], 2, v[134:135]
	global_store_dword v[34:35], v36, off
	v_mul_f32_e32 v34, v128, v36
	v_cvt_pk_bf16_f32 v34, v34, s0
	v_lshl_add_u64 v[32:33], v[32:33], 1, v[136:137]
	global_store_short v[32:33], v34, off
	v_or_b32_e32 v32, 0x28820, v130
	v_ashrrev_i32_e32 v33, 31, v32
	v_add_f32_e32 v36, v41, v84
	v_lshl_add_u64 v[34:35], v[32:33], 2, v[134:135]
	global_store_dword v[34:35], v36, off
	v_mul_f32_e32 v34, v128, v36
	v_cvt_pk_bf16_f32 v34, v34, s0
	v_lshl_add_u64 v[32:33], v[32:33], 1, v[136:137]
	global_store_short v[32:33], v34, off
	v_or_b32_e32 v32, 0x29020, v130
	v_ashrrev_i32_e32 v33, 31, v32
	s_waitcnt vmcnt(62)
	v_add_f32_e32 v36, v42, v83
	v_lshl_add_u64 v[34:35], v[32:33], 2, v[134:135]
	global_store_dword v[34:35], v36, off
	v_mul_f32_e32 v34, v128, v36
	v_cvt_pk_bf16_f32 v34, v34, s0
	v_lshl_add_u64 v[32:33], v[32:33], 1, v[136:137]
	global_store_short v[32:33], v34, off
	v_or_b32_e32 v32, 0x29820, v130
	v_ashrrev_i32_e32 v33, 31, v32
	v_add_f32_e32 v36, v43, v82
	v_lshl_add_u64 v[34:35], v[32:33], 2, v[134:135]
	global_store_dword v[34:35], v36, off
	v_mul_f32_e32 v34, v128, v36
	v_cvt_pk_bf16_f32 v34, v34, s0
	v_lshl_add_u64 v[32:33], v[32:33], 1, v[136:137]
	global_store_short v[32:33], v34, off
	v_or_b32_e32 v32, 0x2c020, v130
	v_ashrrev_i32_e32 v33, 31, v32
	v_add_f32_e32 v36, v44, v81
	v_lshl_add_u64 v[34:35], v[32:33], 2, v[134:135]
	global_store_dword v[34:35], v36, off
	v_mul_f32_e32 v34, v128, v36
	v_cvt_pk_bf16_f32 v34, v34, s0
	v_lshl_add_u64 v[32:33], v[32:33], 1, v[136:137]
	global_store_short v[32:33], v34, off
	v_or_b32_e32 v32, 0x2c820, v130
	v_ashrrev_i32_e32 v33, 31, v32
	v_add_f32_e32 v36, v45, v80
	v_lshl_add_u64 v[34:35], v[32:33], 2, v[134:135]
	global_store_dword v[34:35], v36, off
	v_mul_f32_e32 v34, v128, v36
	v_cvt_pk_bf16_f32 v34, v34, s0
	v_lshl_add_u64 v[32:33], v[32:33], 1, v[136:137]
	global_store_short v[32:33], v34, off
	v_or_b32_e32 v32, 0x2d020, v130
	v_ashrrev_i32_e32 v33, 31, v32
	v_add_f32_e32 v36, v46, v79
	v_lshl_add_u64 v[34:35], v[32:33], 2, v[134:135]
	global_store_dword v[34:35], v36, off
	v_mul_f32_e32 v34, v128, v36
	v_cvt_pk_bf16_f32 v34, v34, s0
	v_lshl_add_u64 v[32:33], v[32:33], 1, v[136:137]
	global_store_short v[32:33], v34, off
	v_or_b32_e32 v32, 0x2d820, v130
	v_ashrrev_i32_e32 v33, 31, v32
	v_add_f32_e32 v36, v47, v78
	v_lshl_add_u64 v[34:35], v[32:33], 2, v[134:135]
	global_store_dword v[34:35], v36, off
	v_mul_f32_e32 v34, v128, v36
	v_cvt_pk_bf16_f32 v34, v34, s0
	v_lshl_add_u64 v[32:33], v[32:33], 1, v[136:137]
	global_store_short v[32:33], v34, off
	v_or_b32_e32 v32, 0x30000, v130
	v_ashrrev_i32_e32 v33, 31, v32
	v_lshlrev_b64 v[34:35], 2, v[32:33]
	v_lshl_add_u64 v[36:37], v[132:133], 0, v[34:35]
	s_waitcnt vmcnt(47)
	v_add_f32_e32 v16, v16, v89
	v_lshl_add_u64 v[34:35], v[134:135], 0, v[34:35]
	global_load_dword v36, v[36:37], off offset:128
	s_nop 0
	global_load_dword v37, v[48:49], off offset:128
	global_load_dword v38, v[50:51], off offset:128
	global_load_dword v39, v[52:53], off offset:128
	global_load_dword v40, v[54:55], off offset:128
	global_load_dword v41, v[56:57], off offset:128
	global_load_dword v42, v[58:59], off offset:128
	global_load_dword v43, v[60:61], off offset:128
	global_load_dword v44, v[62:63], off offset:128
	global_load_dword v45, v[64:65], off offset:128
	global_load_dword v46, v[66:67], off offset:128
	global_load_dword v47, v[68:69], off offset:128
	global_load_dword v48, v[70:71], off offset:128
	global_load_dword v49, v[72:73], off offset:128
	global_load_dword v50, v[74:75], off offset:128
	global_load_dword v51, v[76:77], off offset:128
	v_lshl_add_u64 v[32:33], v[32:33], 1, v[136:137]
	global_store_dword v[34:35], v16, off
	v_mul_f32_e32 v16, v209, v16
	v_cvt_pk_bf16_f32 v16, v16, s0
	global_store_short v[32:33], v16, off
	v_or_b32_e32 v16, 0x30800, v130
	s_waitcnt vmcnt(62)
	v_add_f32_e32 v34, v17, v90
	v_ashrrev_i32_e32 v17, 31, v16
	v_lshl_add_u64 v[32:33], v[16:17], 2, v[134:135]
	global_store_dword v[32:33], v34, off
	v_mul_f32_e32 v32, v209, v34
	v_cvt_pk_bf16_f32 v32, v32, s0
	v_lshl_add_u64 v[16:17], v[16:17], 1, v[136:137]
	global_store_short v[16:17], v32, off
	v_or_b32_e32 v16, 0x31000, v130
	v_ashrrev_i32_e32 v17, 31, v16
	v_add_f32_e32 v18, v18, v91
	v_lshl_add_u64 v[32:33], v[16:17], 2, v[134:135]
	global_store_dword v[32:33], v18, off
	v_mul_f32_e32 v18, v209, v18
	v_cvt_pk_bf16_f32 v18, v18, s0
	v_lshl_add_u64 v[16:17], v[16:17], 1, v[136:137]
	global_store_short v[16:17], v18, off
	v_or_b32_e32 v16, 0x31800, v130
	v_ashrrev_i32_e32 v17, 31, v16
	v_add_f32_e32 v32, v19, v92
	v_lshl_add_u64 v[18:19], v[16:17], 2, v[134:135]
	global_store_dword v[18:19], v32, off
	v_mul_f32_e32 v18, v209, v32
	v_cvt_pk_bf16_f32 v18, v18, s0
	v_lshl_add_u64 v[16:17], v[16:17], 1, v[136:137]
	global_store_short v[16:17], v18, off
	v_or_b32_e32 v16, 0x34000, v130
	v_ashrrev_i32_e32 v17, 31, v16
	s_waitcnt vmcnt(62)
	v_add_f32_e32 v20, v20, v93
	v_lshl_add_u64 v[18:19], v[16:17], 2, v[134:135]
	global_store_dword v[18:19], v20, off
	v_mul_f32_e32 v18, v209, v20
	v_cvt_pk_bf16_f32 v18, v18, s0
	v_lshl_add_u64 v[16:17], v[16:17], 1, v[136:137]
	global_store_short v[16:17], v18, off
	v_or_b32_e32 v16, 0x34800, v130
	v_ashrrev_i32_e32 v17, 31, v16
	v_add_f32_e32 v20, v21, v94
	v_lshl_add_u64 v[18:19], v[16:17], 2, v[134:135]
	global_store_dword v[18:19], v20, off
	v_mul_f32_e32 v18, v209, v20
	v_cvt_pk_bf16_f32 v18, v18, s0
	v_lshl_add_u64 v[16:17], v[16:17], 1, v[136:137]
	global_store_short v[16:17], v18, off
	v_or_b32_e32 v16, 0x35000, v130
	v_ashrrev_i32_e32 v17, 31, v16
	v_add_f32_e32 v20, v22, v95
	v_lshl_add_u64 v[18:19], v[16:17], 2, v[134:135]
	global_store_dword v[18:19], v20, off
	v_mul_f32_e32 v18, v209, v20
	v_cvt_pk_bf16_f32 v18, v18, s0
	v_lshl_add_u64 v[16:17], v[16:17], 1, v[136:137]
	global_store_short v[16:17], v18, off
	v_or_b32_e32 v16, 0x35800, v130
	v_ashrrev_i32_e32 v17, 31, v16
	v_add_f32_e32 v20, v23, v96
	v_lshl_add_u64 v[18:19], v[16:17], 2, v[134:135]
	global_store_dword v[18:19], v20, off
	v_mul_f32_e32 v18, v209, v20
	v_cvt_pk_bf16_f32 v18, v18, s0
	v_lshl_add_u64 v[16:17], v[16:17], 1, v[136:137]
	global_store_short v[16:17], v18, off
	v_or_b32_e32 v16, 0x38000, v130
	v_ashrrev_i32_e32 v17, 31, v16
	v_add_f32_e32 v20, v24, v97
	v_lshl_add_u64 v[18:19], v[16:17], 2, v[134:135]
	global_store_dword v[18:19], v20, off
	v_mul_f32_e32 v18, v209, v20
	v_cvt_pk_bf16_f32 v18, v18, s0
	v_lshl_add_u64 v[16:17], v[16:17], 1, v[136:137]
	global_store_short v[16:17], v18, off
	v_or_b32_e32 v16, 0x38800, v130
	v_ashrrev_i32_e32 v17, 31, v16
	v_add_f32_e32 v20, v25, v103
	v_lshl_add_u64 v[18:19], v[16:17], 2, v[134:135]
	global_store_dword v[18:19], v20, off
	v_mul_f32_e32 v18, v209, v20
	v_cvt_pk_bf16_f32 v18, v18, s0
	v_lshl_add_u64 v[16:17], v[16:17], 1, v[136:137]
	global_store_short v[16:17], v18, off
	v_or_b32_e32 v16, 0x39000, v130
	v_ashrrev_i32_e32 v17, 31, v16
	s_waitcnt vmcnt(62)
	v_add_f32_e32 v20, v26, v104
	v_lshl_add_u64 v[18:19], v[16:17], 2, v[134:135]
	global_store_dword v[18:19], v20, off
	v_mul_f32_e32 v18, v209, v20
	v_cvt_pk_bf16_f32 v18, v18, s0
	v_lshl_add_u64 v[16:17], v[16:17], 1, v[136:137]
	global_store_short v[16:17], v18, off
	v_or_b32_e32 v16, 0x39800, v130
	v_ashrrev_i32_e32 v17, 31, v16
	v_add_f32_e32 v20, v27, v105
	v_lshl_add_u64 v[18:19], v[16:17], 2, v[134:135]
	global_store_dword v[18:19], v20, off
	v_mul_f32_e32 v18, v209, v20
	v_cvt_pk_bf16_f32 v18, v18, s0
	v_lshl_add_u64 v[16:17], v[16:17], 1, v[136:137]
	global_store_short v[16:17], v18, off
	v_or_b32_e32 v16, 0x3c000, v130
	v_ashrrev_i32_e32 v17, 31, v16
	v_add_f32_e32 v20, v28, v106
	v_lshl_add_u64 v[18:19], v[16:17], 2, v[134:135]
	global_store_dword v[18:19], v20, off
	v_mul_f32_e32 v18, v209, v20
	v_cvt_pk_bf16_f32 v18, v18, s0
	v_lshl_add_u64 v[16:17], v[16:17], 1, v[136:137]
	global_store_short v[16:17], v18, off
	v_or_b32_e32 v16, 0x3c800, v130
	v_ashrrev_i32_e32 v17, 31, v16
	v_add_f32_e32 v20, v29, v107
	v_lshl_add_u64 v[18:19], v[16:17], 2, v[134:135]
	global_store_dword v[18:19], v20, off
	v_mul_f32_e32 v18, v209, v20
	v_cvt_pk_bf16_f32 v18, v18, s0
	v_lshl_add_u64 v[16:17], v[16:17], 1, v[136:137]
	global_store_short v[16:17], v18, off
	v_or_b32_e32 v16, 0x3d000, v130
	v_ashrrev_i32_e32 v17, 31, v16
	v_add_f32_e32 v20, v30, v108
	v_lshl_add_u64 v[18:19], v[16:17], 2, v[134:135]
	global_store_dword v[18:19], v20, off
	v_mul_f32_e32 v18, v209, v20
	v_cvt_pk_bf16_f32 v18, v18, s0
	v_lshl_add_u64 v[16:17], v[16:17], 1, v[136:137]
	global_store_short v[16:17], v18, off
	v_or_b32_e32 v16, 0x3d800, v130
	v_ashrrev_i32_e32 v17, 31, v16
	v_add_f32_e32 v20, v31, v109
	v_lshl_add_u64 v[18:19], v[16:17], 2, v[134:135]
	global_store_dword v[18:19], v20, off
	v_mul_f32_e32 v18, v209, v20
	v_cvt_pk_bf16_f32 v18, v18, s0
	v_lshl_add_u64 v[16:17], v[16:17], 1, v[136:137]
	global_store_short v[16:17], v18, off
	v_or_b32_e32 v16, 0x30020, v130
	v_ashrrev_i32_e32 v17, 31, v16
	s_waitcnt vmcnt(47)
	v_add_f32_e32 v0, v0, v36
	v_lshl_add_u64 v[18:19], v[16:17], 2, v[134:135]
	global_store_dword v[18:19], v0, off
	v_mul_f32_e32 v0, v128, v0
	v_cvt_pk_bf16_f32 v0, v0, s0
	v_lshl_add_u64 v[16:17], v[16:17], 1, v[136:137]
	global_store_short v[16:17], v0, off
	v_or_b32_e32 v0, 0x30820, v130
	s_waitcnt vmcnt(48)
	v_add_f32_e32 v18, v1, v37
	v_ashrrev_i32_e32 v1, 31, v0
	v_lshl_add_u64 v[16:17], v[0:1], 2, v[134:135]
	global_store_dword v[16:17], v18, off
	v_mul_f32_e32 v16, v128, v18
	v_cvt_pk_bf16_f32 v16, v16, s0
	v_lshl_add_u64 v[0:1], v[0:1], 1, v[136:137]
	global_store_short v[0:1], v16, off
	v_or_b32_e32 v0, 0x31020, v130
	v_ashrrev_i32_e32 v1, 31, v0
	s_waitcnt vmcnt(49)
	v_add_f32_e32 v2, v2, v38
	v_lshl_add_u64 v[16:17], v[0:1], 2, v[134:135]
	global_store_dword v[16:17], v2, off
	v_mul_f32_e32 v2, v128, v2
	v_cvt_pk_bf16_f32 v2, v2, s0
	v_lshl_add_u64 v[0:1], v[0:1], 1, v[136:137]
	global_store_short v[0:1], v2, off
	v_or_b32_e32 v0, 0x31820, v130
	v_ashrrev_i32_e32 v1, 31, v0
	s_waitcnt vmcnt(50)
	v_add_f32_e32 v16, v3, v39
	v_lshl_add_u64 v[2:3], v[0:1], 2, v[134:135]
	global_store_dword v[2:3], v16, off
	v_mul_f32_e32 v2, v128, v16
	v_cvt_pk_bf16_f32 v2, v2, s0
	v_lshl_add_u64 v[0:1], v[0:1], 1, v[136:137]
	global_store_short v[0:1], v2, off
	v_or_b32_e32 v0, 0x34020, v130
	v_ashrrev_i32_e32 v1, 31, v0
	s_waitcnt vmcnt(51)
	v_add_f32_e32 v4, v4, v40
	v_lshl_add_u64 v[2:3], v[0:1], 2, v[134:135]
	global_store_dword v[2:3], v4, off
	v_mul_f32_e32 v2, v128, v4
	v_cvt_pk_bf16_f32 v2, v2, s0
	v_lshl_add_u64 v[0:1], v[0:1], 1, v[136:137]
	global_store_short v[0:1], v2, off
	v_or_b32_e32 v0, 0x34820, v130
	v_ashrrev_i32_e32 v1, 31, v0
	s_waitcnt vmcnt(52)
	v_add_f32_e32 v4, v5, v41
	v_lshl_add_u64 v[2:3], v[0:1], 2, v[134:135]
	global_store_dword v[2:3], v4, off
	v_mul_f32_e32 v2, v128, v4
	v_cvt_pk_bf16_f32 v2, v2, s0
	v_lshl_add_u64 v[0:1], v[0:1], 1, v[136:137]
	global_store_short v[0:1], v2, off
	v_or_b32_e32 v0, 0x35020, v130
	v_ashrrev_i32_e32 v1, 31, v0
	s_waitcnt vmcnt(53)
	v_add_f32_e32 v4, v6, v42
	v_lshl_add_u64 v[2:3], v[0:1], 2, v[134:135]
	global_store_dword v[2:3], v4, off
	v_mul_f32_e32 v2, v128, v4
	v_cvt_pk_bf16_f32 v2, v2, s0
	v_lshl_add_u64 v[0:1], v[0:1], 1, v[136:137]
	global_store_short v[0:1], v2, off
	v_or_b32_e32 v0, 0x35820, v130
	v_ashrrev_i32_e32 v1, 31, v0
	s_waitcnt vmcnt(54)
	v_add_f32_e32 v4, v7, v43
	v_lshl_add_u64 v[2:3], v[0:1], 2, v[134:135]
	global_store_dword v[2:3], v4, off
	v_mul_f32_e32 v2, v128, v4
	v_cvt_pk_bf16_f32 v2, v2, s0
	v_lshl_add_u64 v[0:1], v[0:1], 1, v[136:137]
	global_store_short v[0:1], v2, off
	v_or_b32_e32 v0, 0x38020, v130
	v_ashrrev_i32_e32 v1, 31, v0
	s_waitcnt vmcnt(55)
	v_add_f32_e32 v4, v8, v44
	v_lshl_add_u64 v[2:3], v[0:1], 2, v[134:135]
	global_store_dword v[2:3], v4, off
	v_mul_f32_e32 v2, v128, v4
	v_cvt_pk_bf16_f32 v2, v2, s0
	v_lshl_add_u64 v[0:1], v[0:1], 1, v[136:137]
	global_store_short v[0:1], v2, off
	v_or_b32_e32 v0, 0x38820, v130
	v_ashrrev_i32_e32 v1, 31, v0
	s_waitcnt vmcnt(56)
	v_add_f32_e32 v4, v9, v45
	v_lshl_add_u64 v[2:3], v[0:1], 2, v[134:135]
	global_store_dword v[2:3], v4, off
	v_mul_f32_e32 v2, v128, v4
	v_cvt_pk_bf16_f32 v2, v2, s0
	v_lshl_add_u64 v[0:1], v[0:1], 1, v[136:137]
	global_store_short v[0:1], v2, off
	v_or_b32_e32 v0, 0x39020, v130
	v_ashrrev_i32_e32 v1, 31, v0
	s_waitcnt vmcnt(57)
	v_add_f32_e32 v4, v10, v46
	v_lshl_add_u64 v[2:3], v[0:1], 2, v[134:135]
	global_store_dword v[2:3], v4, off
	v_mul_f32_e32 v2, v128, v4
	v_cvt_pk_bf16_f32 v2, v2, s0
	v_lshl_add_u64 v[0:1], v[0:1], 1, v[136:137]
	global_store_short v[0:1], v2, off
	v_or_b32_e32 v0, 0x39820, v130
	v_ashrrev_i32_e32 v1, 31, v0
	s_waitcnt vmcnt(58)
	v_add_f32_e32 v4, v11, v47
	v_lshl_add_u64 v[2:3], v[0:1], 2, v[134:135]
	global_store_dword v[2:3], v4, off
	v_mul_f32_e32 v2, v128, v4
	v_cvt_pk_bf16_f32 v2, v2, s0
	v_lshl_add_u64 v[0:1], v[0:1], 1, v[136:137]
	global_store_short v[0:1], v2, off
	v_or_b32_e32 v0, 0x3c020, v130
	v_ashrrev_i32_e32 v1, 31, v0
	s_waitcnt vmcnt(59)
	v_add_f32_e32 v4, v12, v48
	v_lshl_add_u64 v[2:3], v[0:1], 2, v[134:135]
	global_store_dword v[2:3], v4, off
	v_mul_f32_e32 v2, v128, v4
	v_cvt_pk_bf16_f32 v2, v2, s0
	v_lshl_add_u64 v[0:1], v[0:1], 1, v[136:137]
	global_store_short v[0:1], v2, off
	v_or_b32_e32 v0, 0x3c820, v130
	v_ashrrev_i32_e32 v1, 31, v0
	s_waitcnt vmcnt(60)
	v_add_f32_e32 v4, v13, v49
	v_lshl_add_u64 v[2:3], v[0:1], 2, v[134:135]
	global_store_dword v[2:3], v4, off
	v_mul_f32_e32 v2, v128, v4
	v_cvt_pk_bf16_f32 v2, v2, s0
	v_lshl_add_u64 v[0:1], v[0:1], 1, v[136:137]
	global_store_short v[0:1], v2, off
	v_or_b32_e32 v0, 0x3d020, v130
	v_ashrrev_i32_e32 v1, 31, v0
	s_waitcnt vmcnt(61)
	v_add_f32_e32 v4, v14, v50
	v_lshl_add_u64 v[2:3], v[0:1], 2, v[134:135]
	global_store_dword v[2:3], v4, off
	v_mul_f32_e32 v2, v128, v4
	v_cvt_pk_bf16_f32 v2, v2, s0
	v_lshl_add_u64 v[0:1], v[0:1], 1, v[136:137]
	global_store_short v[0:1], v2, off
	v_or_b32_e32 v0, 0x3d820, v130
	v_ashrrev_i32_e32 v1, 31, v0
	s_waitcnt vmcnt(62)
	v_add_f32_e32 v4, v15, v51
	v_lshl_add_u64 v[2:3], v[0:1], 2, v[134:135]
	global_store_dword v[2:3], v4, off
	v_mul_f32_e32 v2, v128, v4
	v_cvt_pk_bf16_f32 v2, v2, s0
	v_lshl_add_u64 v[0:1], v[0:1], 1, v[136:137]
	global_store_short v[0:1], v2, off
	v_add_u32_e32 v206, s46, v206
	v_add_u32_e32 v208, s46, v208
	v_cmp_le_i32_e64 s[40:41], s51, v206
	s_and_b64 vcc, exec, s[40:41]
	s_cbranch_vccz .LBB0_707

.LBB0_715:
	s_add_i32 s16, s22, s33
	s_cmpk_gt_i32 s16, 0x7f
	s_mov_b64 s[30:31], -1
	s_cbranch_scc1 .LBB0_714
	s_ashr_i32 s30, s16, 31
	s_lshr_b32 s30, s30, 25
	s_add_i32 s30, s16, s30
	s_ashr_i32 s61, s30, 7
	s_and_b32 s30, s30, 0xffffff80
	s_lshl_b32 s31, s61, 3
	s_sub_i32 s30, s16, s30
	s_sub_i32 s34, 8, s31
	s_cmpk_gt_i32 s16, 0x7f
	s_cselect_b32 s16, s34, 8
	s_abs_i32 s34, s16
	v_cvt_f32_u32_e32 v0, s34
	s_sub_i32 s41, 0, s34
	s_abs_i32 s35, s30
	s_xor_b32 s40, s30, s16
	v_rcp_iflag_f32_e32 v0, v0
	s_ashr_i32 s40, s40, 31
	v_mov_b32_e32 v10, v204
	v_mul_f32_e32 v0, 0x4f7ffffe, v0
	v_cvt_u32_f32_e32 v0, v0
	v_ashrrev_i32_e32 v1, 6, v10
	v_lshlrev_b32_e32 v3, 9, v10
	v_and_b32_e32 v3, 0x7800, v3
	v_readfirstlane_b32 s42, v0
	s_mul_i32 s41, s41, s42
	s_mul_hi_u32 s41, s42, s41
	s_add_i32 s42, s42, s41
	s_mul_hi_u32 s41, s35, s42
	s_mul_i32 s42, s41, s34
	s_sub_i32 s35, s35, s42
	s_add_i32 s43, s41, 1
	s_sub_i32 s42, s35, s34
	s_cmp_ge_u32 s35, s34
	s_cselect_b32 s41, s43, s41
	s_cselect_b32 s35, s42, s35
	s_add_i32 s42, s41, 1
	s_cmp_ge_u32 s35, s34
	s_cselect_b32 s34, s42, s41
	s_xor_b32 s34, s34, s40
	s_sub_i32 s34, s34, s40
	s_mul_i32 s62, s16, s34
	s_sub_i32 s55, s30, s62
	s_add_i32 s55, s55, s31
	s_lshl_b32 s16, s55, 6
	s_add_i32 s40, s16, 0x2000
	s_ashr_i32 s41, s40, 31
	v_bfe_u32 v0, v10, 4, 2
	s_lshl_b64 s[30:31], s[40:41], 11
	s_lshl_b64 s[40:41], s[40:41], 12
	v_bitop3_b32 v0, v0, v10, 3 bitop3:0x78
	s_add_u32 s40, s50, s40
	v_lshlrev_b32_e32 v2, 3, v0
	v_lshlrev_b32_e32 v0, 15, v1
	v_lshlrev_b32_e32 v4, 16, v1
	v_lshlrev_b32_e32 v1, 10, v1
	s_addc_u32 s41, s51, s41
	s_ashr_i32 s35, s34, 31
	v_or3_b32 v0, v3, v0, v2
	v_add_u32_e32 v40, 32, v1
	s_lshl_b64 s[42:43], s[34:35], 19
	v_or3_b32 v2, v3, v4, v2
	v_add_u32_e32 v41, v40, v1
	v_ashrrev_i32_e32 v1, 31, v0
	s_add_u32 s44, s47, s42
	v_add_u32_e32 v8, 0x1000, v41
	v_lshlrev_b64 v[0:1], 1, v[0:1]
	v_ashrrev_i32_e32 v3, 31, v2
	v_readfirstlane_b32 s35, v40
	s_addc_u32 s45, s49, s43
	v_lshl_add_u64 v[4:5], s[40:41], 0, v[0:1]
	v_lshlrev_b64 v[2:3], 1, v[2:3]
	s_mov_b32 m0, s35
	v_readfirstlane_b32 s35, v8
	v_add_u32_e32 v11, 0x1400, v41
	v_lshl_add_u64 v[6:7], s[44:45], 0, v[2:3]
	s_mov_b32 m0, s35
	v_readfirstlane_b32 s35, v11
	v_add_u32_e32 v11, 0x3000, v40
	v_lshl_add_u64 v[8:9], v[6:7], 0, s[6:7]
	s_mov_b32 m0, s35
	v_readfirstlane_b32 s35, v11
	v_add_u32_e32 v11, 0x4000, v41
	v_lshl_add_u64 v[8:9], v[4:5], 0, 64
	s_mov_b32 m0, s35
	v_readfirstlane_b32 s35, v11
	v_add_u32_e32 v11, 0x4400, v41
	v_lshl_add_u64 v[8:9], v[6:7], 0, 64
	s_mov_b32 m0, s35
	v_readfirstlane_b32 s35, v11
	v_lshl_add_u64 v[8:9], v[6:7], 0, s[8:9]
	s_mov_b32 m0, s35
	v_lshl_add_u64 v[4:5], v[4:5], 0, s[10:11]
	v_add_u32_e32 v8, 0x6000, v40
	s_add_u32 s40, s94, s42
	v_readfirstlane_b32 s35, v8
	v_add_u32_e32 v8, 0x7000, v41
	s_mov_b32 m0, s35
	v_readfirstlane_b32 s35, v8
	v_lshl_add_u64 v[4:5], v[6:7], 0, s[10:11]
	s_mov_b32 m0, s35
	s_addc_u32 s41, s95, s43
	v_lshl_add_u64 v[4:5], v[6:7], 0, s[12:13]
	v_add_u32_e32 v6, 0x7400, v41
	v_lshl_add_u64 v[32:33], s[40:41], 0, v[2:3]
	v_readfirstlane_b32 s35, v6
	s_mov_b32 m0, s35
	s_sub_i32 s40, s48, s62
	s_mulk_i32 s61, 0x78
	s_sub_i32 s40, s40, s61
	s_lshl_b32 s40, s40, 6
	v_and_b32_e32 v4, 31, v10
	v_lshrrev_b32_e32 v6, 2, v10
	s_addk_i32 s40, 0x2000
	v_and_or_b32 v4, v6, s54, v4
	s_ashr_i32 s41, s40, 31
	v_bfe_u32 v5, v10, 5, 1
	v_lshlrev_b32_e32 v42, 6, v4
	v_lshlrev_b32_e32 v4, 6, v10
	s_lshl_b64 s[40:41], s[40:41], 12
	v_bfe_u32 v7, v10, 2, 2
	v_and_b32_e32 v43, 0x17c0, v4
	v_bitop3_b32 v4, v5, v6, 3 bitop3:0x78
	s_add_u32 s40, s94, s40
	v_lshlrev_b32_e32 v44, 4, v4
	v_bitop3_b32 v4, v5, v7, 2 bitop3:0x36
	s_addc_u32 s41, s95, s41
	v_mov_b32_e32 v16, 0
	s_mov_b32 s60, 0
	s_mov_b32 s35, 1
	v_lshlrev_b32_e32 v45, 4, v4
	v_lshl_add_u64 v[34:35], s[40:41], 0, v[0:1]
	s_mov_b64 s[40:41], 0
	v_mov_b32_e32 v17, v16
	v_mov_b32_e32 v18, v16
	v_mov_b32_e32 v19, v16
	v_mov_b32_e32 v20, v16
	v_mov_b32_e32 v21, v16
	v_mov_b32_e32 v22, v16
	v_mov_b32_e32 v23, v16
	v_mov_b32_e32 v24, v16
	v_mov_b32_e32 v25, v16
	v_mov_b32_e32 v26, v16
	v_mov_b32_e32 v27, v16
	v_mov_b32_e32 v28, v16
	v_mov_b32_e32 v29, v16
	v_mov_b32_e32 v30, v16
	v_mov_b32_e32 v31, v16
	v_mov_b32_e32 v0, v16
	v_mov_b32_e32 v1, v16
	v_mov_b32_e32 v2, v16
	v_mov_b32_e32 v3, v16
	v_mov_b32_e32 v4, v16
	v_mov_b32_e32 v5, v16
	v_mov_b32_e32 v6, v16
	v_mov_b32_e32 v7, v16
	v_mov_b32_e32 v8, v16
	v_mov_b32_e32 v9, v16
	v_mov_b32_e32 v10, v16
	v_mov_b32_e32 v11, v16
	v_mov_b32_e32 v12, v16
	v_mov_b32_e32 v13, v16
	v_mov_b32_e32 v14, v16
	v_mov_b32_e32 v15, v16
	s_nop 0
	v_add3_u32 v184, v42, v44, 32
	v_add3_u32 v185, v42, v45, 32
	v_add_u32_e32 v186, 0x1020, v43
	v_add_u32_e32 v187, v186, v45
	v_add_u32_e32 v186, v186, v44
	v_subrev_u32_e32 v188, s94, v34
	v_subrev_u32_e32 v189, s94, v32
	v_add_u32_e32 v188, 0x15c88000, v188
	v_add_u32_e32 v189, 0x18a88000, v189
	v_add_u32_e32 v190, 0x10000, v189
	v_readfirstlane_b32 s80, v40
	v_readfirstlane_b32 s81, v41
	s_add_u32 s81, s81, 0x1000
	s_mov_b64 s[76:77], s[94:95]
	s_add_u32 s78, s94, 64
	s_addc_u32 s79, s95, 0
	s_nop 0
	v_bfe_u32 v191, v204, 2, 4
	v_lshlrev_b32_e32 v191, 7, v191
	s_mov_b32 s83, 0
	s_movk_i32 s84, 0x800
	s_nop 0
	v_xad_u32 v192, s83, v191, v189
	v_xad_u32 v193, s84, v191, v190
	s_add_u32 m0, s80, 0x0
	s_nop 0
	global_load_lds_dwordx4 v188, s[76:77]
	s_add_u32 m0, s80, 0x3000
	s_nop 0
	s_nop 0
	global_load_lds_dwordx4 v188, s[78:79]
	s_add_u32 m0, s81, 0x0
	s_nop 0
	global_load_lds_dwordx4 v192, s[94:95]
	s_add_u32 m0, s81, 0x2fc0
	s_nop 0
	s_nop 0
	global_load_lds_dwordx4 v192, s[94:95] offset:64
	s_add_u32 m0, s81, 0x400
	s_nop 0
	s_nop 0
	global_load_lds_dwordx4 v193, s[94:95]
	s_add_u32 m0, s81, 0x33c0
	s_nop 0
	s_nop 0
	global_load_lds_dwordx4 v193, s[94:95] offset:64
	s_add_u32 s83, s83, 0x80
	s_xor_b32 s84, s83, 0x800
	s_add_u32 s76, s76, 128
	s_addc_u32 s77, s77, 0
	s_nop 0
	s_add_u32 s78, s78, 128
	s_addc_u32 s79, s79, 0
	s_nop 0
	v_xad_u32 v192, s83, v191, v189
	v_xad_u32 v193, s84, v191, v190
	s_add_u32 m0, s80, 0x6000
	s_nop 0
	s_nop 0
	global_load_lds_dwordx4 v188, s[76:77]
	s_add_u32 m0, s80, 0x9000
	s_nop 0
	s_nop 0
	global_load_lds_dwordx4 v188, s[78:79]
	s_add_u32 m0, s81, 0x6000
	s_nop 0
	s_nop 0
	global_load_lds_dwordx4 v192, s[94:95]
	s_add_u32 m0, s81, 0x8fc0
	s_nop 0
	s_nop 0
	global_load_lds_dwordx4 v192, s[94:95] offset:64
	s_add_u32 m0, s81, 0x6400
	s_nop 0
	s_nop 0
	global_load_lds_dwordx4 v193, s[94:95]
	s_add_u32 m0, s81, 0x93c0
	s_nop 0
	s_nop 0
	global_load_lds_dwordx4 v193, s[94:95] offset:64
	s_add_u32 s83, s83, 0x80
	s_xor_b32 s84, s83, 0x800
	s_add_u32 s76, s76, 128
	s_addc_u32 s77, s77, 0
	s_nop 0
	s_add_u32 s78, s78, 128
	s_addc_u32 s79, s79, 0
	s_nop 0
	v_xad_u32 v192, s83, v191, v189
	v_xad_u32 v193, s84, v191, v190
	s_add_u32 m0, s80, 0xc000
	s_nop 0
	s_nop 0
	global_load_lds_dwordx4 v188, s[76:77]
	s_add_u32 m0, s80, 0xf000
	s_nop 0
	s_nop 0
	global_load_lds_dwordx4 v188, s[78:79]
	s_add_u32 m0, s81, 0xc000
	s_nop 0
	s_nop 0
	global_load_lds_dwordx4 v192, s[94:95]
	s_add_u32 m0, s81, 0xefc0
	s_nop 0
	s_nop 0
	global_load_lds_dwordx4 v192, s[94:95] offset:64
	s_add_u32 m0, s81, 0xc400
	s_nop 0
	s_nop 0
	global_load_lds_dwordx4 v193, s[94:95]
	s_add_u32 m0, s81, 0xf3c0
	s_nop 0
	s_nop 0
	global_load_lds_dwordx4 v193, s[94:95] offset:64
	s_add_u32 s83, s83, 0x80
	s_xor_b32 s84, s83, 0x800
	s_add_u32 s76, s76, 128
	s_addc_u32 s77, s77, 0
	s_nop 0
	s_add_u32 s78, s78, 128
	s_addc_u32 s79, s79, 0
	s_waitcnt vmcnt(13)
	s_barrier
	s_nop 0
	ds_read_b128 v[160:163], v186 offset:0
	ds_read_b128 v[164:167], v186 offset:2048
	ds_read_b128 v[168:171], v184 offset:0
	s_waitcnt lgkmcnt(0)
	s_setprio 1
	v_mfma_f32_32x32x16_bf16 v[16:31], v[168:171], v[160:163], v[16:31]
	v_mfma_f32_32x32x16_bf16 v[0:15], v[168:171], v[164:167], v[0:15]
	s_setprio 0
	s_nop 0
	ds_read_b128 v[172:175], v187 offset:0
	ds_read_b128 v[176:179], v187 offset:2048
	ds_read_b128 v[180:183], v185 offset:0
	s_waitcnt vmcnt(12) lgkmcnt(0)
	s_barrier
	ds_read_b128 v[160:163], v186 offset:12288
	ds_read_b128 v[164:167], v186 offset:14336
	ds_read_b128 v[168:171], v184 offset:12288
	s_setprio 1
	s_nop 0
	v_mfma_f32_32x32x16_bf16 v[16:31], v[180:183], v[172:175], v[16:31]
	v_mfma_f32_32x32x16_bf16 v[0:15], v[180:183], v[176:179], v[0:15]
	s_setprio 0
	s_waitcnt lgkmcnt(0)
	s_setprio 1
	s_nop 0
	v_mfma_f32_32x32x16_bf16 v[16:31], v[168:171], v[160:163], v[16:31]
	v_mfma_f32_32x32x16_bf16 v[0:15], v[168:171], v[164:167], v[0:15]
	s_setprio 0
	s_nop 0
	ds_read_b128 v[172:175], v187 offset:12288
	ds_read_b128 v[176:179], v187 offset:14336
	ds_read_b128 v[180:183], v185 offset:12288
	s_waitcnt vmcnt(7) lgkmcnt(0)
	s_barrier
	ds_read_b128 v[160:163], v186 offset:24576
	ds_read_b128 v[164:167], v186 offset:26624
	ds_read_b128 v[168:171], v184 offset:24576
	s_setprio 1
	s_nop 0
	v_mfma_f32_32x32x16_bf16 v[16:31], v[180:183], v[172:175], v[16:31]
	v_mfma_f32_32x32x16_bf16 v[0:15], v[180:183], v[176:179], v[0:15]
	s_setprio 0
	s_add_u32 m0, s80, 0x0
	s_nop 0
	s_nop 0
	global_load_lds_dwordx4 v188, s[76:77]
	s_add_u32 m0, s80, 0x3000
	s_nop 0
	s_nop 0
	global_load_lds_dwordx4 v188, s[78:79]
	s_waitcnt lgkmcnt(0)
	s_setprio 1
	v_mfma_f32_32x32x16_bf16 v[16:31], v[168:171], v[160:163], v[16:31]
	v_mfma_f32_32x32x16_bf16 v[0:15], v[168:171], v[164:167], v[0:15]
	s_setprio 0
	s_nop 0
	ds_read_b128 v[172:175], v187 offset:24576
	ds_read_b128 v[176:179], v187 offset:26624
	ds_read_b128 v[180:183], v185 offset:24576
	v_xad_u32 v192, s83, v191, v189
	v_xad_u32 v193, s84, v191, v190
	s_add_u32 m0, s81, 0x0
	s_nop 0
	global_load_lds_dwordx4 v192, s[94:95]
	s_add_u32 m0, s81, 0x2fc0
	s_nop 0
	s_nop 0
	global_load_lds_dwordx4 v192, s[94:95] offset:64
	s_add_u32 m0, s81, 0x400
	s_nop 0
	s_nop 0
	global_load_lds_dwordx4 v193, s[94:95]
	s_add_u32 m0, s81, 0x33c0
	s_nop 0
	s_nop 0
	global_load_lds_dwordx4 v193, s[94:95] offset:64
	s_add_u32 s83, s83, 0x80
	s_xor_b32 s84, s83, 0x800
	s_add_u32 s76, s76, 128
	s_addc_u32 s77, s77, 0
	s_nop 0
	s_add_u32 s78, s78, 128
	s_addc_u32 s79, s79, 0
	s_waitcnt vmcnt(12) lgkmcnt(0)
	s_barrier
	s_nop 0
	ds_read_b128 v[160:163], v186 offset:36864
	ds_read_b128 v[164:167], v186 offset:38912
	ds_read_b128 v[168:171], v184 offset:36864
	s_setprio 1
	s_nop 0
	v_mfma_f32_32x32x16_bf16 v[16:31], v[180:183], v[172:175], v[16:31]
	v_mfma_f32_32x32x16_bf16 v[0:15], v[180:183], v[176:179], v[0:15]
	s_setprio 0
	s_waitcnt lgkmcnt(0)
	s_setprio 1
	s_nop 0
	v_mfma_f32_32x32x16_bf16 v[16:31], v[168:171], v[160:163], v[16:31]
	v_mfma_f32_32x32x16_bf16 v[0:15], v[168:171], v[164:167], v[0:15]
	s_setprio 0
	s_nop 0
	ds_read_b128 v[172:175], v187 offset:36864
	ds_read_b128 v[176:179], v187 offset:38912
	ds_read_b128 v[180:183], v185 offset:36864
	s_waitcnt vmcnt(7) lgkmcnt(0)
	s_barrier
	ds_read_b128 v[160:163], v186 offset:49152
	ds_read_b128 v[164:167], v186 offset:51200
	ds_read_b128 v[168:171], v184 offset:49152
	s_setprio 1
	s_nop 0
	v_mfma_f32_32x32x16_bf16 v[16:31], v[180:183], v[172:175], v[16:31]
	v_mfma_f32_32x32x16_bf16 v[0:15], v[180:183], v[176:179], v[0:15]
	s_setprio 0
	s_nop 0
	s_add_u32 m0, s80, 0x6000
	s_nop 0
	s_nop 0
	global_load_lds_dwordx4 v188, s[76:77]
	s_add_u32 m0, s80, 0x9000
	s_nop 0
	s_nop 0
	global_load_lds_dwordx4 v188, s[78:79]
	s_waitcnt lgkmcnt(0)
	s_setprio 1
	v_mfma_f32_32x32x16_bf16 v[16:31], v[168:171], v[160:163], v[16:31]
	v_mfma_f32_32x32x16_bf16 v[0:15], v[168:171], v[164:167], v[0:15]
	s_setprio 0
	s_nop 0
	ds_read_b128 v[172:175], v187 offset:49152
	ds_read_b128 v[176:179], v187 offset:51200
	ds_read_b128 v[180:183], v185 offset:49152
	v_xad_u32 v192, s83, v191, v189
	v_xad_u32 v193, s84, v191, v190
	s_add_u32 m0, s81, 0x6000
	s_nop 0
	s_nop 0
	global_load_lds_dwordx4 v192, s[94:95]
	s_add_u32 m0, s81, 0x8fc0
	s_nop 0
	s_nop 0
	global_load_lds_dwordx4 v192, s[94:95] offset:64
	s_add_u32 m0, s81, 0x6400
	s_nop 0
	s_nop 0
	global_load_lds_dwordx4 v193, s[94:95]
	s_add_u32 m0, s81, 0x93c0
	s_nop 0
	s_nop 0
	global_load_lds_dwordx4 v193, s[94:95] offset:64
	s_add_u32 s83, s83, 0x80
	s_xor_b32 s84, s83, 0x800
	s_add_u32 s76, s76, 128
	s_addc_u32 s77, s77, 0
	s_nop 0
	s_add_u32 s78, s78, 128
	s_addc_u32 s79, s79, 0
	s_waitcnt vmcnt(12) lgkmcnt(0)
	s_barrier
	s_nop 0
	ds_read_b128 v[160:163], v186 offset:61440
	ds_read_b128 v[164:167], v186 offset:63488
	ds_read_b128 v[168:171], v184 offset:61440
	s_setprio 1
	s_nop 0
	v_mfma_f32_32x32x16_bf16 v[16:31], v[180:183], v[172:175], v[16:31]
	v_mfma_f32_32x32x16_bf16 v[0:15], v[180:183], v[176:179], v[0:15]
	s_setprio 0
	s_waitcnt lgkmcnt(0)
	s_setprio 1
	s_nop 0
	v_mfma_f32_32x32x16_bf16 v[16:31], v[168:171], v[160:163], v[16:31]
	v_mfma_f32_32x32x16_bf16 v[0:15], v[168:171], v[164:167], v[0:15]
	s_setprio 0
	s_nop 0
	ds_read_b128 v[172:175], v187 offset:61440
	ds_read_b128 v[176:179], v187 offset:63488
	ds_read_b128 v[180:183], v185 offset:61440
	s_mov_b32 s82, 9
.Lp5s_kloop:
	s_waitcnt vmcnt(6) lgkmcnt(0)
	s_barrier
	s_nop 0
	ds_read_b128 v[160:163], v186 offset:0
	ds_read_b128 v[164:167], v186 offset:2048
	ds_read_b128 v[168:171], v184 offset:0
	s_setprio 1
	s_nop 0
	v_mfma_f32_32x32x16_bf16 v[16:31], v[180:183], v[172:175], v[16:31]
	v_mfma_f32_32x32x16_bf16 v[0:15], v[180:183], v[176:179], v[0:15]
	s_setprio 0
	s_nop 0
	s_add_u32 m0, s80, 0xc000
	s_nop 0
	s_nop 0
	global_load_lds_dwordx4 v188, s[76:77]
	s_add_u32 m0, s80, 0xf000
	s_nop 0
	s_nop 0
	global_load_lds_dwordx4 v188, s[78:79]
	s_waitcnt lgkmcnt(0)
	s_setprio 1
	v_mfma_f32_32x32x16_bf16 v[16:31], v[168:171], v[160:163], v[16:31]
	v_mfma_f32_32x32x16_bf16 v[0:15], v[168:171], v[164:167], v[0:15]
	s_setprio 0
	s_nop 0
	ds_read_b128 v[172:175], v187 offset:0
	ds_read_b128 v[176:179], v187 offset:2048
	ds_read_b128 v[180:183], v185 offset:0
	v_xad_u32 v192, s83, v191, v189
	v_xad_u32 v193, s84, v191, v190
	s_add_u32 m0, s81, 0xc000
	s_nop 0
	s_nop 0
	global_load_lds_dwordx4 v192, s[94:95]
	s_add_u32 m0, s81, 0xefc0
	s_nop 0
	s_nop 0
	global_load_lds_dwordx4 v192, s[94:95] offset:64
	s_add_u32 m0, s81, 0xc400
	s_nop 0
	s_nop 0
	global_load_lds_dwordx4 v193, s[94:95]
	s_add_u32 m0, s81, 0xf3c0
	s_nop 0
	s_nop 0
	global_load_lds_dwordx4 v193, s[94:95] offset:64
	s_add_u32 s83, s83, 0x80
	s_xor_b32 s84, s83, 0x800
	s_add_u32 s76, s76, 128
	s_addc_u32 s77, s77, 0
	s_nop 0
	s_add_u32 s78, s78, 128
	s_addc_u32 s79, s79, 0
	s_waitcnt lgkmcnt(0)
	s_barrier
	s_nop 0
	ds_read_b128 v[160:163], v186 offset:12288
	ds_read_b128 v[164:167], v186 offset:14336
	ds_read_b128 v[168:171], v184 offset:12288
	s_setprio 1
	s_nop 0
	v_mfma_f32_32x32x16_bf16 v[16:31], v[180:183], v[172:175], v[16:31]
	v_mfma_f32_32x32x16_bf16 v[0:15], v[180:183], v[176:179], v[0:15]
	s_setprio 0
	s_waitcnt lgkmcnt(0)
	s_setprio 1
	s_nop 0
	v_mfma_f32_32x32x16_bf16 v[16:31], v[168:171], v[160:163], v[16:31]
	v_mfma_f32_32x32x16_bf16 v[0:15], v[168:171], v[164:167], v[0:15]
	s_setprio 0
	s_nop 0
	ds_read_b128 v[172:175], v187 offset:12288
	ds_read_b128 v[176:179], v187 offset:14336
	ds_read_b128 v[180:183], v185 offset:12288
	s_waitcnt vmcnt(6) lgkmcnt(0)
	s_barrier
	ds_read_b128 v[160:163], v186 offset:24576
	ds_read_b128 v[164:167], v186 offset:26624
	ds_read_b128 v[168:171], v184 offset:24576
	s_setprio 1
	s_nop 0
	v_mfma_f32_32x32x16_bf16 v[16:31], v[180:183], v[172:175], v[16:31]
	v_mfma_f32_32x32x16_bf16 v[0:15], v[180:183], v[176:179], v[0:15]
	s_setprio 0
	s_add_u32 m0, s80, 0x0
	s_nop 0
	s_nop 0
	global_load_lds_dwordx4 v188, s[76:77]
	s_add_u32 m0, s80, 0x3000
	s_nop 0
	s_nop 0
	global_load_lds_dwordx4 v188, s[78:79]
	s_waitcnt lgkmcnt(0)
	s_setprio 1
	v_mfma_f32_32x32x16_bf16 v[16:31], v[168:171], v[160:163], v[16:31]
	v_mfma_f32_32x32x16_bf16 v[0:15], v[168:171], v[164:167], v[0:15]
	s_setprio 0
	s_nop 0
	ds_read_b128 v[172:175], v187 offset:24576
	ds_read_b128 v[176:179], v187 offset:26624
	ds_read_b128 v[180:183], v185 offset:24576
	v_xad_u32 v192, s83, v191, v189
	v_xad_u32 v193, s84, v191, v190
	s_add_u32 m0, s81, 0x0
	s_nop 0
	global_load_lds_dwordx4 v192, s[94:95]
	s_add_u32 m0, s81, 0x2fc0
	s_nop 0
	s_nop 0
	global_load_lds_dwordx4 v192, s[94:95] offset:64
	s_add_u32 m0, s81, 0x400
	s_nop 0
	s_nop 0
	global_load_lds_dwordx4 v193, s[94:95]
	s_add_u32 m0, s81, 0x33c0
	s_nop 0
	s_nop 0
	global_load_lds_dwordx4 v193, s[94:95] offset:64
	s_add_u32 s83, s83, 0x80
	s_xor_b32 s84, s83, 0x800
	s_add_u32 s76, s76, 128
	s_addc_u32 s77, s77, 0
	s_nop 0
	s_add_u32 s78, s78, 128
	s_addc_u32 s79, s79, 0
	s_waitcnt lgkmcnt(0)
	s_barrier
	s_nop 0
	ds_read_b128 v[160:163], v186 offset:36864
	ds_read_b128 v[164:167], v186 offset:38912
	ds_read_b128 v[168:171], v184 offset:36864
	s_setprio 1
	s_nop 0
	v_mfma_f32_32x32x16_bf16 v[16:31], v[180:183], v[172:175], v[16:31]
	v_mfma_f32_32x32x16_bf16 v[0:15], v[180:183], v[176:179], v[0:15]
	s_setprio 0
	s_waitcnt lgkmcnt(0)
	s_setprio 1
	s_nop 0
	v_mfma_f32_32x32x16_bf16 v[16:31], v[168:171], v[160:163], v[16:31]
	v_mfma_f32_32x32x16_bf16 v[0:15], v[168:171], v[164:167], v[0:15]
	s_setprio 0
	s_nop 0
	ds_read_b128 v[172:175], v187 offset:36864
	ds_read_b128 v[176:179], v187 offset:38912
	ds_read_b128 v[180:183], v185 offset:36864
	s_waitcnt vmcnt(6) lgkmcnt(0)
	s_barrier
	ds_read_b128 v[160:163], v186 offset:49152
	ds_read_b128 v[164:167], v186 offset:51200
	ds_read_b128 v[168:171], v184 offset:49152
	s_setprio 1
	s_nop 0
	v_mfma_f32_32x32x16_bf16 v[16:31], v[180:183], v[172:175], v[16:31]
	v_mfma_f32_32x32x16_bf16 v[0:15], v[180:183], v[176:179], v[0:15]
	s_setprio 0
	s_nop 0
	s_add_u32 m0, s80, 0x6000
	s_nop 0
	s_nop 0
	global_load_lds_dwordx4 v188, s[76:77]
	s_add_u32 m0, s80, 0x9000
	s_nop 0
	s_nop 0
	global_load_lds_dwordx4 v188, s[78:79]
	s_waitcnt lgkmcnt(0)
	s_setprio 1
	v_mfma_f32_32x32x16_bf16 v[16:31], v[168:171], v[160:163], v[16:31]
	v_mfma_f32_32x32x16_bf16 v[0:15], v[168:171], v[164:167], v[0:15]
	s_setprio 0
	s_nop 0
	ds_read_b128 v[172:175], v187 offset:49152
	ds_read_b128 v[176:179], v187 offset:51200
	ds_read_b128 v[180:183], v185 offset:49152
	v_xad_u32 v192, s83, v191, v189
	v_xad_u32 v193, s84, v191, v190
	s_add_u32 m0, s81, 0x6000
	s_nop 0
	s_nop 0
	global_load_lds_dwordx4 v192, s[94:95]
	s_add_u32 m0, s81, 0x8fc0
	s_nop 0
	s_nop 0
	global_load_lds_dwordx4 v192, s[94:95] offset:64
	s_add_u32 m0, s81, 0x6400
	s_nop 0
	s_nop 0
	global_load_lds_dwordx4 v193, s[94:95]
	s_add_u32 m0, s81, 0x93c0
	s_nop 0
	s_nop 0
	global_load_lds_dwordx4 v193, s[94:95] offset:64
	s_add_u32 s83, s83, 0x80
	s_xor_b32 s84, s83, 0x800
	s_add_u32 s76, s76, 128
	s_addc_u32 s77, s77, 0
	s_nop 0
	s_add_u32 s78, s78, 128
	s_addc_u32 s79, s79, 0
	s_waitcnt lgkmcnt(0)
	s_barrier
	s_nop 0
	ds_read_b128 v[160:163], v186 offset:61440
	ds_read_b128 v[164:167], v186 offset:63488
	ds_read_b128 v[168:171], v184 offset:61440
	s_setprio 1
	s_nop 0
	v_mfma_f32_32x32x16_bf16 v[16:31], v[180:183], v[172:175], v[16:31]
	v_mfma_f32_32x32x16_bf16 v[0:15], v[180:183], v[176:179], v[0:15]
	s_setprio 0
	s_waitcnt lgkmcnt(0)
	s_setprio 1
	s_nop 0
	v_mfma_f32_32x32x16_bf16 v[16:31], v[168:171], v[160:163], v[16:31]
	v_mfma_f32_32x32x16_bf16 v[0:15], v[168:171], v[164:167], v[0:15]
	s_setprio 0
	s_nop 0
	ds_read_b128 v[172:175], v187 offset:61440
	ds_read_b128 v[176:179], v187 offset:63488
	ds_read_b128 v[180:183], v185 offset:61440
	s_sub_u32 s82, s82, 1
	s_cmp_lg_u32 s82, 0
	s_cbranch_scc1 .Lp5s_kloop
	s_waitcnt vmcnt(6) lgkmcnt(0)
	s_barrier
	s_nop 0
	ds_read_b128 v[160:163], v186 offset:0
	ds_read_b128 v[164:167], v186 offset:2048
	ds_read_b128 v[168:171], v184 offset:0
	s_setprio 1
	s_nop 0
	v_mfma_f32_32x32x16_bf16 v[16:31], v[180:183], v[172:175], v[16:31]
	v_mfma_f32_32x32x16_bf16 v[0:15], v[180:183], v[176:179], v[0:15]
	s_setprio 0
	s_waitcnt lgkmcnt(0)
	s_setprio 1
	s_nop 0
	v_mfma_f32_32x32x16_bf16 v[16:31], v[168:171], v[160:163], v[16:31]
	v_mfma_f32_32x32x16_bf16 v[0:15], v[168:171], v[164:167], v[0:15]
	s_setprio 0
	s_nop 0
	ds_read_b128 v[172:175], v187 offset:0
	ds_read_b128 v[176:179], v187 offset:2048
	ds_read_b128 v[180:183], v185 offset:0
	s_waitcnt lgkmcnt(0)
	s_barrier
	ds_read_b128 v[160:163], v186 offset:12288
	ds_read_b128 v[164:167], v186 offset:14336
	ds_read_b128 v[168:171], v184 offset:12288
	s_setprio 1
	s_nop 0
	v_mfma_f32_32x32x16_bf16 v[16:31], v[180:183], v[172:175], v[16:31]
	v_mfma_f32_32x32x16_bf16 v[0:15], v[180:183], v[176:179], v[0:15]
	s_setprio 0
	s_waitcnt lgkmcnt(0)
	s_setprio 1
	s_nop 0
	v_mfma_f32_32x32x16_bf16 v[16:31], v[168:171], v[160:163], v[16:31]
	v_mfma_f32_32x32x16_bf16 v[0:15], v[168:171], v[164:167], v[0:15]
	s_setprio 0
	s_nop 0
	ds_read_b128 v[172:175], v187 offset:12288
	ds_read_b128 v[176:179], v187 offset:14336
	ds_read_b128 v[180:183], v185 offset:12288
	s_waitcnt vmcnt(0) lgkmcnt(0)
	s_barrier
	ds_read_b128 v[160:163], v186 offset:24576
	ds_read_b128 v[164:167], v186 offset:26624
	ds_read_b128 v[168:171], v184 offset:24576
	s_setprio 1
	s_nop 0
	v_mfma_f32_32x32x16_bf16 v[16:31], v[180:183], v[172:175], v[16:31]
	v_mfma_f32_32x32x16_bf16 v[0:15], v[180:183], v[176:179], v[0:15]
	s_setprio 0
	s_waitcnt lgkmcnt(0)
	s_setprio 1
	s_nop 0
	v_mfma_f32_32x32x16_bf16 v[16:31], v[168:171], v[160:163], v[16:31]
	v_mfma_f32_32x32x16_bf16 v[0:15], v[168:171], v[164:167], v[0:15]
	s_setprio 0
	s_nop 0
	ds_read_b128 v[172:175], v187 offset:24576
	ds_read_b128 v[176:179], v187 offset:26624
	ds_read_b128 v[180:183], v185 offset:24576
	s_waitcnt lgkmcnt(0)
	s_barrier
	ds_read_b128 v[160:163], v186 offset:36864
	ds_read_b128 v[164:167], v186 offset:38912
	ds_read_b128 v[168:171], v184 offset:36864
	s_setprio 1
	s_nop 0
	v_mfma_f32_32x32x16_bf16 v[16:31], v[180:183], v[172:175], v[16:31]
	v_mfma_f32_32x32x16_bf16 v[0:15], v[180:183], v[176:179], v[0:15]
	s_setprio 0
	s_waitcnt lgkmcnt(0)
	s_setprio 1
	s_nop 0
	v_mfma_f32_32x32x16_bf16 v[16:31], v[168:171], v[160:163], v[16:31]
	v_mfma_f32_32x32x16_bf16 v[0:15], v[168:171], v[164:167], v[0:15]
	s_setprio 0
	s_nop 0
	ds_read_b128 v[172:175], v187 offset:36864
	ds_read_b128 v[176:179], v187 offset:38912
	ds_read_b128 v[180:183], v185 offset:36864
	s_waitcnt lgkmcnt(0)
	s_setprio 1
	v_mfma_f32_32x32x16_bf16 v[16:31], v[180:183], v[172:175], v[16:31]
	v_mfma_f32_32x32x16_bf16 v[0:15], v[180:183], v[176:179], v[0:15]
	s_setprio 0
	s_branch .LBB0_713

.LBB0_787:
	v_add_u32_e32 v0, v76, v77
	v_cmp_lt_i32_e32 vcc, s47, v0
	s_cbranch_vccnz .LBB0_786
	v_readfirstlane_b32 s38, v0
	s_ashr_i32 s39, s38, 31
	s_lshr_b32 s39, s39, 25
	s_add_i32 s39, s38, s39
	s_ashr_i32 s44, s39, 7
	s_lshl_b32 s40, s44, 3
	s_and_b32 s39, s39, 0xffffff80
	s_sub_i32 s41, 0x44, s40
	s_cmpk_gt_i32 s38, 0x3ff
	s_cselect_b32 s41, s41, 8
	s_abs_i32 s38, s41
	v_cvt_f32_u32_e32 v1, s38
	v_subrev_u32_e32 v0, s39, v0
	s_sub_i32 s39, 0, s38
	v_sub_u32_e32 v2, 0, v0
	v_rcp_iflag_f32_e32 v1, v1
	v_max_i32_e32 v2, v0, v2
	v_xor_b32_e32 v3, s41, v0
	v_ashrrev_i32_e32 v3, 31, v3
	v_mul_f32_e32 v1, 0x4f7ffffe, v1
	v_cvt_u32_f32_e32 v1, v1
	v_mov_b32_e32 v8, v204
	v_add_u32_e32 v0, s40, v0
	v_mul_lo_u32 v4, s39, v1
	v_mul_hi_u32 v4, v1, v4
	v_add_u32_e32 v1, v1, v4
	v_mul_hi_u32 v1, v2, v1
	v_mul_lo_u32 v4, v1, s38
	v_sub_u32_e32 v2, v2, v4
	v_add_u32_e32 v4, 1, v1
	v_subrev_u32_e32 v5, s38, v2
	v_cmp_le_u32_e32 vcc, s38, v2
	s_mulk_i32 s44, 0x78
	v_and_b32_e32 v9, 31, v8
	v_cndmask_b32_e32 v1, v1, v4, vcc
	v_cndmask_b32_e32 v2, v2, v5, vcc
	v_add_u32_e32 v4, 1, v1
	v_cmp_le_u32_e32 vcc, s38, v2
	v_bfe_u32 v2, v8, 4, 2
	v_bitop3_b32 v2, v2, v8, 3 bitop3:0x78
	v_cndmask_b32_e32 v1, v1, v4, vcc
	v_xor_b32_e32 v1, v1, v3
	v_sub_u32_e32 v1, v1, v3
	v_ashrrev_i32_e32 v3, 6, v8
	v_readfirstlane_b32 s38, v1
	v_lshlrev_b32_e32 v5, 9, v8
	s_mul_i32 s45, s41, s38
	s_ashr_i32 s39, s38, 31
	v_lshlrev_b32_e32 v2, 3, v2
	v_lshlrev_b32_e32 v4, 16, v3
	v_and_b32_e32 v5, 0x7800, v5
	v_subrev_u32_e32 v0, s45, v0
	s_lshl_b64 s[40:41], s[38:39], 19
	v_or3_b32 v2, v5, v4, v2
	v_ashrrev_i32_e32 v1, 31, v0
	s_add_u32 s42, s48, s40
	v_lshl_add_u32 v64, v3, 11, 32
	v_ashrrev_i32_e32 v3, 31, v2
	v_lshlrev_b64 v[66:67], 18, v[0:1]
	v_lshlrev_b64 v[0:1], 19, v[0:1]
	s_addc_u32 s43, s49, s41
	v_lshlrev_b64 v[2:3], 1, v[2:3]
	v_lshl_add_u64 v[0:1], s[6:7], 0, v[0:1]
	v_lshl_add_u64 v[4:5], s[42:43], 0, v[2:3]
	v_readfirstlane_b32 s42, v64
	v_add_u32_e32 v11, 0x400, v64
	v_add_u32_e32 v10, 0x2000, v64
	v_lshl_add_u64 v[0:1], v[0:1], 0, v[2:3]
	s_mov_b32 m0, s42
	v_readfirstlane_b32 s42, v11
	v_lshl_add_u64 v[6:7], v[0:1], 0, s[10:11]
	s_mov_b32 m0, s42
	v_readfirstlane_b32 s42, v10
	v_add_u32_e32 v10, 0x2400, v64
	s_mov_b32 m0, s42
	v_readfirstlane_b32 s42, v10
	v_add_u32_e32 v10, 0x4000, v64
	v_lshl_add_u64 v[6:7], v[4:5], 0, s[10:11]
	s_mov_b32 m0, s42
	v_readfirstlane_b32 s42, v10
	v_add_u32_e32 v10, 0x4400, v64
	v_lshl_add_u64 v[6:7], v[0:1], 0, 64
	s_mov_b32 m0, s42
	v_readfirstlane_b32 s42, v10
	v_add_u32_e32 v10, 0x6000, v64
	v_lshl_add_u64 v[6:7], v[0:1], 0, s[12:13]
	s_mov_b32 m0, s42
	v_readfirstlane_b32 s42, v10
	v_add_u32_e32 v10, 0x6400, v64
	v_lshl_add_u64 v[6:7], v[4:5], 0, 64
	s_mov_b32 m0, s42
	v_readfirstlane_b32 s42, v10
	v_add_u32_e32 v10, 0x8000, v64
	v_lshl_add_u64 v[6:7], v[4:5], 0, s[12:13]
	s_mov_b32 m0, s42
	v_readfirstlane_b32 s42, v10
	v_lshl_add_u64 v[6:7], v[0:1], 0, s[14:15]
	s_mov_b32 m0, s42
	v_lshl_add_u64 v[0:1], v[0:1], 0, s[16:17]
	v_add_u32_e32 v6, 0x8400, v64
	s_add_u32 s40, s94, s40
	v_readfirstlane_b32 s42, v6
	v_add_u32_e32 v6, 0xa000, v64
	s_mov_b32 m0, s42
	v_readfirstlane_b32 s42, v6
	v_lshl_add_u64 v[0:1], v[4:5], 0, s[14:15]
	s_mov_b32 m0, s42
	s_addc_u32 s41, s95, s41
	v_lshl_add_u64 v[0:1], v[4:5], 0, s[16:17]
	v_add_u32_e32 v4, 0xa400, v64
	v_lshrrev_b32_e32 v5, 1, v8
	v_readfirstlane_b32 s42, v4
	s_mov_b32 m0, s42
	v_bfe_u32 v4, v8, 2, 2
	v_bfe_u32 v0, v8, 5, 1
	v_lshrrev_b32_e32 v1, 2, v8
	v_bitop3_b32 v1, v0, v1, 3 bitop3:0x78
	v_bitop3_b32 v0, v0, v4, 2 bitop3:0x36
	v_lshlrev_b32_e32 v82, 4, v0
	v_subrev_u32_e32 v0, s45, v78
	v_subrev_u32_e32 v0, s44, v0
	v_lshlrev_b32_e32 v81, 4, v1
	v_ashrrev_i32_e32 v1, 31, v0
	v_lshlrev_b64 v[0:1], 19, v[0:1]
	v_and_or_b32 v5, v5, s52, v9
	v_lshl_add_u64 v[0:1], s[94:95], 0, v[0:1]
	v_lshlrev_b32_e32 v79, 6, v5
	v_lshlrev_b32_e32 v5, 6, v8
	v_lshl_add_u64 v[70:71], v[0:1], 0, v[2:3]
	v_mov_b32_e32 v0, 0
	s_mov_b32 s54, 0
	s_mov_b32 s53, 1
	v_and_b32_e32 v80, 0x17c0, v5
	v_lshl_add_u64 v[68:69], s[40:41], 0, v[2:3]
	s_mov_b64 s[40:41], 0
	v_mov_b32_e32 v1, v0
	v_mov_b32_e32 v2, v0
	v_mov_b32_e32 v3, v0
	v_mov_b32_e32 v4, v0
	v_mov_b32_e32 v5, v0
	v_mov_b32_e32 v6, v0
	v_mov_b32_e32 v7, v0
	v_mov_b32_e32 v8, v0
	v_mov_b32_e32 v9, v0
	v_mov_b32_e32 v10, v0
	v_mov_b32_e32 v11, v0
	v_mov_b32_e32 v12, v0
	v_mov_b32_e32 v13, v0
	v_mov_b32_e32 v14, v0
	v_mov_b32_e32 v15, v0
	v_mov_b32_e32 v16, v0
	v_mov_b32_e32 v17, v0
	v_mov_b32_e32 v18, v0
	v_mov_b32_e32 v19, v0
	v_mov_b32_e32 v20, v0
	v_mov_b32_e32 v21, v0
	v_mov_b32_e32 v22, v0
	v_mov_b32_e32 v23, v0
	v_mov_b32_e32 v24, v0
	v_mov_b32_e32 v25, v0
	v_mov_b32_e32 v26, v0
	v_mov_b32_e32 v27, v0
	v_mov_b32_e32 v28, v0
	v_mov_b32_e32 v29, v0
	v_mov_b32_e32 v30, v0
	v_mov_b32_e32 v31, v0
	v_mov_b32_e32 v32, v0
	v_mov_b32_e32 v33, v0
	v_mov_b32_e32 v34, v0
	v_mov_b32_e32 v35, v0
	v_mov_b32_e32 v36, v0
	v_mov_b32_e32 v37, v0
	v_mov_b32_e32 v38, v0
	v_mov_b32_e32 v39, v0
	v_mov_b32_e32 v40, v0
	v_mov_b32_e32 v41, v0
	v_mov_b32_e32 v42, v0
	v_mov_b32_e32 v43, v0
	v_mov_b32_e32 v44, v0
	v_mov_b32_e32 v45, v0
	v_mov_b32_e32 v46, v0
	v_mov_b32_e32 v47, v0
	v_mov_b32_e32 v48, v0
	v_mov_b32_e32 v49, v0
	v_mov_b32_e32 v50, v0
	v_mov_b32_e32 v51, v0
	v_mov_b32_e32 v52, v0
	v_mov_b32_e32 v53, v0
	v_mov_b32_e32 v54, v0
	v_mov_b32_e32 v55, v0
	v_mov_b32_e32 v56, v0
	v_mov_b32_e32 v57, v0
	v_mov_b32_e32 v58, v0
	v_mov_b32_e32 v59, v0
	v_mov_b32_e32 v60, v0
	v_mov_b32_e32 v61, v0
	v_mov_b32_e32 v62, v0
	v_mov_b32_e32 v63, v0
	v_add3_u32 v140, v79, v81, 32
	v_add3_u32 v141, v79, v82, 32
	v_add_u32_e32 v142, 0x2020, v80
	v_add_u32_e32 v143, v142, v82
	v_add_u32_e32 v142, v142, v81
	v_subrev_u32_e32 v144, s94, v70
	v_subrev_u32_e32 v146, s94, v68
	v_add_u32_e32 v144, 0x13288000, v144
	v_add_u32_e32 v146, 0x19288000, v146
	v_add_u32_e32 v145, 0x10000, v144
	v_add_u32_e32 v147, 0x10000, v146
	v_readfirstlane_b32 s64, v64
	s_nop 0
	s_add_u32 s65, s64, 0x2000
	s_mov_b64 s[60:61], s[94:95]
	s_add_u32 s62, s94, 64
	s_addc_u32 s63, s95, 0
	s_nop 0
	v_bfe_u32 v148, v204, 2, 4
	v_lshlrev_b32_e32 v148, 7, v148
	s_mov_b32 s70, 0
	s_movk_i32 s71, 0x800
	s_nop 0
	v_xad_u32 v149, s70, v148, v146
	v_xad_u32 v150, s71, v148, v147
	s_add_u32 m0, s64, 0x0
	s_nop 0
	global_load_lds_dwordx4 v144, s[60:61]
	s_add_u32 m0, s64, 0x4000
	s_nop 0
	s_nop 0
	global_load_lds_dwordx4 v144, s[62:63]
	s_add_u32 m0, s64, 0x400
	s_nop 0
	s_nop 0
	global_load_lds_dwordx4 v145, s[60:61]
	s_add_u32 m0, s64, 0x4400
	s_nop 0
	s_nop 0
	global_load_lds_dwordx4 v145, s[62:63]
	s_add_u32 m0, s65, 0x0
	s_nop 0
	global_load_lds_dwordx4 v149, s[94:95]
	s_add_u32 m0, s65, 0x3fc0
	s_nop 0
	s_nop 0
	global_load_lds_dwordx4 v149, s[94:95] offset:64
	s_add_u32 m0, s65, 0x400
	s_nop 0
	s_nop 0
	global_load_lds_dwordx4 v150, s[94:95]
	s_add_u32 m0, s65, 0x43c0
	s_nop 0
	s_nop 0
	global_load_lds_dwordx4 v150, s[94:95] offset:64
	s_add_u32 s70, s70, 0x80
	s_xor_b32 s71, s70, 0x800
	s_add_u32 s60, s60, 128
	s_addc_u32 s61, s61, 0
	s_nop 0
	s_add_u32 s62, s62, 128
	s_addc_u32 s63, s63, 0
	s_nop 0
	v_xad_u32 v149, s70, v148, v146
	v_xad_u32 v150, s71, v148, v147
	s_add_u32 m0, s64, 0x8000
	s_nop 0
	s_nop 0
	global_load_lds_dwordx4 v144, s[60:61]
	s_add_u32 m0, s64, 0xc000
	s_nop 0
	s_nop 0
	global_load_lds_dwordx4 v144, s[62:63]
	s_add_u32 m0, s64, 0x8400
	s_nop 0
	s_nop 0
	global_load_lds_dwordx4 v145, s[60:61]
	s_add_u32 m0, s64, 0xc400
	s_nop 0
	s_nop 0
	global_load_lds_dwordx4 v145, s[62:63]
	s_add_u32 m0, s65, 0x8000
	s_nop 0
	s_nop 0
	global_load_lds_dwordx4 v149, s[94:95]
	s_add_u32 m0, s65, 0xbfc0
	s_nop 0
	s_nop 0
	global_load_lds_dwordx4 v149, s[94:95] offset:64
	s_add_u32 m0, s65, 0x8400
	s_nop 0
	s_nop 0
	global_load_lds_dwordx4 v150, s[94:95]
	s_add_u32 m0, s65, 0xc3c0
	s_nop 0
	s_nop 0
	global_load_lds_dwordx4 v150, s[94:95] offset:64
	s_add_u32 s70, s70, 0x80
	s_xor_b32 s71, s70, 0x800
	s_add_u32 s60, s60, 128
	s_addc_u32 s61, s61, 0
	s_nop 0
	s_add_u32 s62, s62, 128
	s_addc_u32 s63, s63, 0
	s_waitcnt vmcnt(9)
	s_barrier
	s_nop 0
	ds_read_b128 v[108:111], v142 offset:0
	ds_read_b128 v[112:115], v142 offset:2048
	ds_read_b128 v[116:119], v140 offset:0
	ds_read_b128 v[120:123], v140 offset:2048
	s_waitcnt lgkmcnt(0)
	s_setprio 1
	v_mfma_f32_32x32x16_bf16 v[48:63], v[116:119], v[108:111], v[48:63]
	v_mfma_f32_32x32x16_bf16 v[32:47], v[116:119], v[112:115], v[32:47]
	v_mfma_f32_32x32x16_bf16 v[16:31], v[120:123], v[108:111], v[16:31]
	v_mfma_f32_32x32x16_bf16 v[0:15], v[120:123], v[112:115], v[0:15]
	s_setprio 0
	s_nop 0
	ds_read_b128 v[124:127], v143 offset:0
	ds_read_b128 v[128:131], v143 offset:2048
	ds_read_b128 v[132:135], v141 offset:0
	ds_read_b128 v[136:139], v141 offset:2048
	s_waitcnt vmcnt(8) lgkmcnt(0)
	s_barrier
	ds_read_b128 v[108:111], v142 offset:16384
	ds_read_b128 v[112:115], v142 offset:18432
	ds_read_b128 v[116:119], v140 offset:16384
	ds_read_b128 v[120:123], v140 offset:18432
	s_setprio 1
	s_nop 0
	v_mfma_f32_32x32x16_bf16 v[48:63], v[132:135], v[124:127], v[48:63]
	v_mfma_f32_32x32x16_bf16 v[32:47], v[132:135], v[128:131], v[32:47]
	v_mfma_f32_32x32x16_bf16 v[16:31], v[136:139], v[124:127], v[16:31]
	v_mfma_f32_32x32x16_bf16 v[0:15], v[136:139], v[128:131], v[0:15]
	s_setprio 0
	s_waitcnt lgkmcnt(0)
	s_setprio 1
	s_nop 0
	v_mfma_f32_32x32x16_bf16 v[48:63], v[116:119], v[108:111], v[48:63]
	v_mfma_f32_32x32x16_bf16 v[32:47], v[116:119], v[112:115], v[32:47]
	v_mfma_f32_32x32x16_bf16 v[16:31], v[120:123], v[108:111], v[16:31]
	v_mfma_f32_32x32x16_bf16 v[0:15], v[120:123], v[112:115], v[0:15]
	s_setprio 0
	s_nop 0
	ds_read_b128 v[124:127], v143 offset:16384
	ds_read_b128 v[128:131], v143 offset:18432
	ds_read_b128 v[132:135], v141 offset:16384
	ds_read_b128 v[136:139], v141 offset:18432
	s_waitcnt vmcnt(1) lgkmcnt(0)
	s_barrier
	ds_read_b128 v[108:111], v142 offset:32768
	ds_read_b128 v[112:115], v142 offset:34816
	ds_read_b128 v[116:119], v140 offset:32768
	ds_read_b128 v[120:123], v140 offset:34816
	s_setprio 1
	s_nop 0
	v_mfma_f32_32x32x16_bf16 v[48:63], v[132:135], v[124:127], v[48:63]
	v_mfma_f32_32x32x16_bf16 v[32:47], v[132:135], v[128:131], v[32:47]
	v_mfma_f32_32x32x16_bf16 v[16:31], v[136:139], v[124:127], v[16:31]
	v_mfma_f32_32x32x16_bf16 v[0:15], v[136:139], v[128:131], v[0:15]
	s_setprio 0
	s_add_u32 m0, s64, 0x0
	s_nop 0
	s_nop 0
	global_load_lds_dwordx4 v144, s[60:61]
	s_add_u32 m0, s64, 0x4000
	s_nop 0
	s_nop 0
	global_load_lds_dwordx4 v144, s[62:63]
	s_add_u32 m0, s64, 0x400
	s_nop 0
	s_nop 0
	global_load_lds_dwordx4 v145, s[60:61]
	s_add_u32 m0, s64, 0x4400
	s_nop 0
	s_nop 0
	global_load_lds_dwordx4 v145, s[62:63]
	s_waitcnt lgkmcnt(0)
	s_setprio 1
	v_mfma_f32_32x32x16_bf16 v[48:63], v[116:119], v[108:111], v[48:63]
	v_mfma_f32_32x32x16_bf16 v[32:47], v[116:119], v[112:115], v[32:47]
	v_mfma_f32_32x32x16_bf16 v[16:31], v[120:123], v[108:111], v[16:31]
	v_mfma_f32_32x32x16_bf16 v[0:15], v[120:123], v[112:115], v[0:15]
	s_setprio 0
	s_nop 0
	ds_read_b128 v[124:127], v143 offset:32768
	ds_read_b128 v[128:131], v143 offset:34816
	ds_read_b128 v[132:135], v141 offset:32768
	ds_read_b128 v[136:139], v141 offset:34816
	v_xad_u32 v149, s70, v148, v146
	v_xad_u32 v150, s71, v148, v147
	s_add_u32 m0, s65, 0x0
	s_nop 0
	global_load_lds_dwordx4 v149, s[94:95]
	s_add_u32 m0, s65, 0x3fc0
	s_nop 0
	s_nop 0
	global_load_lds_dwordx4 v149, s[94:95] offset:64
	s_add_u32 m0, s65, 0x400
	s_nop 0
	s_nop 0
	global_load_lds_dwordx4 v150, s[94:95]
	s_add_u32 m0, s65, 0x43c0
	s_nop 0
	s_nop 0
	global_load_lds_dwordx4 v150, s[94:95] offset:64
	s_add_u32 s70, s70, 0x80
	s_xor_b32 s71, s70, 0x800
	s_add_u32 s60, s60, 128
	s_addc_u32 s61, s61, 0
	s_nop 0
	s_add_u32 s62, s62, 128
	s_addc_u32 s63, s63, 0
	s_waitcnt vmcnt(8) lgkmcnt(0)
	s_barrier
	s_nop 0
	ds_read_b128 v[108:111], v142 offset:49152
	ds_read_b128 v[112:115], v142 offset:51200
	ds_read_b128 v[116:119], v140 offset:49152
	ds_read_b128 v[120:123], v140 offset:51200
	s_setprio 1
	s_nop 0
	v_mfma_f32_32x32x16_bf16 v[48:63], v[132:135], v[124:127], v[48:63]
	v_mfma_f32_32x32x16_bf16 v[32:47], v[132:135], v[128:131], v[32:47]
	v_mfma_f32_32x32x16_bf16 v[16:31], v[136:139], v[124:127], v[16:31]
	v_mfma_f32_32x32x16_bf16 v[0:15], v[136:139], v[128:131], v[0:15]
	s_setprio 0
	s_waitcnt lgkmcnt(0)
	s_setprio 1
	s_nop 0
	v_mfma_f32_32x32x16_bf16 v[48:63], v[116:119], v[108:111], v[48:63]
	v_mfma_f32_32x32x16_bf16 v[32:47], v[116:119], v[112:115], v[32:47]
	v_mfma_f32_32x32x16_bf16 v[16:31], v[120:123], v[108:111], v[16:31]
	v_mfma_f32_32x32x16_bf16 v[0:15], v[120:123], v[112:115], v[0:15]
	s_setprio 0
	s_nop 0
	ds_read_b128 v[124:127], v143 offset:49152
	ds_read_b128 v[128:131], v143 offset:51200
	ds_read_b128 v[132:135], v141 offset:49152
	ds_read_b128 v[136:139], v141 offset:51200
	s_mov_b32 s69, 14
.Lp6_kloop:
	s_waitcnt vmcnt(0) lgkmcnt(0)
	s_barrier
	s_nop 0
	ds_read_b128 v[108:111], v142 offset:0
	ds_read_b128 v[112:115], v142 offset:2048
	ds_read_b128 v[116:119], v140 offset:0
	ds_read_b128 v[120:123], v140 offset:2048
	s_setprio 1
	s_nop 0
	v_mfma_f32_32x32x16_bf16 v[48:63], v[132:135], v[124:127], v[48:63]
	v_mfma_f32_32x32x16_bf16 v[32:47], v[132:135], v[128:131], v[32:47]
	v_mfma_f32_32x32x16_bf16 v[16:31], v[136:139], v[124:127], v[16:31]
	v_mfma_f32_32x32x16_bf16 v[0:15], v[136:139], v[128:131], v[0:15]
	s_setprio 0
	s_nop 0
	s_add_u32 m0, s64, 0x8000
	s_nop 0
	s_nop 0
	global_load_lds_dwordx4 v144, s[60:61]
	s_add_u32 m0, s64, 0xc000
	s_nop 0
	s_nop 0
	global_load_lds_dwordx4 v144, s[62:63]
	s_add_u32 m0, s64, 0x8400
	s_nop 0
	s_nop 0
	global_load_lds_dwordx4 v145, s[60:61]
	s_add_u32 m0, s64, 0xc400
	s_nop 0
	s_nop 0
	global_load_lds_dwordx4 v145, s[62:63]
	s_waitcnt lgkmcnt(0)
	s_setprio 1
	v_mfma_f32_32x32x16_bf16 v[48:63], v[116:119], v[108:111], v[48:63]
	v_mfma_f32_32x32x16_bf16 v[32:47], v[116:119], v[112:115], v[32:47]
	v_mfma_f32_32x32x16_bf16 v[16:31], v[120:123], v[108:111], v[16:31]
	v_mfma_f32_32x32x16_bf16 v[0:15], v[120:123], v[112:115], v[0:15]
	s_setprio 0
	s_nop 0
	ds_read_b128 v[124:127], v143 offset:0
	ds_read_b128 v[128:131], v143 offset:2048
	ds_read_b128 v[132:135], v141 offset:0
	ds_read_b128 v[136:139], v141 offset:2048
	v_xad_u32 v149, s70, v148, v146
	v_xad_u32 v150, s71, v148, v147
	s_add_u32 m0, s65, 0x8000
	s_nop 0
	s_nop 0
	global_load_lds_dwordx4 v149, s[94:95]
	s_add_u32 m0, s65, 0xbfc0
	s_nop 0
	s_nop 0
	global_load_lds_dwordx4 v149, s[94:95] offset:64
	s_add_u32 m0, s65, 0x8400
	s_nop 0
	s_nop 0
	global_load_lds_dwordx4 v150, s[94:95]
	s_add_u32 m0, s65, 0xc3c0
	s_nop 0
	s_nop 0
	global_load_lds_dwordx4 v150, s[94:95] offset:64
	s_add_u32 s70, s70, 0x80
	s_xor_b32 s71, s70, 0x800
	s_add_u32 s60, s60, 128
	s_addc_u32 s61, s61, 0
	s_nop 0
	s_add_u32 s62, s62, 128
	s_addc_u32 s63, s63, 0
	s_waitcnt lgkmcnt(0)
	s_barrier
	s_nop 0
	ds_read_b128 v[108:111], v142 offset:16384
	ds_read_b128 v[112:115], v142 offset:18432
	ds_read_b128 v[116:119], v140 offset:16384
	ds_read_b128 v[120:123], v140 offset:18432
	s_setprio 1
	s_nop 0
	v_mfma_f32_32x32x16_bf16 v[48:63], v[132:135], v[124:127], v[48:63]
	v_mfma_f32_32x32x16_bf16 v[32:47], v[132:135], v[128:131], v[32:47]
	v_mfma_f32_32x32x16_bf16 v[16:31], v[136:139], v[124:127], v[16:31]
	v_mfma_f32_32x32x16_bf16 v[0:15], v[136:139], v[128:131], v[0:15]
	s_setprio 0
	s_waitcnt lgkmcnt(0)
	s_setprio 1
	s_nop 0
	v_mfma_f32_32x32x16_bf16 v[48:63], v[116:119], v[108:111], v[48:63]
	v_mfma_f32_32x32x16_bf16 v[32:47], v[116:119], v[112:115], v[32:47]
	v_mfma_f32_32x32x16_bf16 v[16:31], v[120:123], v[108:111], v[16:31]
	v_mfma_f32_32x32x16_bf16 v[0:15], v[120:123], v[112:115], v[0:15]
	s_setprio 0
	s_nop 0
	ds_read_b128 v[124:127], v143 offset:16384
	ds_read_b128 v[128:131], v143 offset:18432
	ds_read_b128 v[132:135], v141 offset:16384
	ds_read_b128 v[136:139], v141 offset:18432
	s_waitcnt vmcnt(0) lgkmcnt(0)
	s_barrier
	ds_read_b128 v[108:111], v142 offset:32768
	ds_read_b128 v[112:115], v142 offset:34816
	ds_read_b128 v[116:119], v140 offset:32768
	ds_read_b128 v[120:123], v140 offset:34816
	s_setprio 1
	s_nop 0
	v_mfma_f32_32x32x16_bf16 v[48:63], v[132:135], v[124:127], v[48:63]
	v_mfma_f32_32x32x16_bf16 v[32:47], v[132:135], v[128:131], v[32:47]
	v_mfma_f32_32x32x16_bf16 v[16:31], v[136:139], v[124:127], v[16:31]
	v_mfma_f32_32x32x16_bf16 v[0:15], v[136:139], v[128:131], v[0:15]
	s_setprio 0
	s_add_u32 m0, s64, 0x0
	s_nop 0
	s_nop 0
	global_load_lds_dwordx4 v144, s[60:61]
	s_add_u32 m0, s64, 0x4000
	s_nop 0
	s_nop 0
	global_load_lds_dwordx4 v144, s[62:63]
	s_add_u32 m0, s64, 0x400
	s_nop 0
	s_nop 0
	global_load_lds_dwordx4 v145, s[60:61]
	s_add_u32 m0, s64, 0x4400
	s_nop 0
	s_nop 0
	global_load_lds_dwordx4 v145, s[62:63]
	s_waitcnt lgkmcnt(0)
	s_setprio 1
	v_mfma_f32_32x32x16_bf16 v[48:63], v[116:119], v[108:111], v[48:63]
	v_mfma_f32_32x32x16_bf16 v[32:47], v[116:119], v[112:115], v[32:47]
	v_mfma_f32_32x32x16_bf16 v[16:31], v[120:123], v[108:111], v[16:31]
	v_mfma_f32_32x32x16_bf16 v[0:15], v[120:123], v[112:115], v[0:15]
	s_setprio 0
	s_nop 0
	ds_read_b128 v[124:127], v143 offset:32768
	ds_read_b128 v[128:131], v143 offset:34816
	ds_read_b128 v[132:135], v141 offset:32768
	ds_read_b128 v[136:139], v141 offset:34816
	v_xad_u32 v149, s70, v148, v146
	v_xad_u32 v150, s71, v148, v147
	s_add_u32 m0, s65, 0x0
	s_nop 0
	global_load_lds_dwordx4 v149, s[94:95]
	s_add_u32 m0, s65, 0x3fc0
	s_nop 0
	s_nop 0
	global_load_lds_dwordx4 v149, s[94:95] offset:64
	s_add_u32 m0, s65, 0x400
	s_nop 0
	s_nop 0
	global_load_lds_dwordx4 v150, s[94:95]
	s_add_u32 m0, s65, 0x43c0
	s_nop 0
	s_nop 0
	global_load_lds_dwordx4 v150, s[94:95] offset:64
	s_add_u32 s70, s70, 0x80
	s_xor_b32 s71, s70, 0x800
	s_add_u32 s60, s60, 128
	s_addc_u32 s61, s61, 0
	s_nop 0
	s_add_u32 s62, s62, 128
	s_addc_u32 s63, s63, 0
	s_waitcnt lgkmcnt(0)
	s_barrier
	s_nop 0
	ds_read_b128 v[108:111], v142 offset:49152
	ds_read_b128 v[112:115], v142 offset:51200
	ds_read_b128 v[116:119], v140 offset:49152
	ds_read_b128 v[120:123], v140 offset:51200
	s_setprio 1
	s_nop 0
	v_mfma_f32_32x32x16_bf16 v[48:63], v[132:135], v[124:127], v[48:63]
	v_mfma_f32_32x32x16_bf16 v[32:47], v[132:135], v[128:131], v[32:47]
	v_mfma_f32_32x32x16_bf16 v[16:31], v[136:139], v[124:127], v[16:31]
	v_mfma_f32_32x32x16_bf16 v[0:15], v[136:139], v[128:131], v[0:15]
	s_setprio 0
	s_waitcnt lgkmcnt(0)
	s_setprio 1
	s_nop 0
	v_mfma_f32_32x32x16_bf16 v[48:63], v[116:119], v[108:111], v[48:63]
	v_mfma_f32_32x32x16_bf16 v[32:47], v[116:119], v[112:115], v[32:47]
	v_mfma_f32_32x32x16_bf16 v[16:31], v[120:123], v[108:111], v[16:31]
	v_mfma_f32_32x32x16_bf16 v[0:15], v[120:123], v[112:115], v[0:15]
	s_setprio 0
	s_nop 0
	ds_read_b128 v[124:127], v143 offset:49152
	ds_read_b128 v[128:131], v143 offset:51200
	ds_read_b128 v[132:135], v141 offset:49152
	ds_read_b128 v[136:139], v141 offset:51200
	s_sub_u32 s69, s69, 1
	s_cmp_lg_u32 s69, 0
	s_cbranch_scc1 .Lp6_kloop
	s_waitcnt vmcnt(0) lgkmcnt(0)
	s_barrier
	s_nop 0
	ds_read_b128 v[108:111], v142 offset:0
	ds_read_b128 v[112:115], v142 offset:2048
	ds_read_b128 v[116:119], v140 offset:0
	ds_read_b128 v[120:123], v140 offset:2048
	s_setprio 1
	s_nop 0
	v_mfma_f32_32x32x16_bf16 v[48:63], v[132:135], v[124:127], v[48:63]
	v_mfma_f32_32x32x16_bf16 v[32:47], v[132:135], v[128:131], v[32:47]
	v_mfma_f32_32x32x16_bf16 v[16:31], v[136:139], v[124:127], v[16:31]
	v_mfma_f32_32x32x16_bf16 v[0:15], v[136:139], v[128:131], v[0:15]
	s_setprio 0
	s_nop 0
	s_add_u32 m0, s64, 0x8000
	s_nop 0
	s_nop 0
	global_load_lds_dwordx4 v144, s[60:61]
	s_add_u32 m0, s64, 0xc000
	s_nop 0
	s_nop 0
	global_load_lds_dwordx4 v144, s[62:63]
	s_add_u32 m0, s64, 0x8400
	s_nop 0
	s_nop 0
	global_load_lds_dwordx4 v145, s[60:61]
	s_add_u32 m0, s64, 0xc400
	s_nop 0
	s_nop 0
	global_load_lds_dwordx4 v145, s[62:63]
	s_waitcnt lgkmcnt(0)
	s_setprio 1
	v_mfma_f32_32x32x16_bf16 v[48:63], v[116:119], v[108:111], v[48:63]
	v_mfma_f32_32x32x16_bf16 v[32:47], v[116:119], v[112:115], v[32:47]
	v_mfma_f32_32x32x16_bf16 v[16:31], v[120:123], v[108:111], v[16:31]
	v_mfma_f32_32x32x16_bf16 v[0:15], v[120:123], v[112:115], v[0:15]
	s_setprio 0
	s_nop 0
	ds_read_b128 v[124:127], v143 offset:0
	ds_read_b128 v[128:131], v143 offset:2048
	ds_read_b128 v[132:135], v141 offset:0
	ds_read_b128 v[136:139], v141 offset:2048
	v_xad_u32 v149, s70, v148, v146
	v_xad_u32 v150, s71, v148, v147
	s_add_u32 m0, s65, 0x8000
	s_nop 0
	s_nop 0
	global_load_lds_dwordx4 v149, s[94:95]
	s_add_u32 m0, s65, 0xbfc0
	s_nop 0
	s_nop 0
	global_load_lds_dwordx4 v149, s[94:95] offset:64
	s_add_u32 m0, s65, 0x8400
	s_nop 0
	s_nop 0
	global_load_lds_dwordx4 v150, s[94:95]
	s_add_u32 m0, s65, 0xc3c0
	s_nop 0
	s_nop 0
	global_load_lds_dwordx4 v150, s[94:95] offset:64
	s_add_u32 s70, s70, 0x80
	s_xor_b32 s71, s70, 0x800
	s_add_u32 s60, s60, 128
	s_addc_u32 s61, s61, 0
	s_nop 0
	s_add_u32 s62, s62, 128
	s_addc_u32 s63, s63, 0
	s_waitcnt lgkmcnt(0)
	s_barrier
	s_nop 0
	ds_read_b128 v[108:111], v142 offset:16384
	ds_read_b128 v[112:115], v142 offset:18432
	ds_read_b128 v[116:119], v140 offset:16384
	ds_read_b128 v[120:123], v140 offset:18432
	s_setprio 1
	s_nop 0
	v_mfma_f32_32x32x16_bf16 v[48:63], v[132:135], v[124:127], v[48:63]
	v_mfma_f32_32x32x16_bf16 v[32:47], v[132:135], v[128:131], v[32:47]
	v_mfma_f32_32x32x16_bf16 v[16:31], v[136:139], v[124:127], v[16:31]
	v_mfma_f32_32x32x16_bf16 v[0:15], v[136:139], v[128:131], v[0:15]
	s_setprio 0
	s_waitcnt lgkmcnt(0)
	s_setprio 1
	s_nop 0
	v_mfma_f32_32x32x16_bf16 v[48:63], v[116:119], v[108:111], v[48:63]
	v_mfma_f32_32x32x16_bf16 v[32:47], v[116:119], v[112:115], v[32:47]
	v_mfma_f32_32x32x16_bf16 v[16:31], v[120:123], v[108:111], v[16:31]
	v_mfma_f32_32x32x16_bf16 v[0:15], v[120:123], v[112:115], v[0:15]
	s_setprio 0
	s_nop 0
	ds_read_b128 v[124:127], v143 offset:16384
	ds_read_b128 v[128:131], v143 offset:18432
	ds_read_b128 v[132:135], v141 offset:16384
	ds_read_b128 v[136:139], v141 offset:18432
	s_waitcnt vmcnt(0) lgkmcnt(0)
	s_barrier
	ds_read_b128 v[108:111], v142 offset:32768
	ds_read_b128 v[112:115], v142 offset:34816
	ds_read_b128 v[116:119], v140 offset:32768
	ds_read_b128 v[120:123], v140 offset:34816
	s_setprio 1
	s_nop 0
	v_mfma_f32_32x32x16_bf16 v[48:63], v[132:135], v[124:127], v[48:63]
	v_mfma_f32_32x32x16_bf16 v[32:47], v[132:135], v[128:131], v[32:47]
	v_mfma_f32_32x32x16_bf16 v[16:31], v[136:139], v[124:127], v[16:31]
	v_mfma_f32_32x32x16_bf16 v[0:15], v[136:139], v[128:131], v[0:15]
	s_setprio 0
	s_waitcnt lgkmcnt(0)
	s_setprio 1
	s_nop 0
	v_mfma_f32_32x32x16_bf16 v[48:63], v[116:119], v[108:111], v[48:63]
	v_mfma_f32_32x32x16_bf16 v[32:47], v[116:119], v[112:115], v[32:47]
	v_mfma_f32_32x32x16_bf16 v[16:31], v[120:123], v[108:111], v[16:31]
	v_mfma_f32_32x32x16_bf16 v[0:15], v[120:123], v[112:115], v[0:15]
	s_setprio 0
	s_nop 0
	ds_read_b128 v[124:127], v143 offset:32768
	ds_read_b128 v[128:131], v143 offset:34816
	ds_read_b128 v[132:135], v141 offset:32768
	ds_read_b128 v[136:139], v141 offset:34816
	s_waitcnt lgkmcnt(0)
	s_barrier
	ds_read_b128 v[108:111], v142 offset:49152
	ds_read_b128 v[112:115], v142 offset:51200
	ds_read_b128 v[116:119], v140 offset:49152
	ds_read_b128 v[120:123], v140 offset:51200
	s_setprio 1
	s_nop 0
	v_mfma_f32_32x32x16_bf16 v[48:63], v[132:135], v[124:127], v[48:63]
	v_mfma_f32_32x32x16_bf16 v[32:47], v[132:135], v[128:131], v[32:47]
	v_mfma_f32_32x32x16_bf16 v[16:31], v[136:139], v[124:127], v[16:31]
	v_mfma_f32_32x32x16_bf16 v[0:15], v[136:139], v[128:131], v[0:15]
	s_setprio 0
	s_waitcnt lgkmcnt(0)
	s_setprio 1
	s_nop 0
	v_mfma_f32_32x32x16_bf16 v[48:63], v[116:119], v[108:111], v[48:63]
	v_mfma_f32_32x32x16_bf16 v[32:47], v[116:119], v[112:115], v[32:47]
	v_mfma_f32_32x32x16_bf16 v[16:31], v[120:123], v[108:111], v[16:31]
	v_mfma_f32_32x32x16_bf16 v[0:15], v[120:123], v[112:115], v[0:15]
	s_setprio 0
	s_nop 0
	ds_read_b128 v[124:127], v143 offset:49152
	ds_read_b128 v[128:131], v143 offset:51200
	ds_read_b128 v[132:135], v141 offset:49152
	ds_read_b128 v[136:139], v141 offset:51200
	s_waitcnt lgkmcnt(0)
	s_setprio 1
	v_mfma_f32_32x32x16_bf16 v[48:63], v[132:135], v[124:127], v[48:63]
	v_mfma_f32_32x32x16_bf16 v[32:47], v[132:135], v[128:131], v[32:47]
	v_mfma_f32_32x32x16_bf16 v[16:31], v[136:139], v[124:127], v[16:31]
	v_mfma_f32_32x32x16_bf16 v[0:15], v[136:139], v[128:131], v[0:15]
	s_setprio 0
